# GEMM K-loops: MFMAs reordered so each accumulator's two k-step MFMAs issue back to back (accumulate forwarding), on top of setprio/NA-mask/S-wave edits
# speedup vs baseline: 1.0126x; 1.0075x over previous
.LBB0_236:
	ds_read_b128 v[146:149], v162
	ds_read_b128 v[150:153], v162 offset:1024
	ds_read_b128 v[166:169], v162 offset:2048
	ds_read_b128 v[170:173], v162 offset:3072
	ds_read_b128 v[174:177], v163
	ds_read_b128 v[182:185], v163 offset:1024
	ds_read_b128 v[186:189], v163 offset:2048
	ds_read_b128 v[190:193], v163 offset:3072
	s_add_u32 s26, s4, 0xfff80080
	s_addc_u32 s27, s5, -1
	s_cmp_eq_u32 s63, 28
	s_cselect_b32 s29, s17, s27
	s_cselect_b32 s28, s58, s26
	s_cselect_b32 s27, s15, s62
	s_cselect_b32 s26, s59, s60
	v_lshl_add_u64 v[226:227], s[4:5], 0, v[138:139]
	s_add_i32 m0, s23, 0xc000
	ds_read_b128 v[194:197], v164
	ds_read_b128 v[198:201], v164 offset:1024
	ds_read_b128 v[202:205], v164 offset:2048
	ds_read_b128 v[206:209], v164 offset:3072
	ds_read_b128 v[210:213], v164 offset:4096
	ds_read_b128 v[214:217], v164 offset:5120
	ds_read_b128 v[218:221], v164 offset:6144
	ds_read_b128 v[222:225], v164 offset:7168
	global_load_lds_dwordx4 v[226:227], off
	v_lshl_add_u64 v[226:227], s[4:5], 0, v[140:141]
	s_add_i32 m0, s23, 0xe000
	s_nop 0
	global_load_lds_dwordx4 v[226:227], off
	s_waitcnt vmcnt(8)
	s_waitcnt lgkmcnt(0)
	s_setprio 1
	s_barrier
	v_mfma_f32_16x16x32_bf16 v[126:129], v[146:149], v[194:197], v[126:129]
	v_mfma_f32_16x16x32_bf16 v[126:129], v[150:153], v[198:201], v[126:129]
	v_mfma_f32_16x16x32_bf16 v[122:125], v[166:169], v[194:197], v[122:125]
	v_mfma_f32_16x16x32_bf16 v[122:125], v[170:173], v[198:201], v[122:125]
	v_mfma_f32_16x16x32_bf16 v[110:113], v[146:149], v[202:205], v[110:113]
	v_mfma_f32_16x16x32_bf16 v[110:113], v[150:153], v[206:209], v[110:113]
	v_mfma_f32_16x16x32_bf16 v[106:109], v[166:169], v[202:205], v[106:109]
	v_mfma_f32_16x16x32_bf16 v[106:109], v[170:173], v[206:209], v[106:109]
	v_mfma_f32_16x16x32_bf16 v[94:97], v[146:149], v[210:213], v[94:97]
	v_mfma_f32_16x16x32_bf16 v[94:97], v[150:153], v[214:217], v[94:97]
	v_mfma_f32_16x16x32_bf16 v[90:93], v[166:169], v[210:213], v[90:93]
	v_mfma_f32_16x16x32_bf16 v[90:93], v[170:173], v[214:217], v[90:93]
	v_mfma_f32_16x16x32_bf16 v[78:81], v[146:149], v[218:221], v[78:81]
	v_mfma_f32_16x16x32_bf16 v[78:81], v[150:153], v[222:225], v[78:81]
	v_mfma_f32_16x16x32_bf16 v[74:77], v[166:169], v[218:221], v[74:77]
	v_mfma_f32_16x16x32_bf16 v[74:77], v[170:173], v[222:225], v[74:77]
	v_mfma_f32_16x16x32_bf16 v[118:121], v[174:177], v[194:197], v[118:121]
	v_mfma_f32_16x16x32_bf16 v[118:121], v[182:185], v[198:201], v[118:121]
	v_mfma_f32_16x16x32_bf16 v[114:117], v[186:189], v[194:197], v[114:117]
	v_mfma_f32_16x16x32_bf16 v[114:117], v[190:193], v[198:201], v[114:117]
	v_mfma_f32_16x16x32_bf16 v[102:105], v[174:177], v[202:205], v[102:105]
	v_mfma_f32_16x16x32_bf16 v[102:105], v[182:185], v[206:209], v[102:105]
	v_mfma_f32_16x16x32_bf16 v[98:101], v[186:189], v[202:205], v[98:101]
	v_mfma_f32_16x16x32_bf16 v[98:101], v[190:193], v[206:209], v[98:101]
	v_mfma_f32_16x16x32_bf16 v[86:89], v[174:177], v[210:213], v[86:89]
	v_mfma_f32_16x16x32_bf16 v[86:89], v[182:185], v[214:217], v[86:89]
	v_mfma_f32_16x16x32_bf16 v[82:85], v[186:189], v[210:213], v[82:85]
	v_mfma_f32_16x16x32_bf16 v[82:85], v[190:193], v[214:217], v[82:85]
	v_mfma_f32_16x16x32_bf16 v[70:73], v[174:177], v[218:221], v[70:73]
	v_mfma_f32_16x16x32_bf16 v[70:73], v[182:185], v[222:225], v[70:73]
	v_mfma_f32_16x16x32_bf16 v[66:69], v[186:189], v[218:221], v[66:69]
	v_mfma_f32_16x16x32_bf16 v[66:69], v[190:193], v[222:225], v[66:69]
	s_barrier
	s_setprio 0
	s_add_i32 s64, s55, s30
	v_lshl_add_u64 v[226:227], s[26:27], 0, v[132:133]
	s_mov_b32 m0, s64
	ds_read_b128 v[194:197], v164 offset:16384
	ds_read_b128 v[198:201], v164 offset:17408
	ds_read_b128 v[202:205], v164 offset:18432
	ds_read_b128 v[206:209], v164 offset:19456
	ds_read_b128 v[210:213], v164 offset:20480
	ds_read_b128 v[214:217], v164 offset:21504
	ds_read_b128 v[218:221], v164 offset:22528
	ds_read_b128 v[222:225], v164 offset:23552
	global_load_lds_dwordx4 v[226:227], off
	s_add_i32 m0, s64, 0x2000
	s_add_u32 s64, s26, 0x80000
	v_lshl_add_u64 v[228:229], s[26:27], 0, v[136:137]
	s_addc_u32 s65, s27, 0
	s_add_i32 s66, s56, s30
	global_load_lds_dwordx4 v[228:229], off
	v_lshl_add_u64 v[230:231], s[64:65], 0, v[132:133]
	s_mov_b32 m0, s66
	v_lshl_add_u64 v[232:233], s[28:29], 0, v[134:135]
	global_load_lds_dwordx4 v[230:231], off
	v_lshl_add_u64 v[230:231], s[64:65], 0, v[136:137]
	s_add_i32 m0, s66, 0x2000
	s_nop 0
	global_load_lds_dwordx4 v[230:231], off
	v_lshl_add_u64 v[230:231], s[28:29], 0, v[130:131]
	s_mov_b32 m0, s23
	s_nop 0
	global_load_lds_dwordx4 v[230:231], off
	s_mov_b32 m0, s25
	s_nop 0
	global_load_lds_dwordx4 v[232:233], off
	s_waitcnt vmcnt(8)
	s_waitcnt lgkmcnt(0)
	s_setprio 1
	s_barrier
	v_mfma_f32_16x16x32_bf16 v[62:65], v[146:149], v[194:197], v[62:65]
	v_mfma_f32_16x16x32_bf16 v[62:65], v[150:153], v[198:201], v[62:65]
	v_mfma_f32_16x16x32_bf16 v[58:61], v[166:169], v[194:197], v[58:61]
	v_mfma_f32_16x16x32_bf16 v[58:61], v[170:173], v[198:201], v[58:61]
	v_mfma_f32_16x16x32_bf16 v[46:49], v[146:149], v[202:205], v[46:49]
	v_mfma_f32_16x16x32_bf16 v[46:49], v[150:153], v[206:209], v[46:49]
	v_mfma_f32_16x16x32_bf16 v[42:45], v[166:169], v[202:205], v[42:45]
	v_mfma_f32_16x16x32_bf16 v[42:45], v[170:173], v[206:209], v[42:45]
	v_mfma_f32_16x16x32_bf16 v[30:33], v[146:149], v[210:213], v[30:33]
	v_mfma_f32_16x16x32_bf16 v[30:33], v[150:153], v[214:217], v[30:33]
	v_mfma_f32_16x16x32_bf16 v[26:29], v[166:169], v[210:213], v[26:29]
	v_mfma_f32_16x16x32_bf16 v[26:29], v[170:173], v[214:217], v[26:29]
	v_mfma_f32_16x16x32_bf16 v[14:17], v[146:149], v[218:221], v[14:17]
	v_mfma_f32_16x16x32_bf16 v[14:17], v[150:153], v[222:225], v[14:17]
	v_mfma_f32_16x16x32_bf16 v[10:13], v[166:169], v[218:221], v[10:13]
	v_mfma_f32_16x16x32_bf16 v[10:13], v[170:173], v[222:225], v[10:13]
	v_mfma_f32_16x16x32_bf16 v[54:57], v[174:177], v[194:197], v[54:57]
	v_mfma_f32_16x16x32_bf16 v[54:57], v[182:185], v[198:201], v[54:57]
	v_mfma_f32_16x16x32_bf16 v[50:53], v[186:189], v[194:197], v[50:53]
	v_mfma_f32_16x16x32_bf16 v[50:53], v[190:193], v[198:201], v[50:53]
	v_mfma_f32_16x16x32_bf16 v[38:41], v[174:177], v[202:205], v[38:41]
	v_mfma_f32_16x16x32_bf16 v[38:41], v[182:185], v[206:209], v[38:41]
	v_mfma_f32_16x16x32_bf16 v[34:37], v[186:189], v[202:205], v[34:37]
	v_mfma_f32_16x16x32_bf16 v[34:37], v[190:193], v[206:209], v[34:37]
	v_mfma_f32_16x16x32_bf16 v[22:25], v[174:177], v[210:213], v[22:25]
	v_mfma_f32_16x16x32_bf16 v[22:25], v[182:185], v[214:217], v[22:25]
	v_mfma_f32_16x16x32_bf16 v[18:21], v[186:189], v[210:213], v[18:21]
	v_mfma_f32_16x16x32_bf16 v[18:21], v[190:193], v[214:217], v[18:21]
	v_mfma_f32_16x16x32_bf16 v[6:9], v[174:177], v[218:221], v[6:9]
	v_mfma_f32_16x16x32_bf16 v[6:9], v[182:185], v[222:225], v[6:9]
	v_mfma_f32_16x16x32_bf16 v[2:5], v[186:189], v[218:221], v[2:5]
	v_mfma_f32_16x16x32_bf16 v[2:5], v[190:193], v[222:225], v[2:5]
	s_barrier
	s_setprio 0
	s_add_i32 s64, 0, 0x18000
	s_add_i32 s65, 0, 0x1c000
	v_add_u32_e32 v170, s64, v156
	v_add_u32_e32 v179, s65, v156
	ds_read_b128 v[146:149], v170
	ds_read_b128 v[150:153], v170 offset:1024
	ds_read_b128 v[166:169], v170 offset:2048
	ds_read_b128 v[170:173], v170 offset:3072
	ds_read_b128 v[174:177], v179
	ds_read_b128 v[182:185], v179 offset:1024
	ds_read_b128 v[186:189], v179 offset:2048
	ds_read_b128 v[190:193], v179 offset:3072
	s_add_u32 s28, s28, 0x80000
	s_addc_u32 s29, s29, 0
	s_mov_b32 m0, s31
	v_lshl_add_u64 v[234:235], s[28:29], 0, v[130:131]
	ds_read_b128 v[194:197], v164 offset:32768
	ds_read_b128 v[198:201], v164 offset:33792
	ds_read_b128 v[202:205], v164 offset:34816
	ds_read_b128 v[206:209], v164 offset:35840
	ds_read_b128 v[210:213], v164 offset:36864
	ds_read_b128 v[214:217], v164 offset:37888
	ds_read_b128 v[218:221], v164 offset:38912
	ds_read_b128 v[222:225], v164 offset:39936
	global_load_lds_dwordx4 v[234:235], off
	v_lshl_add_u64 v[234:235], s[28:29], 0, v[134:135]
	s_mov_b32 m0, s34
	s_nop 0
	global_load_lds_dwordx4 v[234:235], off
	s_waitcnt vmcnt(8)
	s_waitcnt lgkmcnt(0)
	s_setprio 1
	s_barrier
	v_mfma_f32_16x16x32_bf16 v[126:129], v[146:149], v[194:197], v[126:129]
	v_mfma_f32_16x16x32_bf16 v[126:129], v[150:153], v[198:201], v[126:129]
	v_mfma_f32_16x16x32_bf16 v[122:125], v[166:169], v[194:197], v[122:125]
	v_mfma_f32_16x16x32_bf16 v[122:125], v[170:173], v[198:201], v[122:125]
	v_mfma_f32_16x16x32_bf16 v[110:113], v[146:149], v[202:205], v[110:113]
	v_mfma_f32_16x16x32_bf16 v[110:113], v[150:153], v[206:209], v[110:113]
	v_mfma_f32_16x16x32_bf16 v[106:109], v[166:169], v[202:205], v[106:109]
	v_mfma_f32_16x16x32_bf16 v[106:109], v[170:173], v[206:209], v[106:109]
	v_mfma_f32_16x16x32_bf16 v[94:97], v[146:149], v[210:213], v[94:97]
	v_mfma_f32_16x16x32_bf16 v[94:97], v[150:153], v[214:217], v[94:97]
	v_mfma_f32_16x16x32_bf16 v[90:93], v[166:169], v[210:213], v[90:93]
	v_mfma_f32_16x16x32_bf16 v[90:93], v[170:173], v[214:217], v[90:93]
	v_mfma_f32_16x16x32_bf16 v[78:81], v[146:149], v[218:221], v[78:81]
	v_mfma_f32_16x16x32_bf16 v[78:81], v[150:153], v[222:225], v[78:81]
	v_mfma_f32_16x16x32_bf16 v[74:77], v[166:169], v[218:221], v[74:77]
	v_mfma_f32_16x16x32_bf16 v[74:77], v[170:173], v[222:225], v[74:77]
	v_mfma_f32_16x16x32_bf16 v[118:121], v[174:177], v[194:197], v[118:121]
	v_mfma_f32_16x16x32_bf16 v[118:121], v[182:185], v[198:201], v[118:121]
	v_mfma_f32_16x16x32_bf16 v[114:117], v[186:189], v[194:197], v[114:117]
	v_mfma_f32_16x16x32_bf16 v[114:117], v[190:193], v[198:201], v[114:117]
	v_mfma_f32_16x16x32_bf16 v[102:105], v[174:177], v[202:205], v[102:105]
	v_mfma_f32_16x16x32_bf16 v[102:105], v[182:185], v[206:209], v[102:105]
	v_mfma_f32_16x16x32_bf16 v[98:101], v[186:189], v[202:205], v[98:101]
	v_mfma_f32_16x16x32_bf16 v[98:101], v[190:193], v[206:209], v[98:101]
	v_mfma_f32_16x16x32_bf16 v[86:89], v[174:177], v[210:213], v[86:89]
	v_mfma_f32_16x16x32_bf16 v[86:89], v[182:185], v[214:217], v[86:89]
	v_mfma_f32_16x16x32_bf16 v[82:85], v[186:189], v[210:213], v[82:85]
	v_mfma_f32_16x16x32_bf16 v[82:85], v[190:193], v[214:217], v[82:85]
	v_mfma_f32_16x16x32_bf16 v[70:73], v[174:177], v[218:221], v[70:73]
	v_mfma_f32_16x16x32_bf16 v[70:73], v[182:185], v[222:225], v[70:73]
	v_mfma_f32_16x16x32_bf16 v[66:69], v[186:189], v[218:221], v[66:69]
	v_mfma_f32_16x16x32_bf16 v[66:69], v[190:193], v[222:225], v[66:69]
	s_barrier
	s_setprio 0
	s_add_i32 s28, s64, s30
	v_lshl_add_u64 v[226:227], v[226:227], 0, s[10:11]
	s_mov_b32 m0, s28
	ds_read_b128 v[194:197], v164 offset:49152
	ds_read_b128 v[198:201], v164 offset:50176
	ds_read_b128 v[202:205], v164 offset:51200
	ds_read_b128 v[206:209], v164 offset:52224
	ds_read_b128 v[210:213], v164 offset:53248
	ds_read_b128 v[214:217], v164 offset:54272
	ds_read_b128 v[218:221], v164 offset:55296
	ds_read_b128 v[222:225], v164 offset:56320
	global_load_lds_dwordx4 v[226:227], off
	s_add_i32 m0, s28, 0x2000
	s_add_u32 s26, s26, 0x80080
	v_lshl_add_u64 v[226:227], v[228:229], 0, s[10:11]
	s_addc_u32 s27, s27, 0
	s_add_i32 s28, s65, s30
	global_load_lds_dwordx4 v[226:227], off
	v_lshl_add_u64 v[226:227], s[26:27], 0, v[132:133]
	s_mov_b32 m0, s28
	s_nop 0
	global_load_lds_dwordx4 v[226:227], off
	v_lshl_add_u64 v[226:227], s[26:27], 0, v[136:137]
	s_add_i32 m0, s28, 0x2000
	s_nop 0
	global_load_lds_dwordx4 v[226:227], off
	v_lshl_add_u64 v[226:227], v[230:231], 0, s[10:11]
	s_mov_b32 m0, s36
	s_nop 0
	global_load_lds_dwordx4 v[226:227], off
	v_lshl_add_u64 v[226:227], v[232:233], 0, s[10:11]
	s_mov_b32 m0, s37
	s_nop 0
	global_load_lds_dwordx4 v[226:227], off
	s_waitcnt vmcnt(8)
	s_waitcnt lgkmcnt(0)
	s_setprio 1
	s_barrier
	v_mfma_f32_16x16x32_bf16 v[62:65], v[146:149], v[194:197], v[62:65]
	v_mfma_f32_16x16x32_bf16 v[62:65], v[150:153], v[198:201], v[62:65]
	v_mfma_f32_16x16x32_bf16 v[58:61], v[166:169], v[194:197], v[58:61]
	v_mfma_f32_16x16x32_bf16 v[58:61], v[170:173], v[198:201], v[58:61]
	v_mfma_f32_16x16x32_bf16 v[46:49], v[146:149], v[202:205], v[46:49]
	v_mfma_f32_16x16x32_bf16 v[46:49], v[150:153], v[206:209], v[46:49]
	v_mfma_f32_16x16x32_bf16 v[42:45], v[166:169], v[202:205], v[42:45]
	v_mfma_f32_16x16x32_bf16 v[42:45], v[170:173], v[206:209], v[42:45]
	v_mfma_f32_16x16x32_bf16 v[30:33], v[146:149], v[210:213], v[30:33]
	v_mfma_f32_16x16x32_bf16 v[30:33], v[150:153], v[214:217], v[30:33]
	v_mfma_f32_16x16x32_bf16 v[26:29], v[166:169], v[210:213], v[26:29]
	v_mfma_f32_16x16x32_bf16 v[26:29], v[170:173], v[214:217], v[26:29]
	v_mfma_f32_16x16x32_bf16 v[14:17], v[146:149], v[218:221], v[14:17]
	v_mfma_f32_16x16x32_bf16 v[14:17], v[150:153], v[222:225], v[14:17]
	v_mfma_f32_16x16x32_bf16 v[10:13], v[166:169], v[218:221], v[10:13]
	v_mfma_f32_16x16x32_bf16 v[10:13], v[170:173], v[222:225], v[10:13]
	v_mfma_f32_16x16x32_bf16 v[54:57], v[174:177], v[194:197], v[54:57]
	v_mfma_f32_16x16x32_bf16 v[54:57], v[182:185], v[198:201], v[54:57]
	v_mfma_f32_16x16x32_bf16 v[50:53], v[186:189], v[194:197], v[50:53]
	v_mfma_f32_16x16x32_bf16 v[50:53], v[190:193], v[198:201], v[50:53]
	v_mfma_f32_16x16x32_bf16 v[38:41], v[174:177], v[202:205], v[38:41]
	v_mfma_f32_16x16x32_bf16 v[38:41], v[182:185], v[206:209], v[38:41]
	v_mfma_f32_16x16x32_bf16 v[34:37], v[186:189], v[202:205], v[34:37]
	v_mfma_f32_16x16x32_bf16 v[34:37], v[190:193], v[206:209], v[34:37]
	v_mfma_f32_16x16x32_bf16 v[22:25], v[174:177], v[210:213], v[22:25]
	v_mfma_f32_16x16x32_bf16 v[22:25], v[182:185], v[214:217], v[22:25]
	v_mfma_f32_16x16x32_bf16 v[18:21], v[186:189], v[210:213], v[18:21]
	v_mfma_f32_16x16x32_bf16 v[18:21], v[190:193], v[214:217], v[18:21]
	v_mfma_f32_16x16x32_bf16 v[6:9], v[174:177], v[218:221], v[6:9]
	v_mfma_f32_16x16x32_bf16 v[6:9], v[182:185], v[222:225], v[6:9]
	v_mfma_f32_16x16x32_bf16 v[2:5], v[186:189], v[218:221], v[2:5]
	v_mfma_f32_16x16x32_bf16 v[2:5], v[190:193], v[222:225], v[2:5]
	s_barrier
	s_setprio 0
	s_add_i32 s63, s63, 2
	s_add_u32 s4, s4, 0x100
	s_addc_u32 s5, s5, 0
	s_add_u32 s60, s60, 0x100
	s_addc_u32 s62, s62, 0
	s_cmp_gt_u32 s63, 29
	s_cbranch_scc0 .LBB0_236
	s_and_b64 vcc, exec, s[12:13]
	s_cbranch_vccz .LBB0_239
	s_barrier

.LBB0_591:
	ds_read_b128 v[144:147], v150
	ds_read_b128 v[154:157], v150 offset:1024
	ds_read_b128 v[158:161], v150 offset:2048
	ds_read_b128 v[162:165], v150 offset:3072
	ds_read_b128 v[166:169], v151
	ds_read_b128 v[170:173], v151 offset:1024
	ds_read_b128 v[174:177], v151 offset:2048
	ds_read_b128 v[182:185], v151 offset:3072
	s_add_i32 s63, s22, 2
	s_add_u32 s23, s20, 0xfff80080
	s_addc_u32 s26, s21, -1
	s_cmp_eq_u32 s11, s22
	s_cselect_b32 s22, s18, s13
	s_cselect_b32 s27, s17, s26
	s_cselect_b32 s26, s16, s23
	s_cselect_b32 s23, s19, s15
	v_lshl_add_u64 v[218:219], s[20:21], 0, v[138:139]
	s_add_i32 m0, s3, 0xc000
	ds_read_b128 v[186:189], v152
	ds_read_b128 v[190:193], v152 offset:1024
	ds_read_b128 v[194:197], v152 offset:2048
	ds_read_b128 v[198:201], v152 offset:3072
	ds_read_b128 v[202:205], v152 offset:4096
	ds_read_b128 v[206:209], v152 offset:5120
	ds_read_b128 v[210:213], v152 offset:6144
	ds_read_b128 v[214:217], v152 offset:7168
	global_load_lds_dwordx4 v[218:219], off
	v_lshl_add_u64 v[218:219], s[20:21], 0, v[140:141]
	s_add_i32 m0, s3, 0xe000
	s_nop 0
	global_load_lds_dwordx4 v[218:219], off
	s_waitcnt vmcnt(8)
	s_waitcnt lgkmcnt(0)
	s_setprio 1
	s_barrier
	v_mfma_f32_16x16x32_bf16 v[126:129], v[144:147], v[186:189], v[126:129]
	v_mfma_f32_16x16x32_bf16 v[126:129], v[154:157], v[190:193], v[126:129]
	v_mfma_f32_16x16x32_bf16 v[122:125], v[158:161], v[186:189], v[122:125]
	v_mfma_f32_16x16x32_bf16 v[122:125], v[162:165], v[190:193], v[122:125]
	v_mfma_f32_16x16x32_bf16 v[118:121], v[144:147], v[194:197], v[118:121]
	v_mfma_f32_16x16x32_bf16 v[118:121], v[154:157], v[198:201], v[118:121]
	v_mfma_f32_16x16x32_bf16 v[114:117], v[158:161], v[194:197], v[114:117]
	v_mfma_f32_16x16x32_bf16 v[114:117], v[162:165], v[198:201], v[114:117]
	v_mfma_f32_16x16x32_bf16 v[106:109], v[144:147], v[202:205], v[106:109]
	v_mfma_f32_16x16x32_bf16 v[106:109], v[154:157], v[206:209], v[106:109]
	v_mfma_f32_16x16x32_bf16 v[98:101], v[158:161], v[202:205], v[98:101]
	v_mfma_f32_16x16x32_bf16 v[98:101], v[162:165], v[206:209], v[98:101]
	v_mfma_f32_16x16x32_bf16 v[90:93], v[144:147], v[210:213], v[90:93]
	v_mfma_f32_16x16x32_bf16 v[90:93], v[154:157], v[214:217], v[90:93]
	v_mfma_f32_16x16x32_bf16 v[82:85], v[158:161], v[210:213], v[82:85]
	v_mfma_f32_16x16x32_bf16 v[82:85], v[162:165], v[214:217], v[82:85]
	v_mfma_f32_16x16x32_bf16 v[110:113], v[166:169], v[186:189], v[110:113]
	v_mfma_f32_16x16x32_bf16 v[110:113], v[170:173], v[190:193], v[110:113]
	v_mfma_f32_16x16x32_bf16 v[102:105], v[174:177], v[186:189], v[102:105]
	v_mfma_f32_16x16x32_bf16 v[102:105], v[182:185], v[190:193], v[102:105]
	v_mfma_f32_16x16x32_bf16 v[94:97], v[166:169], v[194:197], v[94:97]
	v_mfma_f32_16x16x32_bf16 v[94:97], v[170:173], v[198:201], v[94:97]
	v_mfma_f32_16x16x32_bf16 v[86:89], v[174:177], v[194:197], v[86:89]
	v_mfma_f32_16x16x32_bf16 v[86:89], v[182:185], v[198:201], v[86:89]
	v_mfma_f32_16x16x32_bf16 v[78:81], v[166:169], v[202:205], v[78:81]
	v_mfma_f32_16x16x32_bf16 v[78:81], v[170:173], v[206:209], v[78:81]
	v_mfma_f32_16x16x32_bf16 v[74:77], v[174:177], v[202:205], v[74:77]
	v_mfma_f32_16x16x32_bf16 v[74:77], v[182:185], v[206:209], v[74:77]
	v_mfma_f32_16x16x32_bf16 v[70:73], v[166:169], v[210:213], v[70:73]
	v_mfma_f32_16x16x32_bf16 v[70:73], v[170:173], v[214:217], v[70:73]
	v_mfma_f32_16x16x32_bf16 v[66:69], v[174:177], v[210:213], v[66:69]
	v_mfma_f32_16x16x32_bf16 v[66:69], v[182:185], v[214:217], v[66:69]
	s_barrier
	s_setprio 0
	s_add_i32 s66, s56, s30
	v_lshl_add_u64 v[218:219], s[22:23], 0, v[132:133]
	s_mov_b32 m0, s66
	ds_read_b128 v[186:189], v152 offset:16384
	ds_read_b128 v[190:193], v152 offset:17408
	ds_read_b128 v[194:197], v152 offset:18432
	ds_read_b128 v[198:201], v152 offset:19456
	ds_read_b128 v[202:205], v152 offset:20480
	ds_read_b128 v[206:209], v152 offset:21504
	ds_read_b128 v[210:213], v152 offset:22528
	ds_read_b128 v[214:217], v152 offset:23552
	global_load_lds_dwordx4 v[218:219], off
	s_add_i32 m0, s66, 0x2000
	s_add_u32 s66, s22, 0x80000
	v_lshl_add_u64 v[220:221], s[22:23], 0, v[136:137]
	s_addc_u32 s67, s23, 0
	s_add_i32 s68, s57, s30
	global_load_lds_dwordx4 v[220:221], off
	v_lshl_add_u64 v[222:223], s[66:67], 0, v[132:133]
	s_mov_b32 m0, s68
	v_lshl_add_u64 v[224:225], s[26:27], 0, v[134:135]
	global_load_lds_dwordx4 v[222:223], off
	v_lshl_add_u64 v[222:223], s[66:67], 0, v[136:137]
	s_add_i32 m0, s68, 0x2000
	s_nop 0
	global_load_lds_dwordx4 v[222:223], off
	v_lshl_add_u64 v[222:223], s[26:27], 0, v[130:131]
	s_mov_b32 m0, s3
	s_nop 0
	global_load_lds_dwordx4 v[222:223], off
	s_mov_b32 m0, s34
	s_nop 0
	global_load_lds_dwordx4 v[224:225], off
	s_waitcnt vmcnt(8)
	s_waitcnt lgkmcnt(0)
	s_setprio 1
	s_barrier
	v_mfma_f32_16x16x32_bf16 v[62:65], v[144:147], v[186:189], v[62:65]
	v_mfma_f32_16x16x32_bf16 v[62:65], v[154:157], v[190:193], v[62:65]
	v_mfma_f32_16x16x32_bf16 v[58:61], v[158:161], v[186:189], v[58:61]
	v_mfma_f32_16x16x32_bf16 v[58:61], v[162:165], v[190:193], v[58:61]
	v_mfma_f32_16x16x32_bf16 v[54:57], v[144:147], v[194:197], v[54:57]
	v_mfma_f32_16x16x32_bf16 v[54:57], v[154:157], v[198:201], v[54:57]
	v_mfma_f32_16x16x32_bf16 v[50:53], v[158:161], v[194:197], v[50:53]
	v_mfma_f32_16x16x32_bf16 v[50:53], v[162:165], v[198:201], v[50:53]
	v_mfma_f32_16x16x32_bf16 v[38:41], v[144:147], v[202:205], v[38:41]
	v_mfma_f32_16x16x32_bf16 v[38:41], v[154:157], v[206:209], v[38:41]
	v_mfma_f32_16x16x32_bf16 v[34:37], v[158:161], v[202:205], v[34:37]
	v_mfma_f32_16x16x32_bf16 v[34:37], v[162:165], v[206:209], v[34:37]
	v_mfma_f32_16x16x32_bf16 v[22:25], v[144:147], v[210:213], v[22:25]
	v_mfma_f32_16x16x32_bf16 v[22:25], v[154:157], v[214:217], v[22:25]
	v_mfma_f32_16x16x32_bf16 v[18:21], v[158:161], v[210:213], v[18:21]
	v_mfma_f32_16x16x32_bf16 v[18:21], v[162:165], v[214:217], v[18:21]
	v_mfma_f32_16x16x32_bf16 v[46:49], v[166:169], v[186:189], v[46:49]
	v_mfma_f32_16x16x32_bf16 v[46:49], v[170:173], v[190:193], v[46:49]
	v_mfma_f32_16x16x32_bf16 v[42:45], v[174:177], v[186:189], v[42:45]
	v_mfma_f32_16x16x32_bf16 v[42:45], v[182:185], v[190:193], v[42:45]
	v_mfma_f32_16x16x32_bf16 v[30:33], v[166:169], v[194:197], v[30:33]
	v_mfma_f32_16x16x32_bf16 v[30:33], v[170:173], v[198:201], v[30:33]
	v_mfma_f32_16x16x32_bf16 v[26:29], v[174:177], v[194:197], v[26:29]
	v_mfma_f32_16x16x32_bf16 v[26:29], v[182:185], v[198:201], v[26:29]
	v_mfma_f32_16x16x32_bf16 v[14:17], v[166:169], v[202:205], v[14:17]
	v_mfma_f32_16x16x32_bf16 v[14:17], v[170:173], v[206:209], v[14:17]
	v_mfma_f32_16x16x32_bf16 v[10:13], v[174:177], v[202:205], v[10:13]
	v_mfma_f32_16x16x32_bf16 v[10:13], v[182:185], v[206:209], v[10:13]
	v_mfma_f32_16x16x32_bf16 v[6:9], v[166:169], v[210:213], v[6:9]
	v_mfma_f32_16x16x32_bf16 v[6:9], v[170:173], v[214:217], v[6:9]
	v_mfma_f32_16x16x32_bf16 v[2:5], v[174:177], v[210:213], v[2:5]
	v_mfma_f32_16x16x32_bf16 v[2:5], v[182:185], v[214:217], v[2:5]
	s_barrier
	s_setprio 0
	s_add_i32 s66, 0, 0x18000
	v_add_u32_e32 v153, s66, v148
	s_add_i32 s67, 0, 0x1c000
	ds_read_b128 v[144:147], v153
	ds_read_b128 v[154:157], v153 offset:1024
	ds_read_b128 v[158:161], v153 offset:2048
	ds_read_b128 v[162:165], v153 offset:3072
	v_add_u32_e32 v153, s67, v148
	ds_read_b128 v[166:169], v153
	ds_read_b128 v[170:173], v153 offset:1024
	ds_read_b128 v[174:177], v153 offset:2048
	ds_read_b128 v[182:185], v153 offset:3072
	s_add_u32 s26, s26, 0x80000
	s_addc_u32 s27, s27, 0
	s_mov_b32 m0, s35
	v_lshl_add_u64 v[226:227], s[26:27], 0, v[130:131]
	ds_read_b128 v[186:189], v152 offset:32768
	ds_read_b128 v[190:193], v152 offset:33792
	ds_read_b128 v[194:197], v152 offset:34816
	ds_read_b128 v[198:201], v152 offset:35840
	ds_read_b128 v[202:205], v152 offset:36864
	ds_read_b128 v[206:209], v152 offset:37888
	ds_read_b128 v[210:213], v152 offset:38912
	ds_read_b128 v[214:217], v152 offset:39936
	global_load_lds_dwordx4 v[226:227], off
	v_lshl_add_u64 v[226:227], s[26:27], 0, v[134:135]
	s_mov_b32 m0, s36
	s_nop 0
	global_load_lds_dwordx4 v[226:227], off
	s_waitcnt vmcnt(8)
	s_waitcnt lgkmcnt(0)
	s_setprio 1
	s_barrier
	v_mfma_f32_16x16x32_bf16 v[126:129], v[144:147], v[186:189], v[126:129]
	v_mfma_f32_16x16x32_bf16 v[126:129], v[154:157], v[190:193], v[126:129]
	v_mfma_f32_16x16x32_bf16 v[122:125], v[158:161], v[186:189], v[122:125]
	v_mfma_f32_16x16x32_bf16 v[122:125], v[162:165], v[190:193], v[122:125]
	v_mfma_f32_16x16x32_bf16 v[118:121], v[144:147], v[194:197], v[118:121]
	v_mfma_f32_16x16x32_bf16 v[118:121], v[154:157], v[198:201], v[118:121]
	v_mfma_f32_16x16x32_bf16 v[114:117], v[158:161], v[194:197], v[114:117]
	v_mfma_f32_16x16x32_bf16 v[114:117], v[162:165], v[198:201], v[114:117]
	v_mfma_f32_16x16x32_bf16 v[106:109], v[144:147], v[202:205], v[106:109]
	v_mfma_f32_16x16x32_bf16 v[106:109], v[154:157], v[206:209], v[106:109]
	v_mfma_f32_16x16x32_bf16 v[98:101], v[158:161], v[202:205], v[98:101]
	v_mfma_f32_16x16x32_bf16 v[98:101], v[162:165], v[206:209], v[98:101]
	v_mfma_f32_16x16x32_bf16 v[90:93], v[144:147], v[210:213], v[90:93]
	v_mfma_f32_16x16x32_bf16 v[90:93], v[154:157], v[214:217], v[90:93]
	v_mfma_f32_16x16x32_bf16 v[82:85], v[158:161], v[210:213], v[82:85]
	v_mfma_f32_16x16x32_bf16 v[82:85], v[162:165], v[214:217], v[82:85]
	v_mfma_f32_16x16x32_bf16 v[110:113], v[166:169], v[186:189], v[110:113]
	v_mfma_f32_16x16x32_bf16 v[110:113], v[170:173], v[190:193], v[110:113]
	v_mfma_f32_16x16x32_bf16 v[102:105], v[174:177], v[186:189], v[102:105]
	v_mfma_f32_16x16x32_bf16 v[102:105], v[182:185], v[190:193], v[102:105]
	v_mfma_f32_16x16x32_bf16 v[94:97], v[166:169], v[194:197], v[94:97]
	v_mfma_f32_16x16x32_bf16 v[94:97], v[170:173], v[198:201], v[94:97]
	v_mfma_f32_16x16x32_bf16 v[86:89], v[174:177], v[194:197], v[86:89]
	v_mfma_f32_16x16x32_bf16 v[86:89], v[182:185], v[198:201], v[86:89]
	v_mfma_f32_16x16x32_bf16 v[78:81], v[166:169], v[202:205], v[78:81]
	v_mfma_f32_16x16x32_bf16 v[78:81], v[170:173], v[206:209], v[78:81]
	v_mfma_f32_16x16x32_bf16 v[74:77], v[174:177], v[202:205], v[74:77]
	v_mfma_f32_16x16x32_bf16 v[74:77], v[182:185], v[206:209], v[74:77]
	v_mfma_f32_16x16x32_bf16 v[70:73], v[166:169], v[210:213], v[70:73]
	v_mfma_f32_16x16x32_bf16 v[70:73], v[170:173], v[214:217], v[70:73]
	v_mfma_f32_16x16x32_bf16 v[66:69], v[174:177], v[210:213], v[66:69]
	v_mfma_f32_16x16x32_bf16 v[66:69], v[182:185], v[214:217], v[66:69]
	s_barrier
	s_setprio 0
	s_add_i32 s26, s66, s30
	v_lshl_add_u64 v[218:219], v[218:219], 0, s[6:7]
	s_mov_b32 m0, s26
	ds_read_b128 v[186:189], v152 offset:49152
	ds_read_b128 v[190:193], v152 offset:50176
	ds_read_b128 v[194:197], v152 offset:51200
	ds_read_b128 v[198:201], v152 offset:52224
	ds_read_b128 v[202:205], v152 offset:53248
	ds_read_b128 v[206:209], v152 offset:54272
	ds_read_b128 v[210:213], v152 offset:55296
	ds_read_b128 v[214:217], v152 offset:56320
	global_load_lds_dwordx4 v[218:219], off
	s_add_i32 m0, s26, 0x2000
	s_add_u32 s22, s22, 0x80080
	v_lshl_add_u64 v[218:219], v[220:221], 0, s[6:7]
	s_addc_u32 s23, s23, 0
	s_add_i32 s26, s67, s30
	global_load_lds_dwordx4 v[218:219], off
	v_lshl_add_u64 v[218:219], s[22:23], 0, v[132:133]
	s_mov_b32 m0, s26
	s_nop 0
	global_load_lds_dwordx4 v[218:219], off
	v_lshl_add_u64 v[218:219], s[22:23], 0, v[136:137]
	s_add_i32 m0, s26, 0x2000
	s_nop 0
	global_load_lds_dwordx4 v[218:219], off
	v_lshl_add_u64 v[218:219], v[222:223], 0, s[6:7]
	s_mov_b32 m0, s52
	s_nop 0
	global_load_lds_dwordx4 v[218:219], off
	v_lshl_add_u64 v[218:219], v[224:225], 0, s[6:7]
	s_mov_b32 m0, s53
	s_nop 0
	global_load_lds_dwordx4 v[218:219], off
	s_waitcnt vmcnt(8)
	s_waitcnt lgkmcnt(0)
	s_setprio 1
	s_barrier
	v_mfma_f32_16x16x32_bf16 v[62:65], v[144:147], v[186:189], v[62:65]
	v_mfma_f32_16x16x32_bf16 v[62:65], v[154:157], v[190:193], v[62:65]
	v_mfma_f32_16x16x32_bf16 v[58:61], v[158:161], v[186:189], v[58:61]
	v_mfma_f32_16x16x32_bf16 v[58:61], v[162:165], v[190:193], v[58:61]
	v_mfma_f32_16x16x32_bf16 v[54:57], v[144:147], v[194:197], v[54:57]
	v_mfma_f32_16x16x32_bf16 v[54:57], v[154:157], v[198:201], v[54:57]
	v_mfma_f32_16x16x32_bf16 v[50:53], v[158:161], v[194:197], v[50:53]
	v_mfma_f32_16x16x32_bf16 v[50:53], v[162:165], v[198:201], v[50:53]
	v_mfma_f32_16x16x32_bf16 v[38:41], v[144:147], v[202:205], v[38:41]
	v_mfma_f32_16x16x32_bf16 v[38:41], v[154:157], v[206:209], v[38:41]
	v_mfma_f32_16x16x32_bf16 v[34:37], v[158:161], v[202:205], v[34:37]
	v_mfma_f32_16x16x32_bf16 v[34:37], v[162:165], v[206:209], v[34:37]
	v_mfma_f32_16x16x32_bf16 v[22:25], v[144:147], v[210:213], v[22:25]
	v_mfma_f32_16x16x32_bf16 v[22:25], v[154:157], v[214:217], v[22:25]
	v_mfma_f32_16x16x32_bf16 v[18:21], v[158:161], v[210:213], v[18:21]
	v_mfma_f32_16x16x32_bf16 v[18:21], v[162:165], v[214:217], v[18:21]
	v_mfma_f32_16x16x32_bf16 v[46:49], v[166:169], v[186:189], v[46:49]
	v_mfma_f32_16x16x32_bf16 v[46:49], v[170:173], v[190:193], v[46:49]
	v_mfma_f32_16x16x32_bf16 v[42:45], v[174:177], v[186:189], v[42:45]
	v_mfma_f32_16x16x32_bf16 v[42:45], v[182:185], v[190:193], v[42:45]
	v_mfma_f32_16x16x32_bf16 v[30:33], v[166:169], v[194:197], v[30:33]
	v_mfma_f32_16x16x32_bf16 v[30:33], v[170:173], v[198:201], v[30:33]
	v_mfma_f32_16x16x32_bf16 v[26:29], v[174:177], v[194:197], v[26:29]
	v_mfma_f32_16x16x32_bf16 v[26:29], v[182:185], v[198:201], v[26:29]
	v_mfma_f32_16x16x32_bf16 v[14:17], v[166:169], v[202:205], v[14:17]
	v_mfma_f32_16x16x32_bf16 v[14:17], v[170:173], v[206:209], v[14:17]
	v_mfma_f32_16x16x32_bf16 v[10:13], v[174:177], v[202:205], v[10:13]
	v_mfma_f32_16x16x32_bf16 v[10:13], v[182:185], v[206:209], v[10:13]
	v_mfma_f32_16x16x32_bf16 v[6:9], v[166:169], v[210:213], v[6:9]
	v_mfma_f32_16x16x32_bf16 v[6:9], v[170:173], v[214:217], v[6:9]
	v_mfma_f32_16x16x32_bf16 v[2:5], v[174:177], v[210:213], v[2:5]
	v_mfma_f32_16x16x32_bf16 v[2:5], v[182:185], v[214:217], v[2:5]
	s_barrier
	s_setprio 0
	s_add_u32 s20, s20, 0x100
	s_addc_u32 s21, s21, 0
	s_add_u32 s13, s13, 0x100
	s_addc_u32 s15, s15, 0
	s_cmp_ge_i32 s63, s62
	s_mov_b32 s22, s63
	s_cbranch_scc0 .LBB0_591
	s_and_b64 vcc, exec, s[8:9]
	s_cbranch_vccz .LBB0_594
	s_barrier

.LBB0_736:
	ds_read_b128 v[154:157], v151
	ds_read_b128 v[158:161], v151 offset:1024
	ds_read_b128 v[162:165], v151 offset:2048
	ds_read_b128 v[166:169], v151 offset:3072
	ds_read_b128 v[170:173], v152
	ds_read_b128 v[174:177], v152 offset:1024
	ds_read_b128 v[182:185], v152 offset:2048
	ds_read_b128 v[186:189], v152 offset:3072
	s_add_u32 s20, s18, 0xfff80080
	s_addc_u32 s21, s19, -1
	s_cmp_eq_u32 s63, 28
	s_cselect_b32 s23, s11, s21
	s_cselect_b32 s22, s58, s20
	s_cselect_b32 s21, s9, s62
	s_cselect_b32 s20, s59, s60
	v_lshl_add_u64 v[146:147], s[18:19], 0, v[138:139]
	s_add_i32 m0, s31, 0xc000
	ds_read_b128 v[190:193], v153
	ds_read_b128 v[194:197], v153 offset:1024
	ds_read_b128 v[198:201], v153 offset:2048
	ds_read_b128 v[202:205], v153 offset:3072
	ds_read_b128 v[206:209], v153 offset:4096
	ds_read_b128 v[210:213], v153 offset:5120
	ds_read_b128 v[214:217], v153 offset:6144
	ds_read_b128 v[218:221], v153 offset:7168
	global_load_lds_dwordx4 v[146:147], off
	v_lshl_add_u64 v[146:147], s[18:19], 0, v[140:141]
	s_add_i32 m0, s31, 0xe000
	s_nop 0
	global_load_lds_dwordx4 v[146:147], off
	s_waitcnt vmcnt(8)
	s_waitcnt lgkmcnt(0)
	s_setprio 1
	s_barrier
	v_mfma_f32_16x16x32_bf16 v[126:129], v[154:157], v[190:193], v[126:129]
	v_mfma_f32_16x16x32_bf16 v[126:129], v[158:161], v[194:197], v[126:129]
	v_mfma_f32_16x16x32_bf16 v[118:121], v[162:165], v[190:193], v[118:121]
	v_mfma_f32_16x16x32_bf16 v[118:121], v[166:169], v[194:197], v[118:121]
	v_mfma_f32_16x16x32_bf16 v[110:113], v[154:157], v[198:201], v[110:113]
	v_mfma_f32_16x16x32_bf16 v[110:113], v[158:161], v[202:205], v[110:113]
	v_mfma_f32_16x16x32_bf16 v[102:105], v[162:165], v[198:201], v[102:105]
	v_mfma_f32_16x16x32_bf16 v[102:105], v[166:169], v[202:205], v[102:105]
	v_mfma_f32_16x16x32_bf16 v[94:97], v[154:157], v[206:209], v[94:97]
	v_mfma_f32_16x16x32_bf16 v[94:97], v[158:161], v[210:213], v[94:97]
	v_mfma_f32_16x16x32_bf16 v[86:89], v[162:165], v[206:209], v[86:89]
	v_mfma_f32_16x16x32_bf16 v[86:89], v[166:169], v[210:213], v[86:89]
	v_mfma_f32_16x16x32_bf16 v[78:81], v[154:157], v[214:217], v[78:81]
	v_mfma_f32_16x16x32_bf16 v[78:81], v[158:161], v[218:221], v[78:81]
	v_mfma_f32_16x16x32_bf16 v[70:73], v[162:165], v[214:217], v[70:73]
	v_mfma_f32_16x16x32_bf16 v[70:73], v[166:169], v[218:221], v[70:73]
	v_mfma_f32_16x16x32_bf16 v[122:125], v[170:173], v[190:193], v[122:125]
	v_mfma_f32_16x16x32_bf16 v[122:125], v[174:177], v[194:197], v[122:125]
	v_mfma_f32_16x16x32_bf16 v[114:117], v[182:185], v[190:193], v[114:117]
	v_mfma_f32_16x16x32_bf16 v[114:117], v[186:189], v[194:197], v[114:117]
	v_mfma_f32_16x16x32_bf16 v[106:109], v[170:173], v[198:201], v[106:109]
	v_mfma_f32_16x16x32_bf16 v[106:109], v[174:177], v[202:205], v[106:109]
	v_mfma_f32_16x16x32_bf16 v[98:101], v[182:185], v[198:201], v[98:101]
	v_mfma_f32_16x16x32_bf16 v[98:101], v[186:189], v[202:205], v[98:101]
	v_mfma_f32_16x16x32_bf16 v[90:93], v[170:173], v[206:209], v[90:93]
	v_mfma_f32_16x16x32_bf16 v[90:93], v[174:177], v[210:213], v[90:93]
	v_mfma_f32_16x16x32_bf16 v[82:85], v[182:185], v[206:209], v[82:85]
	v_mfma_f32_16x16x32_bf16 v[82:85], v[186:189], v[210:213], v[82:85]
	v_mfma_f32_16x16x32_bf16 v[74:77], v[170:173], v[214:217], v[74:77]
	v_mfma_f32_16x16x32_bf16 v[74:77], v[174:177], v[218:221], v[74:77]
	v_mfma_f32_16x16x32_bf16 v[66:69], v[182:185], v[214:217], v[66:69]
	v_mfma_f32_16x16x32_bf16 v[66:69], v[186:189], v[218:221], v[66:69]
	s_barrier
	s_setprio 0
	s_add_i32 s66, s55, s28
	v_lshl_add_u64 v[146:147], s[20:21], 0, v[134:135]
	s_mov_b32 m0, s66
	ds_read_b128 v[190:193], v153 offset:16384
	ds_read_b128 v[194:197], v153 offset:17408
	ds_read_b128 v[198:201], v153 offset:18432
	ds_read_b128 v[202:205], v153 offset:19456
	ds_read_b128 v[206:209], v153 offset:20480
	ds_read_b128 v[210:213], v153 offset:21504
	ds_read_b128 v[214:217], v153 offset:22528
	ds_read_b128 v[218:221], v153 offset:23552
	global_load_lds_dwordx4 v[146:147], off
	s_add_i32 m0, s66, 0x2000
	s_add_u32 s66, s20, 0x80000
	v_lshl_add_u64 v[222:223], s[20:21], 0, v[130:131]
	s_addc_u32 s67, s21, 0
	s_add_i32 s68, s56, s28
	global_load_lds_dwordx4 v[222:223], off
	v_lshl_add_u64 v[224:225], s[66:67], 0, v[134:135]
	s_mov_b32 m0, s68
	v_lshl_add_u64 v[226:227], s[22:23], 0, v[132:133]
	global_load_lds_dwordx4 v[224:225], off
	v_lshl_add_u64 v[224:225], s[66:67], 0, v[130:131]
	s_add_i32 m0, s68, 0x2000
	s_nop 0
	global_load_lds_dwordx4 v[224:225], off
	v_lshl_add_u64 v[224:225], s[22:23], 0, v[136:137]
	s_mov_b32 m0, s31
	s_nop 0
	global_load_lds_dwordx4 v[224:225], off
	s_mov_b32 m0, s34
	s_nop 0
	global_load_lds_dwordx4 v[226:227], off
	s_waitcnt vmcnt(8)
	s_waitcnt lgkmcnt(0)
	s_setprio 1
	s_barrier
	v_mfma_f32_16x16x32_bf16 v[62:65], v[154:157], v[190:193], v[62:65]
	v_mfma_f32_16x16x32_bf16 v[62:65], v[158:161], v[194:197], v[62:65]
	v_mfma_f32_16x16x32_bf16 v[54:57], v[162:165], v[190:193], v[54:57]
	v_mfma_f32_16x16x32_bf16 v[54:57], v[166:169], v[194:197], v[54:57]
	v_mfma_f32_16x16x32_bf16 v[46:49], v[154:157], v[198:201], v[46:49]
	v_mfma_f32_16x16x32_bf16 v[46:49], v[158:161], v[202:205], v[46:49]
	v_mfma_f32_16x16x32_bf16 v[38:41], v[162:165], v[198:201], v[38:41]
	v_mfma_f32_16x16x32_bf16 v[38:41], v[166:169], v[202:205], v[38:41]
	v_mfma_f32_16x16x32_bf16 v[30:33], v[154:157], v[206:209], v[30:33]
	v_mfma_f32_16x16x32_bf16 v[30:33], v[158:161], v[210:213], v[30:33]
	v_mfma_f32_16x16x32_bf16 v[22:25], v[162:165], v[206:209], v[22:25]
	v_mfma_f32_16x16x32_bf16 v[22:25], v[166:169], v[210:213], v[22:25]
	v_mfma_f32_16x16x32_bf16 v[14:17], v[154:157], v[214:217], v[14:17]
	v_mfma_f32_16x16x32_bf16 v[14:17], v[158:161], v[218:221], v[14:17]
	v_mfma_f32_16x16x32_bf16 v[6:9], v[162:165], v[214:217], v[6:9]
	v_mfma_f32_16x16x32_bf16 v[6:9], v[166:169], v[218:221], v[6:9]
	v_mfma_f32_16x16x32_bf16 v[58:61], v[170:173], v[190:193], v[58:61]
	v_mfma_f32_16x16x32_bf16 v[58:61], v[174:177], v[194:197], v[58:61]
	v_mfma_f32_16x16x32_bf16 v[50:53], v[182:185], v[190:193], v[50:53]
	v_mfma_f32_16x16x32_bf16 v[50:53], v[186:189], v[194:197], v[50:53]
	v_mfma_f32_16x16x32_bf16 v[42:45], v[170:173], v[198:201], v[42:45]
	v_mfma_f32_16x16x32_bf16 v[42:45], v[174:177], v[202:205], v[42:45]
	v_mfma_f32_16x16x32_bf16 v[34:37], v[182:185], v[198:201], v[34:37]
	v_mfma_f32_16x16x32_bf16 v[34:37], v[186:189], v[202:205], v[34:37]
	v_mfma_f32_16x16x32_bf16 v[26:29], v[170:173], v[206:209], v[26:29]
	v_mfma_f32_16x16x32_bf16 v[26:29], v[174:177], v[210:213], v[26:29]
	v_mfma_f32_16x16x32_bf16 v[18:21], v[182:185], v[206:209], v[18:21]
	v_mfma_f32_16x16x32_bf16 v[18:21], v[186:189], v[210:213], v[18:21]
	v_mfma_f32_16x16x32_bf16 v[10:13], v[170:173], v[214:217], v[10:13]
	v_mfma_f32_16x16x32_bf16 v[10:13], v[174:177], v[218:221], v[10:13]
	v_mfma_f32_16x16x32_bf16 v[2:5], v[182:185], v[214:217], v[2:5]
	v_mfma_f32_16x16x32_bf16 v[2:5], v[186:189], v[218:221], v[2:5]
	s_barrier
	s_setprio 0
	s_add_i32 s66, 0, 0x18000
	s_add_i32 s67, 0, 0x1c000
	v_add_u32_e32 v166, s66, v149
	v_add_u32_e32 v179, s67, v149
	ds_read_b128 v[154:157], v166
	ds_read_b128 v[158:161], v166 offset:1024
	ds_read_b128 v[162:165], v166 offset:2048
	ds_read_b128 v[166:169], v166 offset:3072
	ds_read_b128 v[170:173], v179
	ds_read_b128 v[174:177], v179 offset:1024
	ds_read_b128 v[182:185], v179 offset:2048
	ds_read_b128 v[186:189], v179 offset:3072
	s_add_u32 s22, s22, 0x80000
	s_addc_u32 s23, s23, 0
	s_mov_b32 m0, s35
	v_lshl_add_u64 v[228:229], s[22:23], 0, v[136:137]
	ds_read_b128 v[190:193], v153 offset:32768
	ds_read_b128 v[194:197], v153 offset:33792
	ds_read_b128 v[198:201], v153 offset:34816
	ds_read_b128 v[202:205], v153 offset:35840
	ds_read_b128 v[206:209], v153 offset:36864
	ds_read_b128 v[210:213], v153 offset:37888
	ds_read_b128 v[214:217], v153 offset:38912
	ds_read_b128 v[218:221], v153 offset:39936
	global_load_lds_dwordx4 v[228:229], off
	v_lshl_add_u64 v[228:229], s[22:23], 0, v[132:133]
	s_mov_b32 m0, s36
	s_nop 0
	global_load_lds_dwordx4 v[228:229], off
	s_waitcnt vmcnt(8)
	s_waitcnt lgkmcnt(0)
	s_setprio 1
	s_barrier
	v_mfma_f32_16x16x32_bf16 v[126:129], v[154:157], v[190:193], v[126:129]
	v_mfma_f32_16x16x32_bf16 v[126:129], v[158:161], v[194:197], v[126:129]
	v_mfma_f32_16x16x32_bf16 v[118:121], v[162:165], v[190:193], v[118:121]
	v_mfma_f32_16x16x32_bf16 v[118:121], v[166:169], v[194:197], v[118:121]
	v_mfma_f32_16x16x32_bf16 v[110:113], v[154:157], v[198:201], v[110:113]
	v_mfma_f32_16x16x32_bf16 v[110:113], v[158:161], v[202:205], v[110:113]
	v_mfma_f32_16x16x32_bf16 v[102:105], v[162:165], v[198:201], v[102:105]
	v_mfma_f32_16x16x32_bf16 v[102:105], v[166:169], v[202:205], v[102:105]
	v_mfma_f32_16x16x32_bf16 v[94:97], v[154:157], v[206:209], v[94:97]
	v_mfma_f32_16x16x32_bf16 v[94:97], v[158:161], v[210:213], v[94:97]
	v_mfma_f32_16x16x32_bf16 v[86:89], v[162:165], v[206:209], v[86:89]
	v_mfma_f32_16x16x32_bf16 v[86:89], v[166:169], v[210:213], v[86:89]
	v_mfma_f32_16x16x32_bf16 v[78:81], v[154:157], v[214:217], v[78:81]
	v_mfma_f32_16x16x32_bf16 v[78:81], v[158:161], v[218:221], v[78:81]
	v_mfma_f32_16x16x32_bf16 v[70:73], v[162:165], v[214:217], v[70:73]
	v_mfma_f32_16x16x32_bf16 v[70:73], v[166:169], v[218:221], v[70:73]
	v_mfma_f32_16x16x32_bf16 v[122:125], v[170:173], v[190:193], v[122:125]
	v_mfma_f32_16x16x32_bf16 v[122:125], v[174:177], v[194:197], v[122:125]
	v_mfma_f32_16x16x32_bf16 v[114:117], v[182:185], v[190:193], v[114:117]
	v_mfma_f32_16x16x32_bf16 v[114:117], v[186:189], v[194:197], v[114:117]
	v_mfma_f32_16x16x32_bf16 v[106:109], v[170:173], v[198:201], v[106:109]
	v_mfma_f32_16x16x32_bf16 v[106:109], v[174:177], v[202:205], v[106:109]
	v_mfma_f32_16x16x32_bf16 v[98:101], v[182:185], v[198:201], v[98:101]
	v_mfma_f32_16x16x32_bf16 v[98:101], v[186:189], v[202:205], v[98:101]
	v_mfma_f32_16x16x32_bf16 v[90:93], v[170:173], v[206:209], v[90:93]
	v_mfma_f32_16x16x32_bf16 v[90:93], v[174:177], v[210:213], v[90:93]
	v_mfma_f32_16x16x32_bf16 v[82:85], v[182:185], v[206:209], v[82:85]
	v_mfma_f32_16x16x32_bf16 v[82:85], v[186:189], v[210:213], v[82:85]
	v_mfma_f32_16x16x32_bf16 v[74:77], v[170:173], v[214:217], v[74:77]
	v_mfma_f32_16x16x32_bf16 v[74:77], v[174:177], v[218:221], v[74:77]
	v_mfma_f32_16x16x32_bf16 v[66:69], v[182:185], v[214:217], v[66:69]
	v_mfma_f32_16x16x32_bf16 v[66:69], v[186:189], v[218:221], v[66:69]
	s_barrier
	s_setprio 0
	s_add_i32 s22, s66, s28
	v_lshl_add_u64 v[146:147], v[146:147], 0, s[4:5]
	s_mov_b32 m0, s22
	ds_read_b128 v[190:193], v153 offset:49152
	ds_read_b128 v[194:197], v153 offset:50176
	ds_read_b128 v[198:201], v153 offset:51200
	ds_read_b128 v[202:205], v153 offset:52224
	ds_read_b128 v[206:209], v153 offset:53248
	ds_read_b128 v[210:213], v153 offset:54272
	ds_read_b128 v[214:217], v153 offset:55296
	ds_read_b128 v[218:221], v153 offset:56320
	global_load_lds_dwordx4 v[146:147], off
	s_add_i32 m0, s22, 0x2000
	s_add_u32 s20, s20, 0x80080
	v_lshl_add_u64 v[146:147], v[222:223], 0, s[4:5]
	s_addc_u32 s21, s21, 0
	s_add_i32 s22, s67, s28
	global_load_lds_dwordx4 v[146:147], off
	v_lshl_add_u64 v[146:147], s[20:21], 0, v[134:135]
	s_mov_b32 m0, s22
	s_nop 0
	global_load_lds_dwordx4 v[146:147], off
	v_lshl_add_u64 v[146:147], s[20:21], 0, v[130:131]
	s_add_i32 m0, s22, 0x2000
	s_nop 0
	global_load_lds_dwordx4 v[146:147], off
	v_lshl_add_u64 v[146:147], v[224:225], 0, s[4:5]
	s_mov_b32 m0, s52
	s_nop 0
	global_load_lds_dwordx4 v[146:147], off
	v_lshl_add_u64 v[146:147], v[226:227], 0, s[4:5]
	s_mov_b32 m0, s53
	s_nop 0
	global_load_lds_dwordx4 v[146:147], off
	s_waitcnt vmcnt(8)
	s_waitcnt lgkmcnt(0)
	s_setprio 1
	s_barrier
	v_mfma_f32_16x16x32_bf16 v[62:65], v[154:157], v[190:193], v[62:65]
	v_mfma_f32_16x16x32_bf16 v[62:65], v[158:161], v[194:197], v[62:65]
	v_mfma_f32_16x16x32_bf16 v[54:57], v[162:165], v[190:193], v[54:57]
	v_mfma_f32_16x16x32_bf16 v[54:57], v[166:169], v[194:197], v[54:57]
	v_mfma_f32_16x16x32_bf16 v[46:49], v[154:157], v[198:201], v[46:49]
	v_mfma_f32_16x16x32_bf16 v[46:49], v[158:161], v[202:205], v[46:49]
	v_mfma_f32_16x16x32_bf16 v[38:41], v[162:165], v[198:201], v[38:41]
	v_mfma_f32_16x16x32_bf16 v[38:41], v[166:169], v[202:205], v[38:41]
	v_mfma_f32_16x16x32_bf16 v[30:33], v[154:157], v[206:209], v[30:33]
	v_mfma_f32_16x16x32_bf16 v[30:33], v[158:161], v[210:213], v[30:33]
	v_mfma_f32_16x16x32_bf16 v[22:25], v[162:165], v[206:209], v[22:25]
	v_mfma_f32_16x16x32_bf16 v[22:25], v[166:169], v[210:213], v[22:25]
	v_mfma_f32_16x16x32_bf16 v[14:17], v[154:157], v[214:217], v[14:17]
	v_mfma_f32_16x16x32_bf16 v[14:17], v[158:161], v[218:221], v[14:17]
	v_mfma_f32_16x16x32_bf16 v[6:9], v[162:165], v[214:217], v[6:9]
	v_mfma_f32_16x16x32_bf16 v[6:9], v[166:169], v[218:221], v[6:9]
	v_mfma_f32_16x16x32_bf16 v[58:61], v[170:173], v[190:193], v[58:61]
	v_mfma_f32_16x16x32_bf16 v[58:61], v[174:177], v[194:197], v[58:61]
	v_mfma_f32_16x16x32_bf16 v[50:53], v[182:185], v[190:193], v[50:53]
	v_mfma_f32_16x16x32_bf16 v[50:53], v[186:189], v[194:197], v[50:53]
	v_mfma_f32_16x16x32_bf16 v[42:45], v[170:173], v[198:201], v[42:45]
	v_mfma_f32_16x16x32_bf16 v[42:45], v[174:177], v[202:205], v[42:45]
	v_mfma_f32_16x16x32_bf16 v[34:37], v[182:185], v[198:201], v[34:37]
	v_mfma_f32_16x16x32_bf16 v[34:37], v[186:189], v[202:205], v[34:37]
	v_mfma_f32_16x16x32_bf16 v[26:29], v[170:173], v[206:209], v[26:29]
	v_mfma_f32_16x16x32_bf16 v[26:29], v[174:177], v[210:213], v[26:29]
	v_mfma_f32_16x16x32_bf16 v[18:21], v[182:185], v[206:209], v[18:21]
	v_mfma_f32_16x16x32_bf16 v[18:21], v[186:189], v[210:213], v[18:21]
	v_mfma_f32_16x16x32_bf16 v[10:13], v[170:173], v[214:217], v[10:13]
	v_mfma_f32_16x16x32_bf16 v[10:13], v[174:177], v[218:221], v[10:13]
	v_mfma_f32_16x16x32_bf16 v[2:5], v[182:185], v[214:217], v[2:5]
	v_mfma_f32_16x16x32_bf16 v[2:5], v[186:189], v[218:221], v[2:5]
	s_barrier
	s_setprio 0
	s_add_i32 s63, s63, 2
	s_add_u32 s18, s18, 0x100
	s_addc_u32 s19, s19, 0
	s_add_u32 s60, s60, 0x100
	s_addc_u32 s62, s62, 0
	s_cmp_gt_u32 s63, 29
	s_cbranch_scc0 .LBB0_736
	s_and_b64 vcc, exec, s[6:7]
	s_cbranch_vccz .LBB0_739
	s_barrier

.LBB0_854:
	ds_read_b128 v[144:147], v151
	ds_read_b128 v[154:157], v151 offset:1024
	ds_read_b128 v[158:161], v151 offset:2048
	ds_read_b128 v[162:165], v151 offset:3072
	ds_read_b128 v[166:169], v152
	ds_read_b128 v[170:173], v152 offset:1024
	ds_read_b128 v[174:177], v152 offset:2048
	ds_read_b128 v[182:185], v152 offset:3072
	s_add_i32 s63, s14, 2
	s_add_u32 s15, s12, 0xffea0080
	s_addc_u32 s16, s13, -1
	s_cmp_eq_u32 s59, s14
	s_cselect_b32 s14, s10, s60
	s_cselect_b32 s17, s9, s16
	s_cselect_b32 s16, s8, s15
	s_cselect_b32 s15, s11, s62
	v_lshl_add_u64 v[218:219], s[12:13], 0, v[138:139]
	s_add_i32 m0, s23, 0xc000
	ds_read_b128 v[186:189], v153
	ds_read_b128 v[190:193], v153 offset:1024
	ds_read_b128 v[194:197], v153 offset:2048
	ds_read_b128 v[198:201], v153 offset:3072
	ds_read_b128 v[202:205], v153 offset:4096
	ds_read_b128 v[206:209], v153 offset:5120
	ds_read_b128 v[210:213], v153 offset:6144
	ds_read_b128 v[214:217], v153 offset:7168
	global_load_lds_dwordx4 v[218:219], off
	v_lshl_add_u64 v[218:219], s[12:13], 0, v[140:141]
	s_add_i32 m0, s23, 0xe000
	s_nop 0
	global_load_lds_dwordx4 v[218:219], off
	s_waitcnt vmcnt(8)
	s_waitcnt lgkmcnt(0)
	s_setprio 1
	s_barrier
	v_mfma_f32_16x16x32_bf16 v[126:129], v[144:147], v[186:189], v[126:129]
	v_mfma_f32_16x16x32_bf16 v[126:129], v[154:157], v[190:193], v[126:129]
	v_mfma_f32_16x16x32_bf16 v[122:125], v[158:161], v[186:189], v[122:125]
	v_mfma_f32_16x16x32_bf16 v[122:125], v[162:165], v[190:193], v[122:125]
	v_mfma_f32_16x16x32_bf16 v[118:121], v[144:147], v[194:197], v[118:121]
	v_mfma_f32_16x16x32_bf16 v[118:121], v[154:157], v[198:201], v[118:121]
	v_mfma_f32_16x16x32_bf16 v[114:117], v[158:161], v[194:197], v[114:117]
	v_mfma_f32_16x16x32_bf16 v[114:117], v[162:165], v[198:201], v[114:117]
	v_mfma_f32_16x16x32_bf16 v[106:109], v[144:147], v[202:205], v[106:109]
	v_mfma_f32_16x16x32_bf16 v[106:109], v[154:157], v[206:209], v[106:109]
	v_mfma_f32_16x16x32_bf16 v[98:101], v[158:161], v[202:205], v[98:101]
	v_mfma_f32_16x16x32_bf16 v[98:101], v[162:165], v[206:209], v[98:101]
	v_mfma_f32_16x16x32_bf16 v[90:93], v[144:147], v[210:213], v[90:93]
	v_mfma_f32_16x16x32_bf16 v[90:93], v[154:157], v[214:217], v[90:93]
	v_mfma_f32_16x16x32_bf16 v[82:85], v[158:161], v[210:213], v[82:85]
	v_mfma_f32_16x16x32_bf16 v[82:85], v[162:165], v[214:217], v[82:85]
	v_mfma_f32_16x16x32_bf16 v[110:113], v[166:169], v[186:189], v[110:113]
	v_mfma_f32_16x16x32_bf16 v[110:113], v[170:173], v[190:193], v[110:113]
	v_mfma_f32_16x16x32_bf16 v[102:105], v[174:177], v[186:189], v[102:105]
	v_mfma_f32_16x16x32_bf16 v[102:105], v[182:185], v[190:193], v[102:105]
	v_mfma_f32_16x16x32_bf16 v[94:97], v[166:169], v[194:197], v[94:97]
	v_mfma_f32_16x16x32_bf16 v[94:97], v[170:173], v[198:201], v[94:97]
	v_mfma_f32_16x16x32_bf16 v[86:89], v[174:177], v[194:197], v[86:89]
	v_mfma_f32_16x16x32_bf16 v[86:89], v[182:185], v[198:201], v[86:89]
	v_mfma_f32_16x16x32_bf16 v[78:81], v[166:169], v[202:205], v[78:81]
	v_mfma_f32_16x16x32_bf16 v[78:81], v[170:173], v[206:209], v[78:81]
	v_mfma_f32_16x16x32_bf16 v[74:77], v[174:177], v[202:205], v[74:77]
	v_mfma_f32_16x16x32_bf16 v[74:77], v[182:185], v[206:209], v[74:77]
	v_mfma_f32_16x16x32_bf16 v[70:73], v[166:169], v[210:213], v[70:73]
	v_mfma_f32_16x16x32_bf16 v[70:73], v[170:173], v[214:217], v[70:73]
	v_mfma_f32_16x16x32_bf16 v[66:69], v[174:177], v[210:213], v[66:69]
	v_mfma_f32_16x16x32_bf16 v[66:69], v[182:185], v[214:217], v[66:69]
	s_barrier
	s_setprio 0
	s_add_i32 s66, s36, s20
	v_lshl_add_u64 v[218:219], s[14:15], 0, v[132:133]
	s_mov_b32 m0, s66
	ds_read_b128 v[186:189], v153 offset:16384
	ds_read_b128 v[190:193], v153 offset:17408
	ds_read_b128 v[194:197], v153 offset:18432
	ds_read_b128 v[198:201], v153 offset:19456
	ds_read_b128 v[202:205], v153 offset:20480
	ds_read_b128 v[206:209], v153 offset:21504
	ds_read_b128 v[210:213], v153 offset:22528
	ds_read_b128 v[214:217], v153 offset:23552
	global_load_lds_dwordx4 v[218:219], off
	s_add_i32 m0, s66, 0x2000
	s_add_u32 s66, s14, 0x160000
	v_lshl_add_u64 v[220:221], s[14:15], 0, v[136:137]
	s_addc_u32 s67, s15, 0
	s_add_i32 s68, s37, s20
	global_load_lds_dwordx4 v[220:221], off
	v_lshl_add_u64 v[222:223], s[66:67], 0, v[132:133]
	s_mov_b32 m0, s68
	v_lshl_add_u64 v[224:225], s[16:17], 0, v[134:135]
	global_load_lds_dwordx4 v[222:223], off
	v_lshl_add_u64 v[222:223], s[66:67], 0, v[136:137]
	s_add_i32 m0, s68, 0x2000
	s_nop 0
	global_load_lds_dwordx4 v[222:223], off
	v_lshl_add_u64 v[222:223], s[16:17], 0, v[130:131]
	s_mov_b32 m0, s23
	s_nop 0
	global_load_lds_dwordx4 v[222:223], off
	s_mov_b32 m0, s26
	s_nop 0
	global_load_lds_dwordx4 v[224:225], off
	s_waitcnt vmcnt(8)
	s_waitcnt lgkmcnt(0)
	s_setprio 1
	s_barrier
	v_mfma_f32_16x16x32_bf16 v[62:65], v[144:147], v[186:189], v[62:65]
	v_mfma_f32_16x16x32_bf16 v[62:65], v[154:157], v[190:193], v[62:65]
	v_mfma_f32_16x16x32_bf16 v[58:61], v[158:161], v[186:189], v[58:61]
	v_mfma_f32_16x16x32_bf16 v[58:61], v[162:165], v[190:193], v[58:61]
	v_mfma_f32_16x16x32_bf16 v[54:57], v[144:147], v[194:197], v[54:57]
	v_mfma_f32_16x16x32_bf16 v[54:57], v[154:157], v[198:201], v[54:57]
	v_mfma_f32_16x16x32_bf16 v[50:53], v[158:161], v[194:197], v[50:53]
	v_mfma_f32_16x16x32_bf16 v[50:53], v[162:165], v[198:201], v[50:53]
	v_mfma_f32_16x16x32_bf16 v[38:41], v[144:147], v[202:205], v[38:41]
	v_mfma_f32_16x16x32_bf16 v[38:41], v[154:157], v[206:209], v[38:41]
	v_mfma_f32_16x16x32_bf16 v[34:37], v[158:161], v[202:205], v[34:37]
	v_mfma_f32_16x16x32_bf16 v[34:37], v[162:165], v[206:209], v[34:37]
	v_mfma_f32_16x16x32_bf16 v[22:25], v[144:147], v[210:213], v[22:25]
	v_mfma_f32_16x16x32_bf16 v[22:25], v[154:157], v[214:217], v[22:25]
	v_mfma_f32_16x16x32_bf16 v[18:21], v[158:161], v[210:213], v[18:21]
	v_mfma_f32_16x16x32_bf16 v[18:21], v[162:165], v[214:217], v[18:21]
	v_mfma_f32_16x16x32_bf16 v[46:49], v[166:169], v[186:189], v[46:49]
	v_mfma_f32_16x16x32_bf16 v[46:49], v[170:173], v[190:193], v[46:49]
	v_mfma_f32_16x16x32_bf16 v[42:45], v[174:177], v[186:189], v[42:45]
	v_mfma_f32_16x16x32_bf16 v[42:45], v[182:185], v[190:193], v[42:45]
	v_mfma_f32_16x16x32_bf16 v[30:33], v[166:169], v[194:197], v[30:33]
	v_mfma_f32_16x16x32_bf16 v[30:33], v[170:173], v[198:201], v[30:33]
	v_mfma_f32_16x16x32_bf16 v[26:29], v[174:177], v[194:197], v[26:29]
	v_mfma_f32_16x16x32_bf16 v[26:29], v[182:185], v[198:201], v[26:29]
	v_mfma_f32_16x16x32_bf16 v[14:17], v[166:169], v[202:205], v[14:17]
	v_mfma_f32_16x16x32_bf16 v[14:17], v[170:173], v[206:209], v[14:17]
	v_mfma_f32_16x16x32_bf16 v[10:13], v[174:177], v[202:205], v[10:13]
	v_mfma_f32_16x16x32_bf16 v[10:13], v[182:185], v[206:209], v[10:13]
	v_mfma_f32_16x16x32_bf16 v[6:9], v[166:169], v[210:213], v[6:9]
	v_mfma_f32_16x16x32_bf16 v[6:9], v[170:173], v[214:217], v[6:9]
	v_mfma_f32_16x16x32_bf16 v[2:5], v[174:177], v[210:213], v[2:5]
	v_mfma_f32_16x16x32_bf16 v[2:5], v[182:185], v[214:217], v[2:5]
	s_barrier
	s_setprio 0
	s_add_i32 s66, 0, 0x18000
	s_add_i32 s67, 0, 0x1c000
	v_add_u32_e32 v162, s66, v149
	v_add_u32_e32 v179, s67, v149
	ds_read_b128 v[144:147], v162
	ds_read_b128 v[154:157], v162 offset:1024
	ds_read_b128 v[158:161], v162 offset:2048
	ds_read_b128 v[162:165], v162 offset:3072
	ds_read_b128 v[166:169], v179
	ds_read_b128 v[170:173], v179 offset:1024
	ds_read_b128 v[174:177], v179 offset:2048
	ds_read_b128 v[182:185], v179 offset:3072
	s_add_u32 s16, s16, 0x160000
	s_addc_u32 s17, s17, 0
	s_mov_b32 m0, s27
	v_lshl_add_u64 v[226:227], s[16:17], 0, v[130:131]
	ds_read_b128 v[186:189], v153 offset:32768
	ds_read_b128 v[190:193], v153 offset:33792
	ds_read_b128 v[194:197], v153 offset:34816
	ds_read_b128 v[198:201], v153 offset:35840
	ds_read_b128 v[202:205], v153 offset:36864
	ds_read_b128 v[206:209], v153 offset:37888
	ds_read_b128 v[210:213], v153 offset:38912
	ds_read_b128 v[214:217], v153 offset:39936
	global_load_lds_dwordx4 v[226:227], off
	v_lshl_add_u64 v[226:227], s[16:17], 0, v[134:135]
	s_mov_b32 m0, s28
	s_nop 0
	global_load_lds_dwordx4 v[226:227], off
	s_waitcnt vmcnt(8)
	s_waitcnt lgkmcnt(0)
	s_setprio 1
	s_barrier
	v_mfma_f32_16x16x32_bf16 v[126:129], v[144:147], v[186:189], v[126:129]
	v_mfma_f32_16x16x32_bf16 v[126:129], v[154:157], v[190:193], v[126:129]
	v_mfma_f32_16x16x32_bf16 v[122:125], v[158:161], v[186:189], v[122:125]
	v_mfma_f32_16x16x32_bf16 v[122:125], v[162:165], v[190:193], v[122:125]
	v_mfma_f32_16x16x32_bf16 v[118:121], v[144:147], v[194:197], v[118:121]
	v_mfma_f32_16x16x32_bf16 v[118:121], v[154:157], v[198:201], v[118:121]
	v_mfma_f32_16x16x32_bf16 v[114:117], v[158:161], v[194:197], v[114:117]
	v_mfma_f32_16x16x32_bf16 v[114:117], v[162:165], v[198:201], v[114:117]
	v_mfma_f32_16x16x32_bf16 v[106:109], v[144:147], v[202:205], v[106:109]
	v_mfma_f32_16x16x32_bf16 v[106:109], v[154:157], v[206:209], v[106:109]
	v_mfma_f32_16x16x32_bf16 v[98:101], v[158:161], v[202:205], v[98:101]
	v_mfma_f32_16x16x32_bf16 v[98:101], v[162:165], v[206:209], v[98:101]
	v_mfma_f32_16x16x32_bf16 v[90:93], v[144:147], v[210:213], v[90:93]
	v_mfma_f32_16x16x32_bf16 v[90:93], v[154:157], v[214:217], v[90:93]
	v_mfma_f32_16x16x32_bf16 v[82:85], v[158:161], v[210:213], v[82:85]
	v_mfma_f32_16x16x32_bf16 v[82:85], v[162:165], v[214:217], v[82:85]
	v_mfma_f32_16x16x32_bf16 v[110:113], v[166:169], v[186:189], v[110:113]
	v_mfma_f32_16x16x32_bf16 v[110:113], v[170:173], v[190:193], v[110:113]
	v_mfma_f32_16x16x32_bf16 v[102:105], v[174:177], v[186:189], v[102:105]
	v_mfma_f32_16x16x32_bf16 v[102:105], v[182:185], v[190:193], v[102:105]
	v_mfma_f32_16x16x32_bf16 v[94:97], v[166:169], v[194:197], v[94:97]
	v_mfma_f32_16x16x32_bf16 v[94:97], v[170:173], v[198:201], v[94:97]
	v_mfma_f32_16x16x32_bf16 v[86:89], v[174:177], v[194:197], v[86:89]
	v_mfma_f32_16x16x32_bf16 v[86:89], v[182:185], v[198:201], v[86:89]
	v_mfma_f32_16x16x32_bf16 v[78:81], v[166:169], v[202:205], v[78:81]
	v_mfma_f32_16x16x32_bf16 v[78:81], v[170:173], v[206:209], v[78:81]
	v_mfma_f32_16x16x32_bf16 v[74:77], v[174:177], v[202:205], v[74:77]
	v_mfma_f32_16x16x32_bf16 v[74:77], v[182:185], v[206:209], v[74:77]
	v_mfma_f32_16x16x32_bf16 v[70:73], v[166:169], v[210:213], v[70:73]
	v_mfma_f32_16x16x32_bf16 v[70:73], v[170:173], v[214:217], v[70:73]
	v_mfma_f32_16x16x32_bf16 v[66:69], v[174:177], v[210:213], v[66:69]
	v_mfma_f32_16x16x32_bf16 v[66:69], v[182:185], v[214:217], v[66:69]
	s_barrier
	s_setprio 0
	s_add_i32 s16, s66, s20
	v_lshl_add_u64 v[218:219], v[218:219], 0, s[4:5]
	s_mov_b32 m0, s16
	ds_read_b128 v[186:189], v153 offset:49152
	ds_read_b128 v[190:193], v153 offset:50176
	ds_read_b128 v[194:197], v153 offset:51200
	ds_read_b128 v[198:201], v153 offset:52224
	ds_read_b128 v[202:205], v153 offset:53248
	ds_read_b128 v[206:209], v153 offset:54272
	ds_read_b128 v[210:213], v153 offset:55296
	ds_read_b128 v[214:217], v153 offset:56320
	global_load_lds_dwordx4 v[218:219], off
	s_add_i32 m0, s16, 0x2000
	s_add_u32 s14, s14, 0x160080
	v_lshl_add_u64 v[218:219], v[220:221], 0, s[4:5]
	s_addc_u32 s15, s15, 0
	s_add_i32 s16, s67, s20
	global_load_lds_dwordx4 v[218:219], off
	v_lshl_add_u64 v[218:219], s[14:15], 0, v[132:133]
	s_mov_b32 m0, s16
	s_nop 0
	global_load_lds_dwordx4 v[218:219], off
	v_lshl_add_u64 v[218:219], s[14:15], 0, v[136:137]
	s_add_i32 m0, s16, 0x2000
	s_nop 0
	global_load_lds_dwordx4 v[218:219], off
	v_lshl_add_u64 v[218:219], v[222:223], 0, s[4:5]
	s_mov_b32 m0, s30
	s_nop 0
	global_load_lds_dwordx4 v[218:219], off
	v_lshl_add_u64 v[218:219], v[224:225], 0, s[4:5]
	s_mov_b32 m0, s31
	s_nop 0
	global_load_lds_dwordx4 v[218:219], off
	s_waitcnt vmcnt(8)
	s_waitcnt lgkmcnt(0)
	s_setprio 1
	s_barrier
	v_mfma_f32_16x16x32_bf16 v[62:65], v[144:147], v[186:189], v[62:65]
	v_mfma_f32_16x16x32_bf16 v[62:65], v[154:157], v[190:193], v[62:65]
	v_mfma_f32_16x16x32_bf16 v[58:61], v[158:161], v[186:189], v[58:61]
	v_mfma_f32_16x16x32_bf16 v[58:61], v[162:165], v[190:193], v[58:61]
	v_mfma_f32_16x16x32_bf16 v[54:57], v[144:147], v[194:197], v[54:57]
	v_mfma_f32_16x16x32_bf16 v[54:57], v[154:157], v[198:201], v[54:57]
	v_mfma_f32_16x16x32_bf16 v[50:53], v[158:161], v[194:197], v[50:53]
	v_mfma_f32_16x16x32_bf16 v[50:53], v[162:165], v[198:201], v[50:53]
	v_mfma_f32_16x16x32_bf16 v[38:41], v[144:147], v[202:205], v[38:41]
	v_mfma_f32_16x16x32_bf16 v[38:41], v[154:157], v[206:209], v[38:41]
	v_mfma_f32_16x16x32_bf16 v[34:37], v[158:161], v[202:205], v[34:37]
	v_mfma_f32_16x16x32_bf16 v[34:37], v[162:165], v[206:209], v[34:37]
	v_mfma_f32_16x16x32_bf16 v[22:25], v[144:147], v[210:213], v[22:25]
	v_mfma_f32_16x16x32_bf16 v[22:25], v[154:157], v[214:217], v[22:25]
	v_mfma_f32_16x16x32_bf16 v[18:21], v[158:161], v[210:213], v[18:21]
	v_mfma_f32_16x16x32_bf16 v[18:21], v[162:165], v[214:217], v[18:21]
	v_mfma_f32_16x16x32_bf16 v[46:49], v[166:169], v[186:189], v[46:49]
	v_mfma_f32_16x16x32_bf16 v[46:49], v[170:173], v[190:193], v[46:49]
	v_mfma_f32_16x16x32_bf16 v[42:45], v[174:177], v[186:189], v[42:45]
	v_mfma_f32_16x16x32_bf16 v[42:45], v[182:185], v[190:193], v[42:45]
	v_mfma_f32_16x16x32_bf16 v[30:33], v[166:169], v[194:197], v[30:33]
	v_mfma_f32_16x16x32_bf16 v[30:33], v[170:173], v[198:201], v[30:33]
	v_mfma_f32_16x16x32_bf16 v[26:29], v[174:177], v[194:197], v[26:29]
	v_mfma_f32_16x16x32_bf16 v[26:29], v[182:185], v[198:201], v[26:29]
	v_mfma_f32_16x16x32_bf16 v[14:17], v[166:169], v[202:205], v[14:17]
	v_mfma_f32_16x16x32_bf16 v[14:17], v[170:173], v[206:209], v[14:17]
	v_mfma_f32_16x16x32_bf16 v[10:13], v[174:177], v[202:205], v[10:13]
	v_mfma_f32_16x16x32_bf16 v[10:13], v[182:185], v[206:209], v[10:13]
	v_mfma_f32_16x16x32_bf16 v[6:9], v[166:169], v[210:213], v[6:9]
	v_mfma_f32_16x16x32_bf16 v[6:9], v[170:173], v[214:217], v[6:9]
	v_mfma_f32_16x16x32_bf16 v[2:5], v[174:177], v[210:213], v[2:5]
	v_mfma_f32_16x16x32_bf16 v[2:5], v[182:185], v[214:217], v[2:5]
	s_barrier
	s_setprio 0
	s_add_u32 s12, s12, 0x100
	s_addc_u32 s13, s13, 0
	s_add_u32 s60, s60, 0x100
	s_addc_u32 s62, s62, 0
	s_cmp_ge_i32 s63, s58
	s_mov_b32 s14, s63
	s_cbranch_scc0 .LBB0_854
	s_and_b64 vcc, exec, s[6:7]
	s_cbranch_vccz .LBB0_857
	s_barrier

.LBB0_1037:
	ds_read_b128 v[150:153], v170
	ds_read_b128 v[154:157], v170 offset:1024
	ds_read_b128 v[158:161], v170 offset:2048
	ds_read_b128 v[182:185], v170 offset:3072
	ds_read_b128 v[186:189], v171
	ds_read_b128 v[190:193], v171 offset:1024
	ds_read_b128 v[194:197], v171 offset:2048
	ds_read_b128 v[198:201], v171 offset:3072
	s_add_u32 s34, s4, 0xfff80080
	s_addc_u32 s35, s5, -1
	s_cmp_eq_u32 s69, 28
	s_cselect_b32 s37, s9, s35
	s_cselect_b32 s36, s14, s34
	s_cselect_b32 s35, s23, s68
	s_cselect_b32 s34, s27, s67
	v_lshl_add_u64 v[176:177], s[4:5], 0, v[142:143]
	s_add_i32 m0, s13, 0xc000
	ds_read_b128 v[202:205], v172
	ds_read_b128 v[206:209], v172 offset:1024
	ds_read_b128 v[210:213], v172 offset:2048
	ds_read_b128 v[214:217], v172 offset:3072
	ds_read_b128 v[218:221], v172 offset:4096
	ds_read_b128 v[222:225], v172 offset:5120
	ds_read_b128 v[226:229], v172 offset:6144
	ds_read_b128 v[230:233], v172 offset:7168
	global_load_lds_dwordx4 v[176:177], off
	v_lshl_add_u64 v[176:177], s[4:5], 0, v[144:145]
	s_add_i32 m0, s13, 0xe000
	s_nop 0
	global_load_lds_dwordx4 v[176:177], off
	s_waitcnt vmcnt(8)
	s_waitcnt lgkmcnt(0)
	s_setprio 1
	s_barrier
	v_mfma_f32_16x16x32_bf16 v[126:129], v[150:153], v[202:205], v[126:129]
	v_mfma_f32_16x16x32_bf16 v[126:129], v[154:157], v[206:209], v[126:129]
	v_mfma_f32_16x16x32_bf16 v[122:125], v[158:161], v[202:205], v[122:125]
	v_mfma_f32_16x16x32_bf16 v[122:125], v[182:185], v[206:209], v[122:125]
	v_mfma_f32_16x16x32_bf16 v[110:113], v[150:153], v[210:213], v[110:113]
	v_mfma_f32_16x16x32_bf16 v[110:113], v[154:157], v[214:217], v[110:113]
	v_mfma_f32_16x16x32_bf16 v[106:109], v[158:161], v[210:213], v[106:109]
	v_mfma_f32_16x16x32_bf16 v[106:109], v[182:185], v[214:217], v[106:109]
	v_mfma_f32_16x16x32_bf16 v[94:97], v[150:153], v[218:221], v[94:97]
	v_mfma_f32_16x16x32_bf16 v[94:97], v[154:157], v[222:225], v[94:97]
	v_mfma_f32_16x16x32_bf16 v[90:93], v[158:161], v[218:221], v[90:93]
	v_mfma_f32_16x16x32_bf16 v[90:93], v[182:185], v[222:225], v[90:93]
	v_mfma_f32_16x16x32_bf16 v[78:81], v[150:153], v[226:229], v[78:81]
	v_mfma_f32_16x16x32_bf16 v[78:81], v[154:157], v[230:233], v[78:81]
	v_mfma_f32_16x16x32_bf16 v[74:77], v[158:161], v[226:229], v[74:77]
	v_mfma_f32_16x16x32_bf16 v[74:77], v[182:185], v[230:233], v[74:77]
	v_mfma_f32_16x16x32_bf16 v[118:121], v[186:189], v[202:205], v[118:121]
	v_mfma_f32_16x16x32_bf16 v[118:121], v[190:193], v[206:209], v[118:121]
	v_mfma_f32_16x16x32_bf16 v[114:117], v[194:197], v[202:205], v[114:117]
	v_mfma_f32_16x16x32_bf16 v[114:117], v[198:201], v[206:209], v[114:117]
	v_mfma_f32_16x16x32_bf16 v[102:105], v[186:189], v[210:213], v[102:105]
	v_mfma_f32_16x16x32_bf16 v[102:105], v[190:193], v[214:217], v[102:105]
	v_mfma_f32_16x16x32_bf16 v[98:101], v[194:197], v[210:213], v[98:101]
	v_mfma_f32_16x16x32_bf16 v[98:101], v[198:201], v[214:217], v[98:101]
	v_mfma_f32_16x16x32_bf16 v[86:89], v[186:189], v[218:221], v[86:89]
	v_mfma_f32_16x16x32_bf16 v[86:89], v[190:193], v[222:225], v[86:89]
	v_mfma_f32_16x16x32_bf16 v[82:85], v[194:197], v[218:221], v[82:85]
	v_mfma_f32_16x16x32_bf16 v[82:85], v[198:201], v[222:225], v[82:85]
	v_mfma_f32_16x16x32_bf16 v[70:73], v[186:189], v[226:229], v[70:73]
	v_mfma_f32_16x16x32_bf16 v[70:73], v[190:193], v[230:233], v[70:73]
	v_mfma_f32_16x16x32_bf16 v[66:69], v[194:197], v[226:229], v[66:69]
	v_mfma_f32_16x16x32_bf16 v[66:69], v[198:201], v[230:233], v[66:69]
	s_barrier
	s_setprio 0
	s_add_i32 s70, s62, s52
	v_lshl_add_u64 v[176:177], s[34:35], 0, v[132:133]
	s_mov_b32 m0, s70
	ds_read_b128 v[202:205], v172 offset:16384
	ds_read_b128 v[206:209], v172 offset:17408
	ds_read_b128 v[210:213], v172 offset:18432
	ds_read_b128 v[214:217], v172 offset:19456
	ds_read_b128 v[218:221], v172 offset:20480
	ds_read_b128 v[222:225], v172 offset:21504
	ds_read_b128 v[226:229], v172 offset:22528
	ds_read_b128 v[230:233], v172 offset:23552
	global_load_lds_dwordx4 v[176:177], off
	s_add_i32 m0, s70, 0x2000
	s_add_u32 s70, s34, 0x80000
	v_lshl_add_u64 v[234:235], s[34:35], 0, v[136:137]
	s_addc_u32 s71, s35, 0
	s_add_i32 s72, s63, s52
	global_load_lds_dwordx4 v[234:235], off
	v_lshl_add_u64 v[236:237], s[70:71], 0, v[132:133]
	s_mov_b32 m0, s72
	v_lshl_add_u64 v[238:239], s[36:37], 0, v[134:135]
	global_load_lds_dwordx4 v[236:237], off
	v_lshl_add_u64 v[236:237], s[70:71], 0, v[136:137]
	s_add_i32 m0, s72, 0x2000
	s_nop 0
	global_load_lds_dwordx4 v[236:237], off
	v_lshl_add_u64 v[236:237], s[36:37], 0, v[130:131]
	s_mov_b32 m0, s13
	s_nop 0
	global_load_lds_dwordx4 v[236:237], off
	s_mov_b32 m0, s53
	s_nop 0
	global_load_lds_dwordx4 v[238:239], off
	s_waitcnt vmcnt(8)
	s_waitcnt lgkmcnt(0)
	s_setprio 1
	s_barrier
	v_mfma_f32_16x16x32_bf16 v[62:65], v[150:153], v[202:205], v[62:65]
	v_mfma_f32_16x16x32_bf16 v[62:65], v[154:157], v[206:209], v[62:65]
	v_mfma_f32_16x16x32_bf16 v[58:61], v[158:161], v[202:205], v[58:61]
	v_mfma_f32_16x16x32_bf16 v[58:61], v[182:185], v[206:209], v[58:61]
	v_mfma_f32_16x16x32_bf16 v[46:49], v[150:153], v[210:213], v[46:49]
	v_mfma_f32_16x16x32_bf16 v[46:49], v[154:157], v[214:217], v[46:49]
	v_mfma_f32_16x16x32_bf16 v[42:45], v[158:161], v[210:213], v[42:45]
	v_mfma_f32_16x16x32_bf16 v[42:45], v[182:185], v[214:217], v[42:45]
	v_mfma_f32_16x16x32_bf16 v[30:33], v[150:153], v[218:221], v[30:33]
	v_mfma_f32_16x16x32_bf16 v[30:33], v[154:157], v[222:225], v[30:33]
	v_mfma_f32_16x16x32_bf16 v[26:29], v[158:161], v[218:221], v[26:29]
	v_mfma_f32_16x16x32_bf16 v[26:29], v[182:185], v[222:225], v[26:29]
	v_mfma_f32_16x16x32_bf16 v[14:17], v[150:153], v[226:229], v[14:17]
	v_mfma_f32_16x16x32_bf16 v[14:17], v[154:157], v[230:233], v[14:17]
	v_mfma_f32_16x16x32_bf16 v[10:13], v[158:161], v[226:229], v[10:13]
	v_mfma_f32_16x16x32_bf16 v[10:13], v[182:185], v[230:233], v[10:13]
	v_mfma_f32_16x16x32_bf16 v[54:57], v[186:189], v[202:205], v[54:57]
	v_mfma_f32_16x16x32_bf16 v[54:57], v[190:193], v[206:209], v[54:57]
	v_mfma_f32_16x16x32_bf16 v[50:53], v[194:197], v[202:205], v[50:53]
	v_mfma_f32_16x16x32_bf16 v[50:53], v[198:201], v[206:209], v[50:53]
	v_mfma_f32_16x16x32_bf16 v[38:41], v[186:189], v[210:213], v[38:41]
	v_mfma_f32_16x16x32_bf16 v[38:41], v[190:193], v[214:217], v[38:41]
	v_mfma_f32_16x16x32_bf16 v[34:37], v[194:197], v[210:213], v[34:37]
	v_mfma_f32_16x16x32_bf16 v[34:37], v[198:201], v[214:217], v[34:37]
	v_mfma_f32_16x16x32_bf16 v[22:25], v[186:189], v[218:221], v[22:25]
	v_mfma_f32_16x16x32_bf16 v[22:25], v[190:193], v[222:225], v[22:25]
	v_mfma_f32_16x16x32_bf16 v[18:21], v[194:197], v[218:221], v[18:21]
	v_mfma_f32_16x16x32_bf16 v[18:21], v[198:201], v[222:225], v[18:21]
	v_mfma_f32_16x16x32_bf16 v[6:9], v[186:189], v[226:229], v[6:9]
	v_mfma_f32_16x16x32_bf16 v[6:9], v[190:193], v[230:233], v[6:9]
	v_mfma_f32_16x16x32_bf16 v[2:5], v[194:197], v[226:229], v[2:5]
	v_mfma_f32_16x16x32_bf16 v[2:5], v[198:201], v[230:233], v[2:5]
	s_barrier
	s_setprio 0
	s_add_i32 s70, 0, 0x18000
	v_add_u32_e32 v175, s70, v164
	s_add_i32 s71, 0, 0x1c000
	ds_read_b128 v[150:153], v175
	ds_read_b128 v[154:157], v175 offset:1024
	ds_read_b128 v[158:161], v175 offset:2048
	ds_read_b128 v[182:185], v175 offset:3072
	v_add_u32_e32 v175, s71, v164
	ds_read_b128 v[186:189], v175
	ds_read_b128 v[190:193], v175 offset:1024
	ds_read_b128 v[194:197], v175 offset:2048
	ds_read_b128 v[198:201], v175 offset:3072
	s_add_u32 s36, s36, 0x80000
	s_addc_u32 s37, s37, 0
	s_mov_b32 m0, s54
	v_lshl_add_u64 v[240:241], s[36:37], 0, v[130:131]
	ds_read_b128 v[202:205], v172 offset:32768
	ds_read_b128 v[206:209], v172 offset:33792
	ds_read_b128 v[210:213], v172 offset:34816
	ds_read_b128 v[214:217], v172 offset:35840
	ds_read_b128 v[218:221], v172 offset:36864
	ds_read_b128 v[222:225], v172 offset:37888
	ds_read_b128 v[226:229], v172 offset:38912
	ds_read_b128 v[230:233], v172 offset:39936
	global_load_lds_dwordx4 v[240:241], off
	v_lshl_add_u64 v[240:241], s[36:37], 0, v[134:135]
	s_mov_b32 m0, s55
	s_nop 0
	global_load_lds_dwordx4 v[240:241], off
	s_waitcnt vmcnt(8)
	s_waitcnt lgkmcnt(0)
	s_setprio 1
	s_barrier
	v_mfma_f32_16x16x32_bf16 v[126:129], v[150:153], v[202:205], v[126:129]
	v_mfma_f32_16x16x32_bf16 v[126:129], v[154:157], v[206:209], v[126:129]
	v_mfma_f32_16x16x32_bf16 v[122:125], v[158:161], v[202:205], v[122:125]
	v_mfma_f32_16x16x32_bf16 v[122:125], v[182:185], v[206:209], v[122:125]
	v_mfma_f32_16x16x32_bf16 v[110:113], v[150:153], v[210:213], v[110:113]
	v_mfma_f32_16x16x32_bf16 v[110:113], v[154:157], v[214:217], v[110:113]
	v_mfma_f32_16x16x32_bf16 v[106:109], v[158:161], v[210:213], v[106:109]
	v_mfma_f32_16x16x32_bf16 v[106:109], v[182:185], v[214:217], v[106:109]
	v_mfma_f32_16x16x32_bf16 v[94:97], v[150:153], v[218:221], v[94:97]
	v_mfma_f32_16x16x32_bf16 v[94:97], v[154:157], v[222:225], v[94:97]
	v_mfma_f32_16x16x32_bf16 v[90:93], v[158:161], v[218:221], v[90:93]
	v_mfma_f32_16x16x32_bf16 v[90:93], v[182:185], v[222:225], v[90:93]
	v_mfma_f32_16x16x32_bf16 v[78:81], v[150:153], v[226:229], v[78:81]
	v_mfma_f32_16x16x32_bf16 v[78:81], v[154:157], v[230:233], v[78:81]
	v_mfma_f32_16x16x32_bf16 v[74:77], v[158:161], v[226:229], v[74:77]
	v_mfma_f32_16x16x32_bf16 v[74:77], v[182:185], v[230:233], v[74:77]
	v_mfma_f32_16x16x32_bf16 v[118:121], v[186:189], v[202:205], v[118:121]
	v_mfma_f32_16x16x32_bf16 v[118:121], v[190:193], v[206:209], v[118:121]
	v_mfma_f32_16x16x32_bf16 v[114:117], v[194:197], v[202:205], v[114:117]
	v_mfma_f32_16x16x32_bf16 v[114:117], v[198:201], v[206:209], v[114:117]
	v_mfma_f32_16x16x32_bf16 v[102:105], v[186:189], v[210:213], v[102:105]
	v_mfma_f32_16x16x32_bf16 v[102:105], v[190:193], v[214:217], v[102:105]
	v_mfma_f32_16x16x32_bf16 v[98:101], v[194:197], v[210:213], v[98:101]
	v_mfma_f32_16x16x32_bf16 v[98:101], v[198:201], v[214:217], v[98:101]
	v_mfma_f32_16x16x32_bf16 v[86:89], v[186:189], v[218:221], v[86:89]
	v_mfma_f32_16x16x32_bf16 v[86:89], v[190:193], v[222:225], v[86:89]
	v_mfma_f32_16x16x32_bf16 v[82:85], v[194:197], v[218:221], v[82:85]
	v_mfma_f32_16x16x32_bf16 v[82:85], v[198:201], v[222:225], v[82:85]
	v_mfma_f32_16x16x32_bf16 v[70:73], v[186:189], v[226:229], v[70:73]
	v_mfma_f32_16x16x32_bf16 v[70:73], v[190:193], v[230:233], v[70:73]
	v_mfma_f32_16x16x32_bf16 v[66:69], v[194:197], v[226:229], v[66:69]
	v_mfma_f32_16x16x32_bf16 v[66:69], v[198:201], v[230:233], v[66:69]
	s_barrier
	s_setprio 0
	s_add_i32 s36, s70, s52
	v_lshl_add_u64 v[176:177], v[176:177], 0, s[16:17]
	s_mov_b32 m0, s36
	ds_read_b128 v[202:205], v172 offset:49152
	ds_read_b128 v[206:209], v172 offset:50176
	ds_read_b128 v[210:213], v172 offset:51200
	ds_read_b128 v[214:217], v172 offset:52224
	ds_read_b128 v[218:221], v172 offset:53248
	ds_read_b128 v[222:225], v172 offset:54272
	ds_read_b128 v[226:229], v172 offset:55296
	ds_read_b128 v[230:233], v172 offset:56320
	global_load_lds_dwordx4 v[176:177], off
	s_add_i32 m0, s36, 0x2000
	s_add_u32 s34, s34, 0x80080
	v_lshl_add_u64 v[176:177], v[234:235], 0, s[16:17]
	s_addc_u32 s35, s35, 0
	s_add_i32 s36, s71, s52
	global_load_lds_dwordx4 v[176:177], off
	v_lshl_add_u64 v[176:177], s[34:35], 0, v[132:133]
	s_mov_b32 m0, s36
	s_nop 0
	global_load_lds_dwordx4 v[176:177], off
	v_lshl_add_u64 v[176:177], s[34:35], 0, v[136:137]
	s_add_i32 m0, s36, 0x2000
	s_nop 0
	global_load_lds_dwordx4 v[176:177], off
	v_lshl_add_u64 v[176:177], v[236:237], 0, s[16:17]
	s_mov_b32 m0, s56
	s_nop 0
	global_load_lds_dwordx4 v[176:177], off
	v_lshl_add_u64 v[176:177], v[238:239], 0, s[16:17]
	s_mov_b32 m0, s57
	s_nop 0
	global_load_lds_dwordx4 v[176:177], off
	s_waitcnt vmcnt(8)
	s_waitcnt lgkmcnt(0)
	s_setprio 1
	s_barrier
	v_mfma_f32_16x16x32_bf16 v[62:65], v[150:153], v[202:205], v[62:65]
	v_mfma_f32_16x16x32_bf16 v[62:65], v[154:157], v[206:209], v[62:65]
	v_mfma_f32_16x16x32_bf16 v[58:61], v[158:161], v[202:205], v[58:61]
	v_mfma_f32_16x16x32_bf16 v[58:61], v[182:185], v[206:209], v[58:61]
	v_mfma_f32_16x16x32_bf16 v[46:49], v[150:153], v[210:213], v[46:49]
	v_mfma_f32_16x16x32_bf16 v[46:49], v[154:157], v[214:217], v[46:49]
	v_mfma_f32_16x16x32_bf16 v[42:45], v[158:161], v[210:213], v[42:45]
	v_mfma_f32_16x16x32_bf16 v[42:45], v[182:185], v[214:217], v[42:45]
	v_mfma_f32_16x16x32_bf16 v[30:33], v[150:153], v[218:221], v[30:33]
	v_mfma_f32_16x16x32_bf16 v[30:33], v[154:157], v[222:225], v[30:33]
	v_mfma_f32_16x16x32_bf16 v[26:29], v[158:161], v[218:221], v[26:29]
	v_mfma_f32_16x16x32_bf16 v[26:29], v[182:185], v[222:225], v[26:29]
	v_mfma_f32_16x16x32_bf16 v[14:17], v[150:153], v[226:229], v[14:17]
	v_mfma_f32_16x16x32_bf16 v[14:17], v[154:157], v[230:233], v[14:17]
	v_mfma_f32_16x16x32_bf16 v[10:13], v[158:161], v[226:229], v[10:13]
	v_mfma_f32_16x16x32_bf16 v[10:13], v[182:185], v[230:233], v[10:13]
	v_mfma_f32_16x16x32_bf16 v[54:57], v[186:189], v[202:205], v[54:57]
	v_mfma_f32_16x16x32_bf16 v[54:57], v[190:193], v[206:209], v[54:57]
	v_mfma_f32_16x16x32_bf16 v[50:53], v[194:197], v[202:205], v[50:53]
	v_mfma_f32_16x16x32_bf16 v[50:53], v[198:201], v[206:209], v[50:53]
	v_mfma_f32_16x16x32_bf16 v[38:41], v[186:189], v[210:213], v[38:41]
	v_mfma_f32_16x16x32_bf16 v[38:41], v[190:193], v[214:217], v[38:41]
	v_mfma_f32_16x16x32_bf16 v[34:37], v[194:197], v[210:213], v[34:37]
	v_mfma_f32_16x16x32_bf16 v[34:37], v[198:201], v[214:217], v[34:37]
	v_mfma_f32_16x16x32_bf16 v[22:25], v[186:189], v[218:221], v[22:25]
	v_mfma_f32_16x16x32_bf16 v[22:25], v[190:193], v[222:225], v[22:25]
	v_mfma_f32_16x16x32_bf16 v[18:21], v[194:197], v[218:221], v[18:21]
	v_mfma_f32_16x16x32_bf16 v[18:21], v[198:201], v[222:225], v[18:21]
	v_mfma_f32_16x16x32_bf16 v[6:9], v[186:189], v[226:229], v[6:9]
	v_mfma_f32_16x16x32_bf16 v[6:9], v[190:193], v[230:233], v[6:9]
	v_mfma_f32_16x16x32_bf16 v[2:5], v[194:197], v[226:229], v[2:5]
	v_mfma_f32_16x16x32_bf16 v[2:5], v[198:201], v[230:233], v[2:5]
	s_barrier
	s_setprio 0
	s_add_i32 s69, s69, 2
	s_add_u32 s4, s4, 0x100
	s_addc_u32 s5, s5, 0
	s_add_u32 s67, s67, 0x100
	s_addc_u32 s68, s68, 0
	s_cmp_gt_u32 s69, 29
	s_cbranch_scc0 .LBB0_1037
	s_and_b64 vcc, exec, s[18:19]
	s_cbranch_vccz .LBB0_1040
	s_barrier

.LBB0_1637:
	ds_read_b128 v[154:157], v150
	ds_read_b128 v[158:161], v150 offset:1024
	ds_read_b128 v[162:165], v150 offset:2048
	ds_read_b128 v[166:169], v150 offset:3072
	ds_read_b128 v[170:173], v151
	ds_read_b128 v[174:177], v151 offset:1024
	ds_read_b128 v[182:185], v151 offset:2048
	ds_read_b128 v[186:189], v151 offset:3072
	s_add_u32 s20, s18, 0xfff80080
	s_addc_u32 s21, s19, -1
	s_cmp_eq_u32 s63, 28
	s_cselect_b32 s23, s11, s21
	s_cselect_b32 s22, s58, s20
	s_cselect_b32 s21, s9, s62
	s_cselect_b32 s20, s59, s60
	v_lshl_add_u64 v[146:147], s[18:19], 0, v[138:139]
	s_add_i32 m0, s17, 0xc000
	ds_read_b128 v[190:193], v152
	ds_read_b128 v[194:197], v152 offset:1024
	ds_read_b128 v[198:201], v152 offset:2048
	ds_read_b128 v[202:205], v152 offset:3072
	ds_read_b128 v[206:209], v152 offset:4096
	ds_read_b128 v[210:213], v152 offset:5120
	ds_read_b128 v[214:217], v152 offset:6144
	ds_read_b128 v[218:221], v152 offset:7168
	global_load_lds_dwordx4 v[146:147], off
	v_lshl_add_u64 v[146:147], s[18:19], 0, v[140:141]
	s_add_i32 m0, s17, 0xe000
	s_nop 0
	global_load_lds_dwordx4 v[146:147], off
	s_waitcnt vmcnt(8)
	s_waitcnt lgkmcnt(0)
	s_setprio 1
	s_barrier
	v_mfma_f32_16x16x32_bf16 v[126:129], v[154:157], v[190:193], v[126:129]
	v_mfma_f32_16x16x32_bf16 v[126:129], v[158:161], v[194:197], v[126:129]
	v_mfma_f32_16x16x32_bf16 v[122:125], v[162:165], v[190:193], v[122:125]
	v_mfma_f32_16x16x32_bf16 v[122:125], v[166:169], v[194:197], v[122:125]
	v_mfma_f32_16x16x32_bf16 v[110:113], v[154:157], v[198:201], v[110:113]
	v_mfma_f32_16x16x32_bf16 v[110:113], v[158:161], v[202:205], v[110:113]
	v_mfma_f32_16x16x32_bf16 v[106:109], v[162:165], v[198:201], v[106:109]
	v_mfma_f32_16x16x32_bf16 v[106:109], v[166:169], v[202:205], v[106:109]
	v_mfma_f32_16x16x32_bf16 v[94:97], v[154:157], v[206:209], v[94:97]
	v_mfma_f32_16x16x32_bf16 v[94:97], v[158:161], v[210:213], v[94:97]
	v_mfma_f32_16x16x32_bf16 v[90:93], v[162:165], v[206:209], v[90:93]
	v_mfma_f32_16x16x32_bf16 v[90:93], v[166:169], v[210:213], v[90:93]
	v_mfma_f32_16x16x32_bf16 v[78:81], v[154:157], v[214:217], v[78:81]
	v_mfma_f32_16x16x32_bf16 v[78:81], v[158:161], v[218:221], v[78:81]
	v_mfma_f32_16x16x32_bf16 v[74:77], v[162:165], v[214:217], v[74:77]
	v_mfma_f32_16x16x32_bf16 v[74:77], v[166:169], v[218:221], v[74:77]
	v_mfma_f32_16x16x32_bf16 v[118:121], v[170:173], v[190:193], v[118:121]
	v_mfma_f32_16x16x32_bf16 v[118:121], v[174:177], v[194:197], v[118:121]
	v_mfma_f32_16x16x32_bf16 v[114:117], v[182:185], v[190:193], v[114:117]
	v_mfma_f32_16x16x32_bf16 v[114:117], v[186:189], v[194:197], v[114:117]
	v_mfma_f32_16x16x32_bf16 v[102:105], v[170:173], v[198:201], v[102:105]
	v_mfma_f32_16x16x32_bf16 v[102:105], v[174:177], v[202:205], v[102:105]
	v_mfma_f32_16x16x32_bf16 v[98:101], v[182:185], v[198:201], v[98:101]
	v_mfma_f32_16x16x32_bf16 v[98:101], v[186:189], v[202:205], v[98:101]
	v_mfma_f32_16x16x32_bf16 v[86:89], v[170:173], v[206:209], v[86:89]
	v_mfma_f32_16x16x32_bf16 v[86:89], v[174:177], v[210:213], v[86:89]
	v_mfma_f32_16x16x32_bf16 v[82:85], v[182:185], v[206:209], v[82:85]
	v_mfma_f32_16x16x32_bf16 v[82:85], v[186:189], v[210:213], v[82:85]
	v_mfma_f32_16x16x32_bf16 v[70:73], v[170:173], v[214:217], v[70:73]
	v_mfma_f32_16x16x32_bf16 v[70:73], v[174:177], v[218:221], v[70:73]
	v_mfma_f32_16x16x32_bf16 v[66:69], v[182:185], v[214:217], v[66:69]
	v_mfma_f32_16x16x32_bf16 v[66:69], v[186:189], v[218:221], v[66:69]
	s_barrier
	s_setprio 0
	s_add_i32 s66, s54, s28
	v_lshl_add_u64 v[146:147], s[20:21], 0, v[134:135]
	s_mov_b32 m0, s66
	ds_read_b128 v[190:193], v152 offset:16384
	ds_read_b128 v[194:197], v152 offset:17408
	ds_read_b128 v[198:201], v152 offset:18432
	ds_read_b128 v[202:205], v152 offset:19456
	ds_read_b128 v[206:209], v152 offset:20480
	ds_read_b128 v[210:213], v152 offset:21504
	ds_read_b128 v[214:217], v152 offset:22528
	ds_read_b128 v[218:221], v152 offset:23552
	global_load_lds_dwordx4 v[146:147], off
	s_add_i32 m0, s66, 0x2000
	s_add_u32 s66, s20, 0x80000
	v_lshl_add_u64 v[222:223], s[20:21], 0, v[130:131]
	s_addc_u32 s67, s21, 0
	s_add_i32 s68, s55, s28
	global_load_lds_dwordx4 v[222:223], off
	v_lshl_add_u64 v[224:225], s[66:67], 0, v[134:135]
	s_mov_b32 m0, s68
	v_lshl_add_u64 v[226:227], s[22:23], 0, v[132:133]
	global_load_lds_dwordx4 v[224:225], off
	v_lshl_add_u64 v[224:225], s[66:67], 0, v[130:131]
	s_add_i32 m0, s68, 0x2000
	s_nop 0
	global_load_lds_dwordx4 v[224:225], off
	v_lshl_add_u64 v[224:225], s[22:23], 0, v[136:137]
	s_mov_b32 m0, s17
	s_nop 0
	global_load_lds_dwordx4 v[224:225], off
	s_mov_b32 m0, s31
	s_nop 0
	global_load_lds_dwordx4 v[226:227], off
	s_waitcnt vmcnt(8)
	s_waitcnt lgkmcnt(0)
	s_setprio 1
	s_barrier
	v_mfma_f32_16x16x32_bf16 v[62:65], v[154:157], v[190:193], v[62:65]
	v_mfma_f32_16x16x32_bf16 v[62:65], v[158:161], v[194:197], v[62:65]
	v_mfma_f32_16x16x32_bf16 v[58:61], v[162:165], v[190:193], v[58:61]
	v_mfma_f32_16x16x32_bf16 v[58:61], v[166:169], v[194:197], v[58:61]
	v_mfma_f32_16x16x32_bf16 v[46:49], v[154:157], v[198:201], v[46:49]
	v_mfma_f32_16x16x32_bf16 v[46:49], v[158:161], v[202:205], v[46:49]
	v_mfma_f32_16x16x32_bf16 v[42:45], v[162:165], v[198:201], v[42:45]
	v_mfma_f32_16x16x32_bf16 v[42:45], v[166:169], v[202:205], v[42:45]
	v_mfma_f32_16x16x32_bf16 v[30:33], v[154:157], v[206:209], v[30:33]
	v_mfma_f32_16x16x32_bf16 v[30:33], v[158:161], v[210:213], v[30:33]
	v_mfma_f32_16x16x32_bf16 v[26:29], v[162:165], v[206:209], v[26:29]
	v_mfma_f32_16x16x32_bf16 v[26:29], v[166:169], v[210:213], v[26:29]
	v_mfma_f32_16x16x32_bf16 v[14:17], v[154:157], v[214:217], v[14:17]
	v_mfma_f32_16x16x32_bf16 v[14:17], v[158:161], v[218:221], v[14:17]
	v_mfma_f32_16x16x32_bf16 v[10:13], v[162:165], v[214:217], v[10:13]
	v_mfma_f32_16x16x32_bf16 v[10:13], v[166:169], v[218:221], v[10:13]
	v_mfma_f32_16x16x32_bf16 v[54:57], v[170:173], v[190:193], v[54:57]
	v_mfma_f32_16x16x32_bf16 v[54:57], v[174:177], v[194:197], v[54:57]
	v_mfma_f32_16x16x32_bf16 v[50:53], v[182:185], v[190:193], v[50:53]
	v_mfma_f32_16x16x32_bf16 v[50:53], v[186:189], v[194:197], v[50:53]
	v_mfma_f32_16x16x32_bf16 v[38:41], v[170:173], v[198:201], v[38:41]
	v_mfma_f32_16x16x32_bf16 v[38:41], v[174:177], v[202:205], v[38:41]
	v_mfma_f32_16x16x32_bf16 v[34:37], v[182:185], v[198:201], v[34:37]
	v_mfma_f32_16x16x32_bf16 v[34:37], v[186:189], v[202:205], v[34:37]
	v_mfma_f32_16x16x32_bf16 v[22:25], v[170:173], v[206:209], v[22:25]
	v_mfma_f32_16x16x32_bf16 v[22:25], v[174:177], v[210:213], v[22:25]
	v_mfma_f32_16x16x32_bf16 v[18:21], v[182:185], v[206:209], v[18:21]
	v_mfma_f32_16x16x32_bf16 v[18:21], v[186:189], v[210:213], v[18:21]
	v_mfma_f32_16x16x32_bf16 v[6:9], v[170:173], v[214:217], v[6:9]
	v_mfma_f32_16x16x32_bf16 v[6:9], v[174:177], v[218:221], v[6:9]
	v_mfma_f32_16x16x32_bf16 v[2:5], v[182:185], v[214:217], v[2:5]
	v_mfma_f32_16x16x32_bf16 v[2:5], v[186:189], v[218:221], v[2:5]
	s_barrier
	s_setprio 0
	s_add_i32 s66, 0, 0x18000
	v_add_u32_e32 v153, s66, v148
	s_add_i32 s67, 0, 0x1c000
	ds_read_b128 v[154:157], v153
	ds_read_b128 v[158:161], v153 offset:1024
	ds_read_b128 v[162:165], v153 offset:2048
	ds_read_b128 v[166:169], v153 offset:3072
	v_add_u32_e32 v153, s67, v148
	ds_read_b128 v[170:173], v153
	ds_read_b128 v[174:177], v153 offset:1024
	ds_read_b128 v[182:185], v153 offset:2048
	ds_read_b128 v[186:189], v153 offset:3072
	s_add_u32 s22, s22, 0x80000
	s_addc_u32 s23, s23, 0
	s_mov_b32 m0, s34
	v_lshl_add_u64 v[228:229], s[22:23], 0, v[136:137]
	ds_read_b128 v[190:193], v152 offset:32768
	ds_read_b128 v[194:197], v152 offset:33792
	ds_read_b128 v[198:201], v152 offset:34816
	ds_read_b128 v[202:205], v152 offset:35840
	ds_read_b128 v[206:209], v152 offset:36864
	ds_read_b128 v[210:213], v152 offset:37888
	ds_read_b128 v[214:217], v152 offset:38912
	ds_read_b128 v[218:221], v152 offset:39936
	global_load_lds_dwordx4 v[228:229], off
	v_lshl_add_u64 v[228:229], s[22:23], 0, v[132:133]
	s_mov_b32 m0, s35
	s_nop 0
	global_load_lds_dwordx4 v[228:229], off
	s_waitcnt vmcnt(8)
	s_waitcnt lgkmcnt(0)
	s_setprio 1
	s_barrier
	v_mfma_f32_16x16x32_bf16 v[126:129], v[154:157], v[190:193], v[126:129]
	v_mfma_f32_16x16x32_bf16 v[126:129], v[158:161], v[194:197], v[126:129]
	v_mfma_f32_16x16x32_bf16 v[122:125], v[162:165], v[190:193], v[122:125]
	v_mfma_f32_16x16x32_bf16 v[122:125], v[166:169], v[194:197], v[122:125]
	v_mfma_f32_16x16x32_bf16 v[110:113], v[154:157], v[198:201], v[110:113]
	v_mfma_f32_16x16x32_bf16 v[110:113], v[158:161], v[202:205], v[110:113]
	v_mfma_f32_16x16x32_bf16 v[106:109], v[162:165], v[198:201], v[106:109]
	v_mfma_f32_16x16x32_bf16 v[106:109], v[166:169], v[202:205], v[106:109]
	v_mfma_f32_16x16x32_bf16 v[94:97], v[154:157], v[206:209], v[94:97]
	v_mfma_f32_16x16x32_bf16 v[94:97], v[158:161], v[210:213], v[94:97]
	v_mfma_f32_16x16x32_bf16 v[90:93], v[162:165], v[206:209], v[90:93]
	v_mfma_f32_16x16x32_bf16 v[90:93], v[166:169], v[210:213], v[90:93]
	v_mfma_f32_16x16x32_bf16 v[78:81], v[154:157], v[214:217], v[78:81]
	v_mfma_f32_16x16x32_bf16 v[78:81], v[158:161], v[218:221], v[78:81]
	v_mfma_f32_16x16x32_bf16 v[74:77], v[162:165], v[214:217], v[74:77]
	v_mfma_f32_16x16x32_bf16 v[74:77], v[166:169], v[218:221], v[74:77]
	v_mfma_f32_16x16x32_bf16 v[118:121], v[170:173], v[190:193], v[118:121]
	v_mfma_f32_16x16x32_bf16 v[118:121], v[174:177], v[194:197], v[118:121]
	v_mfma_f32_16x16x32_bf16 v[114:117], v[182:185], v[190:193], v[114:117]
	v_mfma_f32_16x16x32_bf16 v[114:117], v[186:189], v[194:197], v[114:117]
	v_mfma_f32_16x16x32_bf16 v[102:105], v[170:173], v[198:201], v[102:105]
	v_mfma_f32_16x16x32_bf16 v[102:105], v[174:177], v[202:205], v[102:105]
	v_mfma_f32_16x16x32_bf16 v[98:101], v[182:185], v[198:201], v[98:101]
	v_mfma_f32_16x16x32_bf16 v[98:101], v[186:189], v[202:205], v[98:101]
	v_mfma_f32_16x16x32_bf16 v[86:89], v[170:173], v[206:209], v[86:89]
	v_mfma_f32_16x16x32_bf16 v[86:89], v[174:177], v[210:213], v[86:89]
	v_mfma_f32_16x16x32_bf16 v[82:85], v[182:185], v[206:209], v[82:85]
	v_mfma_f32_16x16x32_bf16 v[82:85], v[186:189], v[210:213], v[82:85]
	v_mfma_f32_16x16x32_bf16 v[70:73], v[170:173], v[214:217], v[70:73]
	v_mfma_f32_16x16x32_bf16 v[70:73], v[174:177], v[218:221], v[70:73]
	v_mfma_f32_16x16x32_bf16 v[66:69], v[182:185], v[214:217], v[66:69]
	v_mfma_f32_16x16x32_bf16 v[66:69], v[186:189], v[218:221], v[66:69]
	s_barrier
	s_setprio 0
	s_add_i32 s22, s66, s28
	v_lshl_add_u64 v[146:147], v[146:147], 0, s[4:5]
	s_mov_b32 m0, s22
	ds_read_b128 v[190:193], v152 offset:49152
	ds_read_b128 v[194:197], v152 offset:50176
	ds_read_b128 v[198:201], v152 offset:51200
	ds_read_b128 v[202:205], v152 offset:52224
	ds_read_b128 v[206:209], v152 offset:53248
	ds_read_b128 v[210:213], v152 offset:54272
	ds_read_b128 v[214:217], v152 offset:55296
	ds_read_b128 v[218:221], v152 offset:56320
	global_load_lds_dwordx4 v[146:147], off
	s_add_i32 m0, s22, 0x2000
	s_add_u32 s20, s20, 0x80080
	v_lshl_add_u64 v[146:147], v[222:223], 0, s[4:5]
	s_addc_u32 s21, s21, 0
	s_add_i32 s22, s67, s28
	global_load_lds_dwordx4 v[146:147], off
	v_lshl_add_u64 v[146:147], s[20:21], 0, v[134:135]
	s_mov_b32 m0, s22
	s_nop 0
	global_load_lds_dwordx4 v[146:147], off
	v_lshl_add_u64 v[146:147], s[20:21], 0, v[130:131]
	s_add_i32 m0, s22, 0x2000
	s_nop 0
	global_load_lds_dwordx4 v[146:147], off
	v_lshl_add_u64 v[146:147], v[224:225], 0, s[4:5]
	s_mov_b32 m0, s37
	s_nop 0
	global_load_lds_dwordx4 v[146:147], off
	v_lshl_add_u64 v[146:147], v[226:227], 0, s[4:5]
	s_mov_b32 m0, s52
	s_nop 0
	global_load_lds_dwordx4 v[146:147], off
	s_waitcnt vmcnt(8)
	s_waitcnt lgkmcnt(0)
	s_setprio 1
	s_barrier
	v_mfma_f32_16x16x32_bf16 v[62:65], v[154:157], v[190:193], v[62:65]
	v_mfma_f32_16x16x32_bf16 v[62:65], v[158:161], v[194:197], v[62:65]
	v_mfma_f32_16x16x32_bf16 v[58:61], v[162:165], v[190:193], v[58:61]
	v_mfma_f32_16x16x32_bf16 v[58:61], v[166:169], v[194:197], v[58:61]
	v_mfma_f32_16x16x32_bf16 v[46:49], v[154:157], v[198:201], v[46:49]
	v_mfma_f32_16x16x32_bf16 v[46:49], v[158:161], v[202:205], v[46:49]
	v_mfma_f32_16x16x32_bf16 v[42:45], v[162:165], v[198:201], v[42:45]
	v_mfma_f32_16x16x32_bf16 v[42:45], v[166:169], v[202:205], v[42:45]
	v_mfma_f32_16x16x32_bf16 v[30:33], v[154:157], v[206:209], v[30:33]
	v_mfma_f32_16x16x32_bf16 v[30:33], v[158:161], v[210:213], v[30:33]
	v_mfma_f32_16x16x32_bf16 v[26:29], v[162:165], v[206:209], v[26:29]
	v_mfma_f32_16x16x32_bf16 v[26:29], v[166:169], v[210:213], v[26:29]
	v_mfma_f32_16x16x32_bf16 v[14:17], v[154:157], v[214:217], v[14:17]
	v_mfma_f32_16x16x32_bf16 v[14:17], v[158:161], v[218:221], v[14:17]
	v_mfma_f32_16x16x32_bf16 v[10:13], v[162:165], v[214:217], v[10:13]
	v_mfma_f32_16x16x32_bf16 v[10:13], v[166:169], v[218:221], v[10:13]
	v_mfma_f32_16x16x32_bf16 v[54:57], v[170:173], v[190:193], v[54:57]
	v_mfma_f32_16x16x32_bf16 v[54:57], v[174:177], v[194:197], v[54:57]
	v_mfma_f32_16x16x32_bf16 v[50:53], v[182:185], v[190:193], v[50:53]
	v_mfma_f32_16x16x32_bf16 v[50:53], v[186:189], v[194:197], v[50:53]
	v_mfma_f32_16x16x32_bf16 v[38:41], v[170:173], v[198:201], v[38:41]
	v_mfma_f32_16x16x32_bf16 v[38:41], v[174:177], v[202:205], v[38:41]
	v_mfma_f32_16x16x32_bf16 v[34:37], v[182:185], v[198:201], v[34:37]
	v_mfma_f32_16x16x32_bf16 v[34:37], v[186:189], v[202:205], v[34:37]
	v_mfma_f32_16x16x32_bf16 v[22:25], v[170:173], v[206:209], v[22:25]
	v_mfma_f32_16x16x32_bf16 v[22:25], v[174:177], v[210:213], v[22:25]
	v_mfma_f32_16x16x32_bf16 v[18:21], v[182:185], v[206:209], v[18:21]
	v_mfma_f32_16x16x32_bf16 v[18:21], v[186:189], v[210:213], v[18:21]
	v_mfma_f32_16x16x32_bf16 v[6:9], v[170:173], v[214:217], v[6:9]
	v_mfma_f32_16x16x32_bf16 v[6:9], v[174:177], v[218:221], v[6:9]
	v_mfma_f32_16x16x32_bf16 v[2:5], v[182:185], v[214:217], v[2:5]
	v_mfma_f32_16x16x32_bf16 v[2:5], v[186:189], v[218:221], v[2:5]
	s_barrier
	s_setprio 0
	s_add_i32 s63, s63, 2
	s_add_u32 s18, s18, 0x100
	s_addc_u32 s19, s19, 0
	s_add_u32 s60, s60, 0x100
	s_addc_u32 s62, s62, 0
	s_cmp_gt_u32 s63, 29
	s_cbranch_scc0 .LBB0_1637
	s_and_b64 vcc, exec, s[6:7]
	s_cbranch_vccz .LBB0_1640
	s_barrier

.LBB0_1913:
	ds_read_b128 v[148:151], v172
	ds_read_b128 v[152:155], v172 offset:1024
	ds_read_b128 v[156:159], v172 offset:2048
	ds_read_b128 v[160:163], v172 offset:3072
	ds_read_b128 v[182:185], v173
	ds_read_b128 v[186:189], v173 offset:1024
	ds_read_b128 v[190:193], v173 offset:2048
	ds_read_b128 v[194:197], v173 offset:3072
	s_add_u32 s54, s52, 0xfff80080
	s_addc_u32 s55, s53, -1
	s_cmp_eq_u32 s82, 28
	s_cselect_b32 s57, s9, s55
	s_cselect_b32 s56, s31, s54
	s_cselect_b32 s55, s29, s79
	s_cselect_b32 s54, s77, s78
	v_lshl_add_u64 v[176:177], s[52:53], 0, v[140:141]
	s_add_i32 m0, s59, 0xc000
	ds_read_b128 v[198:201], v174
	ds_read_b128 v[202:205], v174 offset:1024
	ds_read_b128 v[206:209], v174 offset:2048
	ds_read_b128 v[210:213], v174 offset:3072
	ds_read_b128 v[214:217], v174 offset:4096
	ds_read_b128 v[218:221], v174 offset:5120
	ds_read_b128 v[222:225], v174 offset:6144
	ds_read_b128 v[226:229], v174 offset:7168
	global_load_lds_dwordx4 v[176:177], off
	v_lshl_add_u64 v[176:177], s[52:53], 0, v[142:143]
	s_add_i32 m0, s59, 0xe000
	s_nop 0
	global_load_lds_dwordx4 v[176:177], off
	s_waitcnt vmcnt(8)
	s_waitcnt lgkmcnt(0)
	s_setprio 1
	s_barrier
	v_mfma_f32_16x16x32_bf16 v[126:129], v[148:151], v[198:201], v[126:129]
	v_mfma_f32_16x16x32_bf16 v[126:129], v[152:155], v[202:205], v[126:129]
	v_mfma_f32_16x16x32_bf16 v[122:125], v[156:159], v[198:201], v[122:125]
	v_mfma_f32_16x16x32_bf16 v[122:125], v[160:163], v[202:205], v[122:125]
	v_mfma_f32_16x16x32_bf16 v[110:113], v[148:151], v[206:209], v[110:113]
	v_mfma_f32_16x16x32_bf16 v[110:113], v[152:155], v[210:213], v[110:113]
	v_mfma_f32_16x16x32_bf16 v[106:109], v[156:159], v[206:209], v[106:109]
	v_mfma_f32_16x16x32_bf16 v[106:109], v[160:163], v[210:213], v[106:109]
	v_mfma_f32_16x16x32_bf16 v[94:97], v[148:151], v[214:217], v[94:97]
	v_mfma_f32_16x16x32_bf16 v[94:97], v[152:155], v[218:221], v[94:97]
	v_mfma_f32_16x16x32_bf16 v[90:93], v[156:159], v[214:217], v[90:93]
	v_mfma_f32_16x16x32_bf16 v[90:93], v[160:163], v[218:221], v[90:93]
	v_mfma_f32_16x16x32_bf16 v[78:81], v[148:151], v[222:225], v[78:81]
	v_mfma_f32_16x16x32_bf16 v[78:81], v[152:155], v[226:229], v[78:81]
	v_mfma_f32_16x16x32_bf16 v[74:77], v[156:159], v[222:225], v[74:77]
	v_mfma_f32_16x16x32_bf16 v[74:77], v[160:163], v[226:229], v[74:77]
	v_mfma_f32_16x16x32_bf16 v[118:121], v[182:185], v[198:201], v[118:121]
	v_mfma_f32_16x16x32_bf16 v[118:121], v[186:189], v[202:205], v[118:121]
	v_mfma_f32_16x16x32_bf16 v[114:117], v[190:193], v[198:201], v[114:117]
	v_mfma_f32_16x16x32_bf16 v[114:117], v[194:197], v[202:205], v[114:117]
	v_mfma_f32_16x16x32_bf16 v[102:105], v[182:185], v[206:209], v[102:105]
	v_mfma_f32_16x16x32_bf16 v[102:105], v[186:189], v[210:213], v[102:105]
	v_mfma_f32_16x16x32_bf16 v[98:101], v[190:193], v[206:209], v[98:101]
	v_mfma_f32_16x16x32_bf16 v[98:101], v[194:197], v[210:213], v[98:101]
	v_mfma_f32_16x16x32_bf16 v[86:89], v[182:185], v[214:217], v[86:89]
	v_mfma_f32_16x16x32_bf16 v[86:89], v[186:189], v[218:221], v[86:89]
	v_mfma_f32_16x16x32_bf16 v[82:85], v[190:193], v[214:217], v[82:85]
	v_mfma_f32_16x16x32_bf16 v[82:85], v[194:197], v[218:221], v[82:85]
	v_mfma_f32_16x16x32_bf16 v[70:73], v[182:185], v[222:225], v[70:73]
	v_mfma_f32_16x16x32_bf16 v[70:73], v[186:189], v[226:229], v[70:73]
	v_mfma_f32_16x16x32_bf16 v[66:69], v[190:193], v[222:225], v[66:69]
	v_mfma_f32_16x16x32_bf16 v[66:69], v[194:197], v[226:229], v[66:69]
	s_barrier
	s_setprio 0
	s_add_i32 s83, s72, s58
	v_lshl_add_u64 v[176:177], s[54:55], 0, v[132:133]
	s_mov_b32 m0, s83
	ds_read_b128 v[198:201], v174 offset:16384
	ds_read_b128 v[202:205], v174 offset:17408
	ds_read_b128 v[206:209], v174 offset:18432
	ds_read_b128 v[210:213], v174 offset:19456
	ds_read_b128 v[214:217], v174 offset:20480
	ds_read_b128 v[218:221], v174 offset:21504
	ds_read_b128 v[222:225], v174 offset:22528
	ds_read_b128 v[226:229], v174 offset:23552
	global_load_lds_dwordx4 v[176:177], off
	s_add_i32 m0, s83, 0x2000
	s_add_u32 s88, s54, 0x80000
	v_lshl_add_u64 v[230:231], s[54:55], 0, v[136:137]
	s_addc_u32 s89, s55, 0
	s_add_i32 s83, s73, s58
	global_load_lds_dwordx4 v[230:231], off
	v_lshl_add_u64 v[232:233], s[88:89], 0, v[132:133]
	s_mov_b32 m0, s83
	v_lshl_add_u64 v[234:235], s[56:57], 0, v[134:135]
	global_load_lds_dwordx4 v[232:233], off
	v_lshl_add_u64 v[232:233], s[88:89], 0, v[136:137]
	s_add_i32 m0, s83, 0x2000
	s_nop 0
	global_load_lds_dwordx4 v[232:233], off
	v_lshl_add_u64 v[232:233], s[56:57], 0, v[130:131]
	s_mov_b32 m0, s59
	s_nop 0
	global_load_lds_dwordx4 v[232:233], off
	s_mov_b32 m0, s60
	s_nop 0
	global_load_lds_dwordx4 v[234:235], off
	s_waitcnt vmcnt(8)
	s_waitcnt lgkmcnt(0)
	s_setprio 1
	s_barrier
	v_mfma_f32_16x16x32_bf16 v[62:65], v[148:151], v[198:201], v[62:65]
	v_mfma_f32_16x16x32_bf16 v[62:65], v[152:155], v[202:205], v[62:65]
	v_mfma_f32_16x16x32_bf16 v[58:61], v[156:159], v[198:201], v[58:61]
	v_mfma_f32_16x16x32_bf16 v[58:61], v[160:163], v[202:205], v[58:61]
	v_mfma_f32_16x16x32_bf16 v[46:49], v[148:151], v[206:209], v[46:49]
	v_mfma_f32_16x16x32_bf16 v[46:49], v[152:155], v[210:213], v[46:49]
	v_mfma_f32_16x16x32_bf16 v[42:45], v[156:159], v[206:209], v[42:45]
	v_mfma_f32_16x16x32_bf16 v[42:45], v[160:163], v[210:213], v[42:45]
	v_mfma_f32_16x16x32_bf16 v[30:33], v[148:151], v[214:217], v[30:33]
	v_mfma_f32_16x16x32_bf16 v[30:33], v[152:155], v[218:221], v[30:33]
	v_mfma_f32_16x16x32_bf16 v[26:29], v[156:159], v[214:217], v[26:29]
	v_mfma_f32_16x16x32_bf16 v[26:29], v[160:163], v[218:221], v[26:29]
	v_mfma_f32_16x16x32_bf16 v[14:17], v[148:151], v[222:225], v[14:17]
	v_mfma_f32_16x16x32_bf16 v[14:17], v[152:155], v[226:229], v[14:17]
	v_mfma_f32_16x16x32_bf16 v[10:13], v[156:159], v[222:225], v[10:13]
	v_mfma_f32_16x16x32_bf16 v[10:13], v[160:163], v[226:229], v[10:13]
	v_mfma_f32_16x16x32_bf16 v[54:57], v[182:185], v[198:201], v[54:57]
	v_mfma_f32_16x16x32_bf16 v[54:57], v[186:189], v[202:205], v[54:57]
	v_mfma_f32_16x16x32_bf16 v[50:53], v[190:193], v[198:201], v[50:53]
	v_mfma_f32_16x16x32_bf16 v[50:53], v[194:197], v[202:205], v[50:53]
	v_mfma_f32_16x16x32_bf16 v[38:41], v[182:185], v[206:209], v[38:41]
	v_mfma_f32_16x16x32_bf16 v[38:41], v[186:189], v[210:213], v[38:41]
	v_mfma_f32_16x16x32_bf16 v[34:37], v[190:193], v[206:209], v[34:37]
	v_mfma_f32_16x16x32_bf16 v[34:37], v[194:197], v[210:213], v[34:37]
	v_mfma_f32_16x16x32_bf16 v[22:25], v[182:185], v[214:217], v[22:25]
	v_mfma_f32_16x16x32_bf16 v[22:25], v[186:189], v[218:221], v[22:25]
	v_mfma_f32_16x16x32_bf16 v[18:21], v[190:193], v[214:217], v[18:21]
	v_mfma_f32_16x16x32_bf16 v[18:21], v[194:197], v[218:221], v[18:21]
	v_mfma_f32_16x16x32_bf16 v[6:9], v[182:185], v[222:225], v[6:9]
	v_mfma_f32_16x16x32_bf16 v[6:9], v[186:189], v[226:229], v[6:9]
	v_mfma_f32_16x16x32_bf16 v[2:5], v[190:193], v[222:225], v[2:5]
	v_mfma_f32_16x16x32_bf16 v[2:5], v[194:197], v[226:229], v[2:5]
	s_barrier
	s_setprio 0
	s_add_i32 s83, 0, 0x18000
	s_add_i32 s88, 0, 0x1c000
	v_add_u32_e32 v160, s83, v166
	v_add_u32_e32 v179, s88, v166
	ds_read_b128 v[148:151], v160
	ds_read_b128 v[152:155], v160 offset:1024
	ds_read_b128 v[156:159], v160 offset:2048
	ds_read_b128 v[160:163], v160 offset:3072
	ds_read_b128 v[182:185], v179
	ds_read_b128 v[186:189], v179 offset:1024
	ds_read_b128 v[190:193], v179 offset:2048
	ds_read_b128 v[194:197], v179 offset:3072
	s_add_u32 s56, s56, 0x80000
	s_addc_u32 s57, s57, 0
	s_mov_b32 m0, s62
	v_lshl_add_u64 v[236:237], s[56:57], 0, v[130:131]
	ds_read_b128 v[198:201], v174 offset:32768
	ds_read_b128 v[202:205], v174 offset:33792
	ds_read_b128 v[206:209], v174 offset:34816
	ds_read_b128 v[210:213], v174 offset:35840
	ds_read_b128 v[214:217], v174 offset:36864
	ds_read_b128 v[218:221], v174 offset:37888
	ds_read_b128 v[222:225], v174 offset:38912
	ds_read_b128 v[226:229], v174 offset:39936
	global_load_lds_dwordx4 v[236:237], off
	v_lshl_add_u64 v[236:237], s[56:57], 0, v[134:135]
	s_mov_b32 m0, s63
	s_nop 0
	global_load_lds_dwordx4 v[236:237], off
	s_waitcnt vmcnt(8)
	s_waitcnt lgkmcnt(0)
	s_setprio 1
	s_barrier
	v_mfma_f32_16x16x32_bf16 v[126:129], v[148:151], v[198:201], v[126:129]
	v_mfma_f32_16x16x32_bf16 v[126:129], v[152:155], v[202:205], v[126:129]
	v_mfma_f32_16x16x32_bf16 v[122:125], v[156:159], v[198:201], v[122:125]
	v_mfma_f32_16x16x32_bf16 v[122:125], v[160:163], v[202:205], v[122:125]
	v_mfma_f32_16x16x32_bf16 v[110:113], v[148:151], v[206:209], v[110:113]
	v_mfma_f32_16x16x32_bf16 v[110:113], v[152:155], v[210:213], v[110:113]
	v_mfma_f32_16x16x32_bf16 v[106:109], v[156:159], v[206:209], v[106:109]
	v_mfma_f32_16x16x32_bf16 v[106:109], v[160:163], v[210:213], v[106:109]
	v_mfma_f32_16x16x32_bf16 v[94:97], v[148:151], v[214:217], v[94:97]
	v_mfma_f32_16x16x32_bf16 v[94:97], v[152:155], v[218:221], v[94:97]
	v_mfma_f32_16x16x32_bf16 v[90:93], v[156:159], v[214:217], v[90:93]
	v_mfma_f32_16x16x32_bf16 v[90:93], v[160:163], v[218:221], v[90:93]
	v_mfma_f32_16x16x32_bf16 v[78:81], v[148:151], v[222:225], v[78:81]
	v_mfma_f32_16x16x32_bf16 v[78:81], v[152:155], v[226:229], v[78:81]
	v_mfma_f32_16x16x32_bf16 v[74:77], v[156:159], v[222:225], v[74:77]
	v_mfma_f32_16x16x32_bf16 v[74:77], v[160:163], v[226:229], v[74:77]
	v_mfma_f32_16x16x32_bf16 v[118:121], v[182:185], v[198:201], v[118:121]
	v_mfma_f32_16x16x32_bf16 v[118:121], v[186:189], v[202:205], v[118:121]
	v_mfma_f32_16x16x32_bf16 v[114:117], v[190:193], v[198:201], v[114:117]
	v_mfma_f32_16x16x32_bf16 v[114:117], v[194:197], v[202:205], v[114:117]
	v_mfma_f32_16x16x32_bf16 v[102:105], v[182:185], v[206:209], v[102:105]
	v_mfma_f32_16x16x32_bf16 v[102:105], v[186:189], v[210:213], v[102:105]
	v_mfma_f32_16x16x32_bf16 v[98:101], v[190:193], v[206:209], v[98:101]
	v_mfma_f32_16x16x32_bf16 v[98:101], v[194:197], v[210:213], v[98:101]
	v_mfma_f32_16x16x32_bf16 v[86:89], v[182:185], v[214:217], v[86:89]
	v_mfma_f32_16x16x32_bf16 v[86:89], v[186:189], v[218:221], v[86:89]
	v_mfma_f32_16x16x32_bf16 v[82:85], v[190:193], v[214:217], v[82:85]
	v_mfma_f32_16x16x32_bf16 v[82:85], v[194:197], v[218:221], v[82:85]
	v_mfma_f32_16x16x32_bf16 v[70:73], v[182:185], v[222:225], v[70:73]
	v_mfma_f32_16x16x32_bf16 v[70:73], v[186:189], v[226:229], v[70:73]
	v_mfma_f32_16x16x32_bf16 v[66:69], v[190:193], v[222:225], v[66:69]
	v_mfma_f32_16x16x32_bf16 v[66:69], v[194:197], v[226:229], v[66:69]
	s_barrier
	s_setprio 0
	s_add_i32 s56, s83, s58
	v_lshl_add_u64 v[176:177], v[176:177], 0, s[20:21]
	s_mov_b32 m0, s56
	ds_read_b128 v[198:201], v174 offset:49152
	ds_read_b128 v[202:205], v174 offset:50176
	ds_read_b128 v[206:209], v174 offset:51200
	ds_read_b128 v[210:213], v174 offset:52224
	ds_read_b128 v[214:217], v174 offset:53248
	ds_read_b128 v[218:221], v174 offset:54272
	ds_read_b128 v[222:225], v174 offset:55296
	ds_read_b128 v[226:229], v174 offset:56320
	global_load_lds_dwordx4 v[176:177], off
	s_add_i32 m0, s56, 0x2000
	s_add_u32 s54, s54, 0x80080
	v_lshl_add_u64 v[176:177], v[230:231], 0, s[20:21]
	s_addc_u32 s55, s55, 0
	s_add_i32 s56, s88, s58
	global_load_lds_dwordx4 v[176:177], off
	v_lshl_add_u64 v[176:177], s[54:55], 0, v[132:133]
	s_mov_b32 m0, s56
	s_nop 0
	global_load_lds_dwordx4 v[176:177], off
	v_lshl_add_u64 v[176:177], s[54:55], 0, v[136:137]
	s_add_i32 m0, s56, 0x2000
	s_nop 0
	global_load_lds_dwordx4 v[176:177], off
	v_lshl_add_u64 v[176:177], v[232:233], 0, s[20:21]
	s_mov_b32 m0, s67
	s_nop 0
	global_load_lds_dwordx4 v[176:177], off
	v_lshl_add_u64 v[176:177], v[234:235], 0, s[20:21]
	s_mov_b32 m0, s68
	s_nop 0
	global_load_lds_dwordx4 v[176:177], off
	s_waitcnt vmcnt(8)
	s_waitcnt lgkmcnt(0)
	s_setprio 1
	s_barrier
	v_mfma_f32_16x16x32_bf16 v[62:65], v[148:151], v[198:201], v[62:65]
	v_mfma_f32_16x16x32_bf16 v[62:65], v[152:155], v[202:205], v[62:65]
	v_mfma_f32_16x16x32_bf16 v[58:61], v[156:159], v[198:201], v[58:61]
	v_mfma_f32_16x16x32_bf16 v[58:61], v[160:163], v[202:205], v[58:61]
	v_mfma_f32_16x16x32_bf16 v[46:49], v[148:151], v[206:209], v[46:49]
	v_mfma_f32_16x16x32_bf16 v[46:49], v[152:155], v[210:213], v[46:49]
	v_mfma_f32_16x16x32_bf16 v[42:45], v[156:159], v[206:209], v[42:45]
	v_mfma_f32_16x16x32_bf16 v[42:45], v[160:163], v[210:213], v[42:45]
	v_mfma_f32_16x16x32_bf16 v[30:33], v[148:151], v[214:217], v[30:33]
	v_mfma_f32_16x16x32_bf16 v[30:33], v[152:155], v[218:221], v[30:33]
	v_mfma_f32_16x16x32_bf16 v[26:29], v[156:159], v[214:217], v[26:29]
	v_mfma_f32_16x16x32_bf16 v[26:29], v[160:163], v[218:221], v[26:29]
	v_mfma_f32_16x16x32_bf16 v[14:17], v[148:151], v[222:225], v[14:17]
	v_mfma_f32_16x16x32_bf16 v[14:17], v[152:155], v[226:229], v[14:17]
	v_mfma_f32_16x16x32_bf16 v[10:13], v[156:159], v[222:225], v[10:13]
	v_mfma_f32_16x16x32_bf16 v[10:13], v[160:163], v[226:229], v[10:13]
	v_mfma_f32_16x16x32_bf16 v[54:57], v[182:185], v[198:201], v[54:57]
	v_mfma_f32_16x16x32_bf16 v[54:57], v[186:189], v[202:205], v[54:57]
	v_mfma_f32_16x16x32_bf16 v[50:53], v[190:193], v[198:201], v[50:53]
	v_mfma_f32_16x16x32_bf16 v[50:53], v[194:197], v[202:205], v[50:53]
	v_mfma_f32_16x16x32_bf16 v[38:41], v[182:185], v[206:209], v[38:41]
	v_mfma_f32_16x16x32_bf16 v[38:41], v[186:189], v[210:213], v[38:41]
	v_mfma_f32_16x16x32_bf16 v[34:37], v[190:193], v[206:209], v[34:37]
	v_mfma_f32_16x16x32_bf16 v[34:37], v[194:197], v[210:213], v[34:37]
	v_mfma_f32_16x16x32_bf16 v[22:25], v[182:185], v[214:217], v[22:25]
	v_mfma_f32_16x16x32_bf16 v[22:25], v[186:189], v[218:221], v[22:25]
	v_mfma_f32_16x16x32_bf16 v[18:21], v[190:193], v[214:217], v[18:21]
	v_mfma_f32_16x16x32_bf16 v[18:21], v[194:197], v[218:221], v[18:21]
	v_mfma_f32_16x16x32_bf16 v[6:9], v[182:185], v[222:225], v[6:9]
	v_mfma_f32_16x16x32_bf16 v[6:9], v[186:189], v[226:229], v[6:9]
	v_mfma_f32_16x16x32_bf16 v[2:5], v[190:193], v[222:225], v[2:5]
	v_mfma_f32_16x16x32_bf16 v[2:5], v[194:197], v[226:229], v[2:5]
	s_barrier
	s_setprio 0
	s_add_i32 s82, s82, 2
	s_add_u32 s52, s52, 0x100
	s_addc_u32 s53, s53, 0
	s_add_u32 s78, s78, 0x100
	s_addc_u32 s79, s79, 0
	s_cmp_gt_u32 s82, 29
	s_cbranch_scc0 .LBB0_1913
	s_and_b64 vcc, exec, s[22:23]
	s_cbranch_vccz .LBB0_1916
	s_barrier

.LBB0_2098:
	ds_read_b128 v[146:149], v168
	ds_read_b128 v[150:153], v168 offset:1024
	ds_read_b128 v[172:175], v168 offset:2048
	ds_read_b128 v[182:185], v168 offset:3072
	ds_read_b128 v[186:189], v169
	ds_read_b128 v[190:193], v169 offset:1024
	ds_read_b128 v[194:197], v169 offset:2048
	ds_read_b128 v[198:201], v169 offset:3072
	s_add_u32 s28, s26, 0xfffc0080
	s_addc_u32 s29, s27, -1
	s_cmp_eq_u32 s72, 4
	s_cselect_b32 s31, s3, s29
	s_cselect_b32 s30, s5, s28
	s_cselect_b32 s29, s17, s71
	s_cselect_b32 s28, s19, s70
	v_lshl_add_u64 v[176:177], s[26:27], 0, v[138:139]
	s_add_i32 m0, s53, 0xc000
	ds_read_b128 v[202:205], v170
	ds_read_b128 v[206:209], v170 offset:1024
	ds_read_b128 v[210:213], v170 offset:2048
	ds_read_b128 v[214:217], v170 offset:3072
	ds_read_b128 v[218:221], v170 offset:4096
	ds_read_b128 v[222:225], v170 offset:5120
	ds_read_b128 v[226:229], v170 offset:6144
	ds_read_b128 v[230:233], v170 offset:7168
	global_load_lds_dwordx4 v[176:177], off
	v_lshl_add_u64 v[176:177], s[26:27], 0, v[140:141]
	s_add_i32 m0, s53, 0xe000
	s_nop 0
	global_load_lds_dwordx4 v[176:177], off
	s_waitcnt vmcnt(8)
	s_waitcnt lgkmcnt(0)
	s_setprio 1
	s_barrier
	v_mfma_f32_16x16x32_bf16 v[126:129], v[146:149], v[202:205], v[126:129]
	v_mfma_f32_16x16x32_bf16 v[126:129], v[150:153], v[206:209], v[126:129]
	v_mfma_f32_16x16x32_bf16 v[122:125], v[172:175], v[202:205], v[122:125]
	v_mfma_f32_16x16x32_bf16 v[122:125], v[182:185], v[206:209], v[122:125]
	v_mfma_f32_16x16x32_bf16 v[110:113], v[146:149], v[210:213], v[110:113]
	v_mfma_f32_16x16x32_bf16 v[110:113], v[150:153], v[214:217], v[110:113]
	v_mfma_f32_16x16x32_bf16 v[106:109], v[172:175], v[210:213], v[106:109]
	v_mfma_f32_16x16x32_bf16 v[106:109], v[182:185], v[214:217], v[106:109]
	v_mfma_f32_16x16x32_bf16 v[94:97], v[146:149], v[218:221], v[94:97]
	v_mfma_f32_16x16x32_bf16 v[94:97], v[150:153], v[222:225], v[94:97]
	v_mfma_f32_16x16x32_bf16 v[90:93], v[172:175], v[218:221], v[90:93]
	v_mfma_f32_16x16x32_bf16 v[90:93], v[182:185], v[222:225], v[90:93]
	v_mfma_f32_16x16x32_bf16 v[78:81], v[146:149], v[226:229], v[78:81]
	v_mfma_f32_16x16x32_bf16 v[78:81], v[150:153], v[230:233], v[78:81]
	v_mfma_f32_16x16x32_bf16 v[74:77], v[172:175], v[226:229], v[74:77]
	v_mfma_f32_16x16x32_bf16 v[74:77], v[182:185], v[230:233], v[74:77]
	v_mfma_f32_16x16x32_bf16 v[118:121], v[186:189], v[202:205], v[118:121]
	v_mfma_f32_16x16x32_bf16 v[118:121], v[190:193], v[206:209], v[118:121]
	v_mfma_f32_16x16x32_bf16 v[114:117], v[194:197], v[202:205], v[114:117]
	v_mfma_f32_16x16x32_bf16 v[114:117], v[198:201], v[206:209], v[114:117]
	v_mfma_f32_16x16x32_bf16 v[102:105], v[186:189], v[210:213], v[102:105]
	v_mfma_f32_16x16x32_bf16 v[102:105], v[190:193], v[214:217], v[102:105]
	v_mfma_f32_16x16x32_bf16 v[98:101], v[194:197], v[210:213], v[98:101]
	v_mfma_f32_16x16x32_bf16 v[98:101], v[198:201], v[214:217], v[98:101]
	v_mfma_f32_16x16x32_bf16 v[86:89], v[186:189], v[218:221], v[86:89]
	v_mfma_f32_16x16x32_bf16 v[86:89], v[190:193], v[222:225], v[86:89]
	v_mfma_f32_16x16x32_bf16 v[82:85], v[194:197], v[218:221], v[82:85]
	v_mfma_f32_16x16x32_bf16 v[82:85], v[198:201], v[222:225], v[82:85]
	v_mfma_f32_16x16x32_bf16 v[70:73], v[186:189], v[226:229], v[70:73]
	v_mfma_f32_16x16x32_bf16 v[70:73], v[190:193], v[230:233], v[70:73]
	v_mfma_f32_16x16x32_bf16 v[66:69], v[194:197], v[226:229], v[66:69]
	v_mfma_f32_16x16x32_bf16 v[66:69], v[198:201], v[230:233], v[66:69]
	s_barrier
	s_setprio 0
	s_add_i32 s73, s67, s52
	v_lshl_add_u64 v[176:177], s[28:29], 0, v[132:133]
	s_mov_b32 m0, s73
	ds_read_b128 v[202:205], v170 offset:16384
	ds_read_b128 v[206:209], v170 offset:17408
	ds_read_b128 v[210:213], v170 offset:18432
	ds_read_b128 v[214:217], v170 offset:19456
	ds_read_b128 v[218:221], v170 offset:20480
	ds_read_b128 v[222:225], v170 offset:21504
	ds_read_b128 v[226:229], v170 offset:22528
	ds_read_b128 v[230:233], v170 offset:23552
	global_load_lds_dwordx4 v[176:177], off
	s_add_i32 m0, s73, 0x2000
	s_add_u32 s76, s28, 0x20000
	v_lshl_add_u64 v[234:235], s[28:29], 0, v[136:137]
	s_addc_u32 s77, s29, 0
	s_add_i32 s73, s68, s52
	global_load_lds_dwordx4 v[234:235], off
	v_lshl_add_u64 v[236:237], s[76:77], 0, v[132:133]
	s_mov_b32 m0, s73
	v_lshl_add_u64 v[238:239], s[30:31], 0, v[134:135]
	global_load_lds_dwordx4 v[236:237], off
	v_lshl_add_u64 v[236:237], s[76:77], 0, v[136:137]
	s_add_i32 m0, s73, 0x2000
	s_nop 0
	global_load_lds_dwordx4 v[236:237], off
	v_lshl_add_u64 v[236:237], s[30:31], 0, v[130:131]
	s_mov_b32 m0, s53
	s_nop 0
	global_load_lds_dwordx4 v[236:237], off
	s_mov_b32 m0, s54
	s_nop 0
	global_load_lds_dwordx4 v[238:239], off
	s_waitcnt vmcnt(8)
	s_waitcnt lgkmcnt(0)
	s_setprio 1
	s_barrier
	v_mfma_f32_16x16x32_bf16 v[62:65], v[146:149], v[202:205], v[62:65]
	v_mfma_f32_16x16x32_bf16 v[62:65], v[150:153], v[206:209], v[62:65]
	v_mfma_f32_16x16x32_bf16 v[58:61], v[172:175], v[202:205], v[58:61]
	v_mfma_f32_16x16x32_bf16 v[58:61], v[182:185], v[206:209], v[58:61]
	v_mfma_f32_16x16x32_bf16 v[46:49], v[146:149], v[210:213], v[46:49]
	v_mfma_f32_16x16x32_bf16 v[46:49], v[150:153], v[214:217], v[46:49]
	v_mfma_f32_16x16x32_bf16 v[42:45], v[172:175], v[210:213], v[42:45]
	v_mfma_f32_16x16x32_bf16 v[42:45], v[182:185], v[214:217], v[42:45]
	v_mfma_f32_16x16x32_bf16 v[30:33], v[146:149], v[218:221], v[30:33]
	v_mfma_f32_16x16x32_bf16 v[30:33], v[150:153], v[222:225], v[30:33]
	v_mfma_f32_16x16x32_bf16 v[26:29], v[172:175], v[218:221], v[26:29]
	v_mfma_f32_16x16x32_bf16 v[26:29], v[182:185], v[222:225], v[26:29]
	v_mfma_f32_16x16x32_bf16 v[14:17], v[146:149], v[226:229], v[14:17]
	v_mfma_f32_16x16x32_bf16 v[14:17], v[150:153], v[230:233], v[14:17]
	v_mfma_f32_16x16x32_bf16 v[10:13], v[172:175], v[226:229], v[10:13]
	v_mfma_f32_16x16x32_bf16 v[10:13], v[182:185], v[230:233], v[10:13]
	v_mfma_f32_16x16x32_bf16 v[54:57], v[186:189], v[202:205], v[54:57]
	v_mfma_f32_16x16x32_bf16 v[54:57], v[190:193], v[206:209], v[54:57]
	v_mfma_f32_16x16x32_bf16 v[50:53], v[194:197], v[202:205], v[50:53]
	v_mfma_f32_16x16x32_bf16 v[50:53], v[198:201], v[206:209], v[50:53]
	v_mfma_f32_16x16x32_bf16 v[38:41], v[186:189], v[210:213], v[38:41]
	v_mfma_f32_16x16x32_bf16 v[38:41], v[190:193], v[214:217], v[38:41]
	v_mfma_f32_16x16x32_bf16 v[34:37], v[194:197], v[210:213], v[34:37]
	v_mfma_f32_16x16x32_bf16 v[34:37], v[198:201], v[214:217], v[34:37]
	v_mfma_f32_16x16x32_bf16 v[22:25], v[186:189], v[218:221], v[22:25]
	v_mfma_f32_16x16x32_bf16 v[22:25], v[190:193], v[222:225], v[22:25]
	v_mfma_f32_16x16x32_bf16 v[18:21], v[194:197], v[218:221], v[18:21]
	v_mfma_f32_16x16x32_bf16 v[18:21], v[198:201], v[222:225], v[18:21]
	v_mfma_f32_16x16x32_bf16 v[6:9], v[186:189], v[226:229], v[6:9]
	v_mfma_f32_16x16x32_bf16 v[6:9], v[190:193], v[230:233], v[6:9]
	v_mfma_f32_16x16x32_bf16 v[2:5], v[194:197], v[226:229], v[2:5]
	v_mfma_f32_16x16x32_bf16 v[2:5], v[198:201], v[230:233], v[2:5]
	s_barrier
	s_setprio 0
	s_add_i32 s73, 0, 0x18000
	v_add_u32_e32 v179, s73, v162
	s_add_i32 s76, 0, 0x1c000
	ds_read_b128 v[146:149], v179
	ds_read_b128 v[150:153], v179 offset:1024
	ds_read_b128 v[172:175], v179 offset:2048
	ds_read_b128 v[182:185], v179 offset:3072
	v_add_u32_e32 v179, s76, v162
	ds_read_b128 v[186:189], v179
	ds_read_b128 v[190:193], v179 offset:1024
	ds_read_b128 v[194:197], v179 offset:2048
	ds_read_b128 v[198:201], v179 offset:3072
	s_add_u32 s30, s30, 0x40000
	s_addc_u32 s31, s31, 0
	s_mov_b32 m0, s55
	v_lshl_add_u64 v[240:241], s[30:31], 0, v[130:131]
	ds_read_b128 v[202:205], v170 offset:32768
	ds_read_b128 v[206:209], v170 offset:33792
	ds_read_b128 v[210:213], v170 offset:34816
	ds_read_b128 v[214:217], v170 offset:35840
	ds_read_b128 v[218:221], v170 offset:36864
	ds_read_b128 v[222:225], v170 offset:37888
	ds_read_b128 v[226:229], v170 offset:38912
	ds_read_b128 v[230:233], v170 offset:39936
	global_load_lds_dwordx4 v[240:241], off
	v_lshl_add_u64 v[240:241], s[30:31], 0, v[134:135]
	s_mov_b32 m0, s56
	s_nop 0
	global_load_lds_dwordx4 v[240:241], off
	s_waitcnt vmcnt(8)
	s_waitcnt lgkmcnt(0)
	s_setprio 1
	s_barrier
	v_mfma_f32_16x16x32_bf16 v[126:129], v[146:149], v[202:205], v[126:129]
	v_mfma_f32_16x16x32_bf16 v[126:129], v[150:153], v[206:209], v[126:129]
	v_mfma_f32_16x16x32_bf16 v[122:125], v[172:175], v[202:205], v[122:125]
	v_mfma_f32_16x16x32_bf16 v[122:125], v[182:185], v[206:209], v[122:125]
	v_mfma_f32_16x16x32_bf16 v[110:113], v[146:149], v[210:213], v[110:113]
	v_mfma_f32_16x16x32_bf16 v[110:113], v[150:153], v[214:217], v[110:113]
	v_mfma_f32_16x16x32_bf16 v[106:109], v[172:175], v[210:213], v[106:109]
	v_mfma_f32_16x16x32_bf16 v[106:109], v[182:185], v[214:217], v[106:109]
	v_mfma_f32_16x16x32_bf16 v[94:97], v[146:149], v[218:221], v[94:97]
	v_mfma_f32_16x16x32_bf16 v[94:97], v[150:153], v[222:225], v[94:97]
	v_mfma_f32_16x16x32_bf16 v[90:93], v[172:175], v[218:221], v[90:93]
	v_mfma_f32_16x16x32_bf16 v[90:93], v[182:185], v[222:225], v[90:93]
	v_mfma_f32_16x16x32_bf16 v[78:81], v[146:149], v[226:229], v[78:81]
	v_mfma_f32_16x16x32_bf16 v[78:81], v[150:153], v[230:233], v[78:81]
	v_mfma_f32_16x16x32_bf16 v[74:77], v[172:175], v[226:229], v[74:77]
	v_mfma_f32_16x16x32_bf16 v[74:77], v[182:185], v[230:233], v[74:77]
	v_mfma_f32_16x16x32_bf16 v[118:121], v[186:189], v[202:205], v[118:121]
	v_mfma_f32_16x16x32_bf16 v[118:121], v[190:193], v[206:209], v[118:121]
	v_mfma_f32_16x16x32_bf16 v[114:117], v[194:197], v[202:205], v[114:117]
	v_mfma_f32_16x16x32_bf16 v[114:117], v[198:201], v[206:209], v[114:117]
	v_mfma_f32_16x16x32_bf16 v[102:105], v[186:189], v[210:213], v[102:105]
	v_mfma_f32_16x16x32_bf16 v[102:105], v[190:193], v[214:217], v[102:105]
	v_mfma_f32_16x16x32_bf16 v[98:101], v[194:197], v[210:213], v[98:101]
	v_mfma_f32_16x16x32_bf16 v[98:101], v[198:201], v[214:217], v[98:101]
	v_mfma_f32_16x16x32_bf16 v[86:89], v[186:189], v[218:221], v[86:89]
	v_mfma_f32_16x16x32_bf16 v[86:89], v[190:193], v[222:225], v[86:89]
	v_mfma_f32_16x16x32_bf16 v[82:85], v[194:197], v[218:221], v[82:85]
	v_mfma_f32_16x16x32_bf16 v[82:85], v[198:201], v[222:225], v[82:85]
	v_mfma_f32_16x16x32_bf16 v[70:73], v[186:189], v[226:229], v[70:73]
	v_mfma_f32_16x16x32_bf16 v[70:73], v[190:193], v[230:233], v[70:73]
	v_mfma_f32_16x16x32_bf16 v[66:69], v[194:197], v[226:229], v[66:69]
	v_mfma_f32_16x16x32_bf16 v[66:69], v[198:201], v[230:233], v[66:69]
	s_barrier
	s_setprio 0
	s_add_i32 s30, s73, s52
	v_lshl_add_u64 v[176:177], v[176:177], 0, s[12:13]
	s_mov_b32 m0, s30
	ds_read_b128 v[202:205], v170 offset:49152
	ds_read_b128 v[206:209], v170 offset:50176
	ds_read_b128 v[210:213], v170 offset:51200
	ds_read_b128 v[214:217], v170 offset:52224
	ds_read_b128 v[218:221], v170 offset:53248
	ds_read_b128 v[222:225], v170 offset:54272
	ds_read_b128 v[226:229], v170 offset:55296
	ds_read_b128 v[230:233], v170 offset:56320
	global_load_lds_dwordx4 v[176:177], off
	s_add_i32 m0, s30, 0x2000
	s_add_u32 s28, s28, 0x20080
	v_lshl_add_u64 v[176:177], v[234:235], 0, s[12:13]
	s_addc_u32 s29, s29, 0
	s_add_i32 s30, s76, s52
	global_load_lds_dwordx4 v[176:177], off
	v_lshl_add_u64 v[176:177], s[28:29], 0, v[132:133]
	s_mov_b32 m0, s30
	s_nop 0
	global_load_lds_dwordx4 v[176:177], off
	v_lshl_add_u64 v[176:177], s[28:29], 0, v[136:137]
	s_add_i32 m0, s30, 0x2000
	s_nop 0
	global_load_lds_dwordx4 v[176:177], off
	v_lshl_add_u64 v[176:177], v[236:237], 0, s[12:13]
	s_mov_b32 m0, s59
	s_nop 0
	global_load_lds_dwordx4 v[176:177], off
	v_lshl_add_u64 v[176:177], v[238:239], 0, s[12:13]
	s_mov_b32 m0, s60
	s_nop 0
	global_load_lds_dwordx4 v[176:177], off
	s_waitcnt vmcnt(8)
	s_waitcnt lgkmcnt(0)
	s_setprio 1
	s_barrier
	v_mfma_f32_16x16x32_bf16 v[62:65], v[146:149], v[202:205], v[62:65]
	v_mfma_f32_16x16x32_bf16 v[62:65], v[150:153], v[206:209], v[62:65]
	v_mfma_f32_16x16x32_bf16 v[58:61], v[172:175], v[202:205], v[58:61]
	v_mfma_f32_16x16x32_bf16 v[58:61], v[182:185], v[206:209], v[58:61]
	v_mfma_f32_16x16x32_bf16 v[46:49], v[146:149], v[210:213], v[46:49]
	v_mfma_f32_16x16x32_bf16 v[46:49], v[150:153], v[214:217], v[46:49]
	v_mfma_f32_16x16x32_bf16 v[42:45], v[172:175], v[210:213], v[42:45]
	v_mfma_f32_16x16x32_bf16 v[42:45], v[182:185], v[214:217], v[42:45]
	v_mfma_f32_16x16x32_bf16 v[30:33], v[146:149], v[218:221], v[30:33]
	v_mfma_f32_16x16x32_bf16 v[30:33], v[150:153], v[222:225], v[30:33]
	v_mfma_f32_16x16x32_bf16 v[26:29], v[172:175], v[218:221], v[26:29]
	v_mfma_f32_16x16x32_bf16 v[26:29], v[182:185], v[222:225], v[26:29]
	v_mfma_f32_16x16x32_bf16 v[14:17], v[146:149], v[226:229], v[14:17]
	v_mfma_f32_16x16x32_bf16 v[14:17], v[150:153], v[230:233], v[14:17]
	v_mfma_f32_16x16x32_bf16 v[10:13], v[172:175], v[226:229], v[10:13]
	v_mfma_f32_16x16x32_bf16 v[10:13], v[182:185], v[230:233], v[10:13]
	v_mfma_f32_16x16x32_bf16 v[54:57], v[186:189], v[202:205], v[54:57]
	v_mfma_f32_16x16x32_bf16 v[54:57], v[190:193], v[206:209], v[54:57]
	v_mfma_f32_16x16x32_bf16 v[50:53], v[194:197], v[202:205], v[50:53]
	v_mfma_f32_16x16x32_bf16 v[50:53], v[198:201], v[206:209], v[50:53]
	v_mfma_f32_16x16x32_bf16 v[38:41], v[186:189], v[210:213], v[38:41]
	v_mfma_f32_16x16x32_bf16 v[38:41], v[190:193], v[214:217], v[38:41]
	v_mfma_f32_16x16x32_bf16 v[34:37], v[194:197], v[210:213], v[34:37]
	v_mfma_f32_16x16x32_bf16 v[34:37], v[198:201], v[214:217], v[34:37]
	v_mfma_f32_16x16x32_bf16 v[22:25], v[186:189], v[218:221], v[22:25]
	v_mfma_f32_16x16x32_bf16 v[22:25], v[190:193], v[222:225], v[22:25]
	v_mfma_f32_16x16x32_bf16 v[18:21], v[194:197], v[218:221], v[18:21]
	v_mfma_f32_16x16x32_bf16 v[18:21], v[198:201], v[222:225], v[18:21]
	v_mfma_f32_16x16x32_bf16 v[6:9], v[186:189], v[226:229], v[6:9]
	v_mfma_f32_16x16x32_bf16 v[6:9], v[190:193], v[230:233], v[6:9]
	v_mfma_f32_16x16x32_bf16 v[2:5], v[194:197], v[226:229], v[2:5]
	v_mfma_f32_16x16x32_bf16 v[2:5], v[198:201], v[230:233], v[2:5]
	s_barrier
	s_setprio 0
	s_add_i32 s72, s72, 2
	s_add_u32 s26, s26, 0x100
	s_addc_u32 s27, s27, 0
	s_add_u32 s70, s70, 0x100
	s_addc_u32 s71, s71, 0
	s_cmp_gt_u32 s72, 5
	s_cbranch_scc0 .LBB0_2098
	s_and_b64 vcc, exec, s[14:15]
	s_cbranch_vccz .LBB0_2101
	s_barrier

.LBB0_2146:
	ds_read_b128 v[146:149], v1
	ds_read_b128 v[156:159], v1 offset:1024
	ds_read_b128 v[160:163], v1 offset:2048
	ds_read_b128 v[164:167], v1 offset:3072
	ds_read_b128 v[168:171], v153
	ds_read_b128 v[172:175], v153 offset:1024
	ds_read_b128 v[182:185], v153 offset:2048
	ds_read_b128 v[186:189], v153 offset:3072
	s_add_u32 s26, s22, 0xfffc0080
	s_addc_u32 s27, s23, -1
	s_cmp_eq_u32 s71, 4
	s_cselect_b32 s29, s15, s27
	s_cselect_b32 s28, s67, s26
	s_cselect_b32 s27, s13, s70
	s_cselect_b32 s26, s68, s69
	v_lshl_add_u64 v[176:177], s[22:23], 0, v[138:139]
	s_add_i32 m0, s21, 0xc000
	ds_read_b128 v[190:193], v154
	ds_read_b128 v[194:197], v154 offset:1024
	ds_read_b128 v[198:201], v154 offset:2048
	ds_read_b128 v[202:205], v154 offset:3072
	ds_read_b128 v[206:209], v154 offset:4096
	ds_read_b128 v[210:213], v154 offset:5120
	ds_read_b128 v[214:217], v154 offset:6144
	ds_read_b128 v[218:221], v154 offset:7168
	global_load_lds_dwordx4 v[176:177], off
	v_lshl_add_u64 v[176:177], s[22:23], 0, v[140:141]
	s_add_i32 m0, s21, 0xe000
	s_nop 0
	global_load_lds_dwordx4 v[176:177], off
	s_waitcnt vmcnt(8)
	s_waitcnt lgkmcnt(0)
	s_setprio 1
	s_barrier
	v_mfma_f32_16x16x32_bf16 v[126:129], v[146:149], v[190:193], v[126:129]
	v_mfma_f32_16x16x32_bf16 v[126:129], v[156:159], v[194:197], v[126:129]
	v_mfma_f32_16x16x32_bf16 v[122:125], v[160:163], v[190:193], v[122:125]
	v_mfma_f32_16x16x32_bf16 v[122:125], v[164:167], v[194:197], v[122:125]
	v_mfma_f32_16x16x32_bf16 v[110:113], v[146:149], v[198:201], v[110:113]
	v_mfma_f32_16x16x32_bf16 v[110:113], v[156:159], v[202:205], v[110:113]
	v_mfma_f32_16x16x32_bf16 v[106:109], v[160:163], v[198:201], v[106:109]
	v_mfma_f32_16x16x32_bf16 v[106:109], v[164:167], v[202:205], v[106:109]
	v_mfma_f32_16x16x32_bf16 v[94:97], v[146:149], v[206:209], v[94:97]
	v_mfma_f32_16x16x32_bf16 v[94:97], v[156:159], v[210:213], v[94:97]
	v_mfma_f32_16x16x32_bf16 v[90:93], v[160:163], v[206:209], v[90:93]
	v_mfma_f32_16x16x32_bf16 v[90:93], v[164:167], v[210:213], v[90:93]
	v_mfma_f32_16x16x32_bf16 v[78:81], v[146:149], v[214:217], v[78:81]
	v_mfma_f32_16x16x32_bf16 v[78:81], v[156:159], v[218:221], v[78:81]
	v_mfma_f32_16x16x32_bf16 v[74:77], v[160:163], v[214:217], v[74:77]
	v_mfma_f32_16x16x32_bf16 v[74:77], v[164:167], v[218:221], v[74:77]
	v_mfma_f32_16x16x32_bf16 v[118:121], v[168:171], v[190:193], v[118:121]
	v_mfma_f32_16x16x32_bf16 v[118:121], v[172:175], v[194:197], v[118:121]
	v_mfma_f32_16x16x32_bf16 v[114:117], v[182:185], v[190:193], v[114:117]
	v_mfma_f32_16x16x32_bf16 v[114:117], v[186:189], v[194:197], v[114:117]
	v_mfma_f32_16x16x32_bf16 v[102:105], v[168:171], v[198:201], v[102:105]
	v_mfma_f32_16x16x32_bf16 v[102:105], v[172:175], v[202:205], v[102:105]
	v_mfma_f32_16x16x32_bf16 v[98:101], v[182:185], v[198:201], v[98:101]
	v_mfma_f32_16x16x32_bf16 v[98:101], v[186:189], v[202:205], v[98:101]
	v_mfma_f32_16x16x32_bf16 v[86:89], v[168:171], v[206:209], v[86:89]
	v_mfma_f32_16x16x32_bf16 v[86:89], v[172:175], v[210:213], v[86:89]
	v_mfma_f32_16x16x32_bf16 v[82:85], v[182:185], v[206:209], v[82:85]
	v_mfma_f32_16x16x32_bf16 v[82:85], v[186:189], v[210:213], v[82:85]
	v_mfma_f32_16x16x32_bf16 v[70:73], v[168:171], v[214:217], v[70:73]
	v_mfma_f32_16x16x32_bf16 v[70:73], v[172:175], v[218:221], v[70:73]
	v_mfma_f32_16x16x32_bf16 v[66:69], v[182:185], v[214:217], v[66:69]
	v_mfma_f32_16x16x32_bf16 v[66:69], v[186:189], v[218:221], v[66:69]
	s_barrier
	s_setprio 0
	s_add_i32 s72, s62, s37
	v_lshl_add_u64 v[176:177], s[26:27], 0, v[132:133]
	s_mov_b32 m0, s72
	ds_read_b128 v[190:193], v154 offset:16384
	ds_read_b128 v[194:197], v154 offset:17408
	ds_read_b128 v[198:201], v154 offset:18432
	ds_read_b128 v[202:205], v154 offset:19456
	ds_read_b128 v[206:209], v154 offset:20480
	ds_read_b128 v[210:213], v154 offset:21504
	ds_read_b128 v[214:217], v154 offset:22528
	ds_read_b128 v[218:221], v154 offset:23552
	global_load_lds_dwordx4 v[176:177], off
	s_add_i32 m0, s72, 0x2000
	s_add_u32 s72, s26, 0x20000
	v_lshl_add_u64 v[222:223], s[26:27], 0, v[136:137]
	s_addc_u32 s73, s27, 0
	s_add_i32 s76, s63, s37
	global_load_lds_dwordx4 v[222:223], off
	v_lshl_add_u64 v[224:225], s[72:73], 0, v[132:133]
	s_mov_b32 m0, s76
	v_lshl_add_u64 v[226:227], s[28:29], 0, v[134:135]
	global_load_lds_dwordx4 v[224:225], off
	v_lshl_add_u64 v[224:225], s[72:73], 0, v[136:137]
	s_add_i32 m0, s76, 0x2000
	s_nop 0
	global_load_lds_dwordx4 v[224:225], off
	v_lshl_add_u64 v[224:225], s[28:29], 0, v[130:131]
	s_mov_b32 m0, s21
	s_nop 0
	global_load_lds_dwordx4 v[224:225], off
	s_mov_b32 m0, s54
	s_nop 0
	global_load_lds_dwordx4 v[226:227], off
	s_waitcnt vmcnt(8)
	s_waitcnt lgkmcnt(0)
	s_setprio 1
	s_barrier
	v_mfma_f32_16x16x32_bf16 v[62:65], v[146:149], v[190:193], v[62:65]
	v_mfma_f32_16x16x32_bf16 v[62:65], v[156:159], v[194:197], v[62:65]
	v_mfma_f32_16x16x32_bf16 v[58:61], v[160:163], v[190:193], v[58:61]
	v_mfma_f32_16x16x32_bf16 v[58:61], v[164:167], v[194:197], v[58:61]
	v_mfma_f32_16x16x32_bf16 v[46:49], v[146:149], v[198:201], v[46:49]
	v_mfma_f32_16x16x32_bf16 v[46:49], v[156:159], v[202:205], v[46:49]
	v_mfma_f32_16x16x32_bf16 v[42:45], v[160:163], v[198:201], v[42:45]
	v_mfma_f32_16x16x32_bf16 v[42:45], v[164:167], v[202:205], v[42:45]
	v_mfma_f32_16x16x32_bf16 v[30:33], v[146:149], v[206:209], v[30:33]
	v_mfma_f32_16x16x32_bf16 v[30:33], v[156:159], v[210:213], v[30:33]
	v_mfma_f32_16x16x32_bf16 v[26:29], v[160:163], v[206:209], v[26:29]
	v_mfma_f32_16x16x32_bf16 v[26:29], v[164:167], v[210:213], v[26:29]
	v_mfma_f32_16x16x32_bf16 v[14:17], v[146:149], v[214:217], v[14:17]
	v_mfma_f32_16x16x32_bf16 v[14:17], v[156:159], v[218:221], v[14:17]
	v_mfma_f32_16x16x32_bf16 v[10:13], v[160:163], v[214:217], v[10:13]
	v_mfma_f32_16x16x32_bf16 v[10:13], v[164:167], v[218:221], v[10:13]
	v_mfma_f32_16x16x32_bf16 v[54:57], v[168:171], v[190:193], v[54:57]
	v_mfma_f32_16x16x32_bf16 v[54:57], v[172:175], v[194:197], v[54:57]
	v_mfma_f32_16x16x32_bf16 v[50:53], v[182:185], v[190:193], v[50:53]
	v_mfma_f32_16x16x32_bf16 v[50:53], v[186:189], v[194:197], v[50:53]
	v_mfma_f32_16x16x32_bf16 v[38:41], v[168:171], v[198:201], v[38:41]
	v_mfma_f32_16x16x32_bf16 v[38:41], v[172:175], v[202:205], v[38:41]
	v_mfma_f32_16x16x32_bf16 v[34:37], v[182:185], v[198:201], v[34:37]
	v_mfma_f32_16x16x32_bf16 v[34:37], v[186:189], v[202:205], v[34:37]
	v_mfma_f32_16x16x32_bf16 v[22:25], v[168:171], v[206:209], v[22:25]
	v_mfma_f32_16x16x32_bf16 v[22:25], v[172:175], v[210:213], v[22:25]
	v_mfma_f32_16x16x32_bf16 v[18:21], v[182:185], v[206:209], v[18:21]
	v_mfma_f32_16x16x32_bf16 v[18:21], v[186:189], v[210:213], v[18:21]
	v_mfma_f32_16x16x32_bf16 v[6:9], v[168:171], v[214:217], v[6:9]
	v_mfma_f32_16x16x32_bf16 v[6:9], v[172:175], v[218:221], v[6:9]
	v_mfma_f32_16x16x32_bf16 v[2:5], v[182:185], v[214:217], v[2:5]
	v_mfma_f32_16x16x32_bf16 v[2:5], v[186:189], v[218:221], v[2:5]
	s_barrier
	s_setprio 0
	s_add_i32 s72, 0, 0x18000
	s_add_i32 s73, 0, 0x1c000
	v_add_u32_e32 v164, s72, v151
	v_add_u32_e32 v179, s73, v151
	ds_read_b128 v[146:149], v164
	ds_read_b128 v[156:159], v164 offset:1024
	ds_read_b128 v[160:163], v164 offset:2048
	ds_read_b128 v[164:167], v164 offset:3072
	ds_read_b128 v[168:171], v179
	ds_read_b128 v[172:175], v179 offset:1024
	ds_read_b128 v[182:185], v179 offset:2048
	ds_read_b128 v[186:189], v179 offset:3072
	s_add_u32 s28, s28, 0x40000
	s_addc_u32 s29, s29, 0
	s_mov_b32 m0, s55
	v_lshl_add_u64 v[228:229], s[28:29], 0, v[130:131]
	ds_read_b128 v[190:193], v154 offset:32768
	ds_read_b128 v[194:197], v154 offset:33792
	ds_read_b128 v[198:201], v154 offset:34816
	ds_read_b128 v[202:205], v154 offset:35840
	ds_read_b128 v[206:209], v154 offset:36864
	ds_read_b128 v[210:213], v154 offset:37888
	ds_read_b128 v[214:217], v154 offset:38912
	ds_read_b128 v[218:221], v154 offset:39936
	global_load_lds_dwordx4 v[228:229], off
	v_lshl_add_u64 v[228:229], s[28:29], 0, v[134:135]
	s_mov_b32 m0, s56
	s_nop 0
	global_load_lds_dwordx4 v[228:229], off
	s_waitcnt vmcnt(8)
	s_waitcnt lgkmcnt(0)
	s_setprio 1
	s_barrier
	v_mfma_f32_16x16x32_bf16 v[126:129], v[146:149], v[190:193], v[126:129]
	v_mfma_f32_16x16x32_bf16 v[126:129], v[156:159], v[194:197], v[126:129]
	v_mfma_f32_16x16x32_bf16 v[122:125], v[160:163], v[190:193], v[122:125]
	v_mfma_f32_16x16x32_bf16 v[122:125], v[164:167], v[194:197], v[122:125]
	v_mfma_f32_16x16x32_bf16 v[110:113], v[146:149], v[198:201], v[110:113]
	v_mfma_f32_16x16x32_bf16 v[110:113], v[156:159], v[202:205], v[110:113]
	v_mfma_f32_16x16x32_bf16 v[106:109], v[160:163], v[198:201], v[106:109]
	v_mfma_f32_16x16x32_bf16 v[106:109], v[164:167], v[202:205], v[106:109]
	v_mfma_f32_16x16x32_bf16 v[94:97], v[146:149], v[206:209], v[94:97]
	v_mfma_f32_16x16x32_bf16 v[94:97], v[156:159], v[210:213], v[94:97]
	v_mfma_f32_16x16x32_bf16 v[90:93], v[160:163], v[206:209], v[90:93]
	v_mfma_f32_16x16x32_bf16 v[90:93], v[164:167], v[210:213], v[90:93]
	v_mfma_f32_16x16x32_bf16 v[78:81], v[146:149], v[214:217], v[78:81]
	v_mfma_f32_16x16x32_bf16 v[78:81], v[156:159], v[218:221], v[78:81]
	v_mfma_f32_16x16x32_bf16 v[74:77], v[160:163], v[214:217], v[74:77]
	v_mfma_f32_16x16x32_bf16 v[74:77], v[164:167], v[218:221], v[74:77]
	v_mfma_f32_16x16x32_bf16 v[118:121], v[168:171], v[190:193], v[118:121]
	v_mfma_f32_16x16x32_bf16 v[118:121], v[172:175], v[194:197], v[118:121]
	v_mfma_f32_16x16x32_bf16 v[114:117], v[182:185], v[190:193], v[114:117]
	v_mfma_f32_16x16x32_bf16 v[114:117], v[186:189], v[194:197], v[114:117]
	v_mfma_f32_16x16x32_bf16 v[102:105], v[168:171], v[198:201], v[102:105]
	v_mfma_f32_16x16x32_bf16 v[102:105], v[172:175], v[202:205], v[102:105]
	v_mfma_f32_16x16x32_bf16 v[98:101], v[182:185], v[198:201], v[98:101]
	v_mfma_f32_16x16x32_bf16 v[98:101], v[186:189], v[202:205], v[98:101]
	v_mfma_f32_16x16x32_bf16 v[86:89], v[168:171], v[206:209], v[86:89]
	v_mfma_f32_16x16x32_bf16 v[86:89], v[172:175], v[210:213], v[86:89]
	v_mfma_f32_16x16x32_bf16 v[82:85], v[182:185], v[206:209], v[82:85]
	v_mfma_f32_16x16x32_bf16 v[82:85], v[186:189], v[210:213], v[82:85]
	v_mfma_f32_16x16x32_bf16 v[70:73], v[168:171], v[214:217], v[70:73]
	v_mfma_f32_16x16x32_bf16 v[70:73], v[172:175], v[218:221], v[70:73]
	v_mfma_f32_16x16x32_bf16 v[66:69], v[182:185], v[214:217], v[66:69]
	v_mfma_f32_16x16x32_bf16 v[66:69], v[186:189], v[218:221], v[66:69]
	s_barrier
	s_setprio 0
	s_add_i32 s28, s72, s37
	v_lshl_add_u64 v[176:177], v[176:177], 0, s[6:7]
	s_mov_b32 m0, s28
	ds_read_b128 v[190:193], v154 offset:49152
	ds_read_b128 v[194:197], v154 offset:50176
	ds_read_b128 v[198:201], v154 offset:51200
	ds_read_b128 v[202:205], v154 offset:52224
	ds_read_b128 v[206:209], v154 offset:53248
	ds_read_b128 v[210:213], v154 offset:54272
	ds_read_b128 v[214:217], v154 offset:55296
	ds_read_b128 v[218:221], v154 offset:56320
	global_load_lds_dwordx4 v[176:177], off
	s_add_i32 m0, s28, 0x2000
	s_add_u32 s26, s26, 0x20080
	v_lshl_add_u64 v[176:177], v[222:223], 0, s[6:7]
	s_addc_u32 s27, s27, 0
	s_add_i32 s28, s73, s37
	global_load_lds_dwordx4 v[176:177], off
	v_lshl_add_u64 v[176:177], s[26:27], 0, v[132:133]
	s_mov_b32 m0, s28
	s_nop 0
	global_load_lds_dwordx4 v[176:177], off
	v_lshl_add_u64 v[176:177], s[26:27], 0, v[136:137]
	s_add_i32 m0, s28, 0x2000
	s_nop 0
	global_load_lds_dwordx4 v[176:177], off
	v_lshl_add_u64 v[176:177], v[224:225], 0, s[6:7]
	s_mov_b32 m0, s58
	s_nop 0
	global_load_lds_dwordx4 v[176:177], off
	v_lshl_add_u64 v[176:177], v[226:227], 0, s[6:7]
	s_mov_b32 m0, s59
	s_nop 0
	global_load_lds_dwordx4 v[176:177], off
	s_waitcnt vmcnt(8)
	s_waitcnt lgkmcnt(0)
	s_setprio 1
	s_barrier
	v_mfma_f32_16x16x32_bf16 v[62:65], v[146:149], v[190:193], v[62:65]
	v_mfma_f32_16x16x32_bf16 v[62:65], v[156:159], v[194:197], v[62:65]
	v_mfma_f32_16x16x32_bf16 v[58:61], v[160:163], v[190:193], v[58:61]
	v_mfma_f32_16x16x32_bf16 v[58:61], v[164:167], v[194:197], v[58:61]
	v_mfma_f32_16x16x32_bf16 v[46:49], v[146:149], v[198:201], v[46:49]
	v_mfma_f32_16x16x32_bf16 v[46:49], v[156:159], v[202:205], v[46:49]
	v_mfma_f32_16x16x32_bf16 v[42:45], v[160:163], v[198:201], v[42:45]
	v_mfma_f32_16x16x32_bf16 v[42:45], v[164:167], v[202:205], v[42:45]
	v_mfma_f32_16x16x32_bf16 v[30:33], v[146:149], v[206:209], v[30:33]
	v_mfma_f32_16x16x32_bf16 v[30:33], v[156:159], v[210:213], v[30:33]
	v_mfma_f32_16x16x32_bf16 v[26:29], v[160:163], v[206:209], v[26:29]
	v_mfma_f32_16x16x32_bf16 v[26:29], v[164:167], v[210:213], v[26:29]
	v_mfma_f32_16x16x32_bf16 v[14:17], v[146:149], v[214:217], v[14:17]
	v_mfma_f32_16x16x32_bf16 v[14:17], v[156:159], v[218:221], v[14:17]
	v_mfma_f32_16x16x32_bf16 v[10:13], v[160:163], v[214:217], v[10:13]
	v_mfma_f32_16x16x32_bf16 v[10:13], v[164:167], v[218:221], v[10:13]
	v_mfma_f32_16x16x32_bf16 v[54:57], v[168:171], v[190:193], v[54:57]
	v_mfma_f32_16x16x32_bf16 v[54:57], v[172:175], v[194:197], v[54:57]
	v_mfma_f32_16x16x32_bf16 v[50:53], v[182:185], v[190:193], v[50:53]
	v_mfma_f32_16x16x32_bf16 v[50:53], v[186:189], v[194:197], v[50:53]
	v_mfma_f32_16x16x32_bf16 v[38:41], v[168:171], v[198:201], v[38:41]
	v_mfma_f32_16x16x32_bf16 v[38:41], v[172:175], v[202:205], v[38:41]
	v_mfma_f32_16x16x32_bf16 v[34:37], v[182:185], v[198:201], v[34:37]
	v_mfma_f32_16x16x32_bf16 v[34:37], v[186:189], v[202:205], v[34:37]
	v_mfma_f32_16x16x32_bf16 v[22:25], v[168:171], v[206:209], v[22:25]
	v_mfma_f32_16x16x32_bf16 v[22:25], v[172:175], v[210:213], v[22:25]
	v_mfma_f32_16x16x32_bf16 v[18:21], v[182:185], v[206:209], v[18:21]
	v_mfma_f32_16x16x32_bf16 v[18:21], v[186:189], v[210:213], v[18:21]
	v_mfma_f32_16x16x32_bf16 v[6:9], v[168:171], v[214:217], v[6:9]
	v_mfma_f32_16x16x32_bf16 v[6:9], v[172:175], v[218:221], v[6:9]
	v_mfma_f32_16x16x32_bf16 v[2:5], v[182:185], v[214:217], v[2:5]
	v_mfma_f32_16x16x32_bf16 v[2:5], v[186:189], v[218:221], v[2:5]
	s_barrier
	s_setprio 0
	s_add_i32 s71, s71, 2
	s_add_u32 s22, s22, 0x100
	s_addc_u32 s23, s23, 0
	s_add_u32 s69, s69, 0x100
	s_addc_u32 s70, s70, 0
	s_cmp_gt_u32 s71, 5
	s_cbranch_scc0 .LBB0_2146
	s_and_b64 vcc, exec, s[10:11]
	s_cbranch_vccz .LBB0_2149
	s_barrier

.LBB0_2322:
	ds_read_b128 v[144:147], v150
	ds_read_b128 v[154:157], v150 offset:1024
	ds_read_b128 v[158:161], v150 offset:2048
	ds_read_b128 v[162:165], v150 offset:3072
	ds_read_b128 v[166:169], v151
	ds_read_b128 v[170:173], v151 offset:1024
	ds_read_b128 v[174:177], v151 offset:2048
	ds_read_b128 v[182:185], v151 offset:3072
	s_add_i32 s72, s30, 2
	s_add_u32 s31, s28, 0xfff80080
	s_addc_u32 s34, s29, -1
	s_cmp_eq_u32 s17, s30
	s_cselect_b32 s30, s26, s19
	s_cselect_b32 s35, s23, s34
	s_cselect_b32 s34, s22, s31
	s_cselect_b32 s31, s27, s21
	v_lshl_add_u64 v[218:219], s[28:29], 0, v[138:139]
	s_add_i32 m0, s3, 0xc000
	ds_read_b128 v[186:189], v152
	ds_read_b128 v[190:193], v152 offset:1024
	ds_read_b128 v[194:197], v152 offset:2048
	ds_read_b128 v[198:201], v152 offset:3072
	ds_read_b128 v[202:205], v152 offset:4096
	ds_read_b128 v[206:209], v152 offset:5120
	ds_read_b128 v[210:213], v152 offset:6144
	ds_read_b128 v[214:217], v152 offset:7168
	global_load_lds_dwordx4 v[218:219], off
	v_lshl_add_u64 v[218:219], s[28:29], 0, v[140:141]
	s_add_i32 m0, s3, 0xe000
	s_nop 0
	global_load_lds_dwordx4 v[218:219], off
	s_waitcnt vmcnt(8)
	s_waitcnt lgkmcnt(0)
	s_setprio 1
	s_barrier
	v_mfma_f32_16x16x32_bf16 v[126:129], v[144:147], v[186:189], v[126:129]
	v_mfma_f32_16x16x32_bf16 v[126:129], v[154:157], v[190:193], v[126:129]
	v_mfma_f32_16x16x32_bf16 v[122:125], v[158:161], v[186:189], v[122:125]
	v_mfma_f32_16x16x32_bf16 v[122:125], v[162:165], v[190:193], v[122:125]
	v_mfma_f32_16x16x32_bf16 v[118:121], v[144:147], v[194:197], v[118:121]
	v_mfma_f32_16x16x32_bf16 v[118:121], v[154:157], v[198:201], v[118:121]
	v_mfma_f32_16x16x32_bf16 v[114:117], v[158:161], v[194:197], v[114:117]
	v_mfma_f32_16x16x32_bf16 v[114:117], v[162:165], v[198:201], v[114:117]
	v_mfma_f32_16x16x32_bf16 v[106:109], v[144:147], v[202:205], v[106:109]
	v_mfma_f32_16x16x32_bf16 v[106:109], v[154:157], v[206:209], v[106:109]
	v_mfma_f32_16x16x32_bf16 v[98:101], v[158:161], v[202:205], v[98:101]
	v_mfma_f32_16x16x32_bf16 v[98:101], v[162:165], v[206:209], v[98:101]
	v_mfma_f32_16x16x32_bf16 v[90:93], v[144:147], v[210:213], v[90:93]
	v_mfma_f32_16x16x32_bf16 v[90:93], v[154:157], v[214:217], v[90:93]
	v_mfma_f32_16x16x32_bf16 v[82:85], v[158:161], v[210:213], v[82:85]
	v_mfma_f32_16x16x32_bf16 v[82:85], v[162:165], v[214:217], v[82:85]
	v_mfma_f32_16x16x32_bf16 v[110:113], v[166:169], v[186:189], v[110:113]
	v_mfma_f32_16x16x32_bf16 v[110:113], v[170:173], v[190:193], v[110:113]
	v_mfma_f32_16x16x32_bf16 v[102:105], v[174:177], v[186:189], v[102:105]
	v_mfma_f32_16x16x32_bf16 v[102:105], v[182:185], v[190:193], v[102:105]
	v_mfma_f32_16x16x32_bf16 v[94:97], v[166:169], v[194:197], v[94:97]
	v_mfma_f32_16x16x32_bf16 v[94:97], v[170:173], v[198:201], v[94:97]
	v_mfma_f32_16x16x32_bf16 v[86:89], v[174:177], v[194:197], v[86:89]
	v_mfma_f32_16x16x32_bf16 v[86:89], v[182:185], v[198:201], v[86:89]
	v_mfma_f32_16x16x32_bf16 v[78:81], v[166:169], v[202:205], v[78:81]
	v_mfma_f32_16x16x32_bf16 v[78:81], v[170:173], v[206:209], v[78:81]
	v_mfma_f32_16x16x32_bf16 v[74:77], v[174:177], v[202:205], v[74:77]
	v_mfma_f32_16x16x32_bf16 v[74:77], v[182:185], v[206:209], v[74:77]
	v_mfma_f32_16x16x32_bf16 v[70:73], v[166:169], v[210:213], v[70:73]
	v_mfma_f32_16x16x32_bf16 v[70:73], v[170:173], v[214:217], v[70:73]
	v_mfma_f32_16x16x32_bf16 v[66:69], v[174:177], v[210:213], v[66:69]
	v_mfma_f32_16x16x32_bf16 v[66:69], v[182:185], v[214:217], v[66:69]
	s_barrier
	s_setprio 0
	s_add_i32 s73, s63, s52
	v_lshl_add_u64 v[218:219], s[30:31], 0, v[132:133]
	s_mov_b32 m0, s73
	ds_read_b128 v[186:189], v152 offset:16384
	ds_read_b128 v[190:193], v152 offset:17408
	ds_read_b128 v[194:197], v152 offset:18432
	ds_read_b128 v[198:201], v152 offset:19456
	ds_read_b128 v[202:205], v152 offset:20480
	ds_read_b128 v[206:209], v152 offset:21504
	ds_read_b128 v[210:213], v152 offset:22528
	ds_read_b128 v[214:217], v152 offset:23552
	global_load_lds_dwordx4 v[218:219], off
	s_add_i32 m0, s73, 0x2000
	s_add_u32 s76, s30, 0x80000
	v_lshl_add_u64 v[220:221], s[30:31], 0, v[136:137]
	s_addc_u32 s77, s31, 0
	s_add_i32 s73, s66, s52
	global_load_lds_dwordx4 v[220:221], off
	v_lshl_add_u64 v[222:223], s[76:77], 0, v[132:133]
	s_mov_b32 m0, s73
	v_lshl_add_u64 v[224:225], s[34:35], 0, v[134:135]
	global_load_lds_dwordx4 v[222:223], off
	v_lshl_add_u64 v[222:223], s[76:77], 0, v[136:137]
	s_add_i32 m0, s73, 0x2000
	s_nop 0
	global_load_lds_dwordx4 v[222:223], off
	v_lshl_add_u64 v[222:223], s[34:35], 0, v[130:131]
	s_mov_b32 m0, s3
	s_nop 0
	global_load_lds_dwordx4 v[222:223], off
	s_mov_b32 m0, s54
	s_nop 0
	global_load_lds_dwordx4 v[224:225], off
	s_waitcnt vmcnt(8)
	s_waitcnt lgkmcnt(0)
	s_setprio 1
	s_barrier
	v_mfma_f32_16x16x32_bf16 v[62:65], v[144:147], v[186:189], v[62:65]
	v_mfma_f32_16x16x32_bf16 v[62:65], v[154:157], v[190:193], v[62:65]
	v_mfma_f32_16x16x32_bf16 v[58:61], v[158:161], v[186:189], v[58:61]
	v_mfma_f32_16x16x32_bf16 v[58:61], v[162:165], v[190:193], v[58:61]
	v_mfma_f32_16x16x32_bf16 v[54:57], v[144:147], v[194:197], v[54:57]
	v_mfma_f32_16x16x32_bf16 v[54:57], v[154:157], v[198:201], v[54:57]
	v_mfma_f32_16x16x32_bf16 v[50:53], v[158:161], v[194:197], v[50:53]
	v_mfma_f32_16x16x32_bf16 v[50:53], v[162:165], v[198:201], v[50:53]
	v_mfma_f32_16x16x32_bf16 v[42:45], v[144:147], v[202:205], v[42:45]
	v_mfma_f32_16x16x32_bf16 v[42:45], v[154:157], v[206:209], v[42:45]
	v_mfma_f32_16x16x32_bf16 v[34:37], v[158:161], v[202:205], v[34:37]
	v_mfma_f32_16x16x32_bf16 v[34:37], v[162:165], v[206:209], v[34:37]
	v_mfma_f32_16x16x32_bf16 v[26:29], v[144:147], v[210:213], v[26:29]
	v_mfma_f32_16x16x32_bf16 v[26:29], v[154:157], v[214:217], v[26:29]
	v_mfma_f32_16x16x32_bf16 v[18:21], v[158:161], v[210:213], v[18:21]
	v_mfma_f32_16x16x32_bf16 v[18:21], v[162:165], v[214:217], v[18:21]
	v_mfma_f32_16x16x32_bf16 v[46:49], v[166:169], v[186:189], v[46:49]
	v_mfma_f32_16x16x32_bf16 v[46:49], v[170:173], v[190:193], v[46:49]
	v_mfma_f32_16x16x32_bf16 v[38:41], v[174:177], v[186:189], v[38:41]
	v_mfma_f32_16x16x32_bf16 v[38:41], v[182:185], v[190:193], v[38:41]
	v_mfma_f32_16x16x32_bf16 v[30:33], v[166:169], v[194:197], v[30:33]
	v_mfma_f32_16x16x32_bf16 v[30:33], v[170:173], v[198:201], v[30:33]
	v_mfma_f32_16x16x32_bf16 v[22:25], v[174:177], v[194:197], v[22:25]
	v_mfma_f32_16x16x32_bf16 v[22:25], v[182:185], v[198:201], v[22:25]
	v_mfma_f32_16x16x32_bf16 v[14:17], v[166:169], v[202:205], v[14:17]
	v_mfma_f32_16x16x32_bf16 v[14:17], v[170:173], v[206:209], v[14:17]
	v_mfma_f32_16x16x32_bf16 v[10:13], v[174:177], v[202:205], v[10:13]
	v_mfma_f32_16x16x32_bf16 v[10:13], v[182:185], v[206:209], v[10:13]
	v_mfma_f32_16x16x32_bf16 v[6:9], v[166:169], v[210:213], v[6:9]
	v_mfma_f32_16x16x32_bf16 v[6:9], v[170:173], v[214:217], v[6:9]
	v_mfma_f32_16x16x32_bf16 v[2:5], v[174:177], v[210:213], v[2:5]
	v_mfma_f32_16x16x32_bf16 v[2:5], v[182:185], v[214:217], v[2:5]
	s_barrier
	s_setprio 0
	s_add_i32 s73, 0, 0x18000
	v_add_u32_e32 v153, s73, v148
	s_add_i32 s76, 0, 0x1c000
	ds_read_b128 v[144:147], v153
	ds_read_b128 v[154:157], v153 offset:1024
	ds_read_b128 v[158:161], v153 offset:2048
	ds_read_b128 v[162:165], v153 offset:3072
	v_add_u32_e32 v153, s76, v148
	ds_read_b128 v[166:169], v153
	ds_read_b128 v[170:173], v153 offset:1024
	ds_read_b128 v[174:177], v153 offset:2048
	ds_read_b128 v[182:185], v153 offset:3072
	s_add_u32 s34, s34, 0x80000
	s_addc_u32 s35, s35, 0
	s_mov_b32 m0, s55
	v_lshl_add_u64 v[226:227], s[34:35], 0, v[130:131]
	ds_read_b128 v[186:189], v152 offset:32768
	ds_read_b128 v[190:193], v152 offset:33792
	ds_read_b128 v[194:197], v152 offset:34816
	ds_read_b128 v[198:201], v152 offset:35840
	ds_read_b128 v[202:205], v152 offset:36864
	ds_read_b128 v[206:209], v152 offset:37888
	ds_read_b128 v[210:213], v152 offset:38912
	ds_read_b128 v[214:217], v152 offset:39936
	global_load_lds_dwordx4 v[226:227], off
	v_lshl_add_u64 v[226:227], s[34:35], 0, v[134:135]
	s_mov_b32 m0, s56
	s_nop 0
	global_load_lds_dwordx4 v[226:227], off
	s_waitcnt vmcnt(8)
	s_waitcnt lgkmcnt(0)
	s_setprio 1
	s_barrier
	v_mfma_f32_16x16x32_bf16 v[126:129], v[144:147], v[186:189], v[126:129]
	v_mfma_f32_16x16x32_bf16 v[126:129], v[154:157], v[190:193], v[126:129]
	v_mfma_f32_16x16x32_bf16 v[122:125], v[158:161], v[186:189], v[122:125]
	v_mfma_f32_16x16x32_bf16 v[122:125], v[162:165], v[190:193], v[122:125]
	v_mfma_f32_16x16x32_bf16 v[118:121], v[144:147], v[194:197], v[118:121]
	v_mfma_f32_16x16x32_bf16 v[118:121], v[154:157], v[198:201], v[118:121]
	v_mfma_f32_16x16x32_bf16 v[114:117], v[158:161], v[194:197], v[114:117]
	v_mfma_f32_16x16x32_bf16 v[114:117], v[162:165], v[198:201], v[114:117]
	v_mfma_f32_16x16x32_bf16 v[106:109], v[144:147], v[202:205], v[106:109]
	v_mfma_f32_16x16x32_bf16 v[106:109], v[154:157], v[206:209], v[106:109]
	v_mfma_f32_16x16x32_bf16 v[98:101], v[158:161], v[202:205], v[98:101]
	v_mfma_f32_16x16x32_bf16 v[98:101], v[162:165], v[206:209], v[98:101]
	v_mfma_f32_16x16x32_bf16 v[90:93], v[144:147], v[210:213], v[90:93]
	v_mfma_f32_16x16x32_bf16 v[90:93], v[154:157], v[214:217], v[90:93]
	v_mfma_f32_16x16x32_bf16 v[82:85], v[158:161], v[210:213], v[82:85]
	v_mfma_f32_16x16x32_bf16 v[82:85], v[162:165], v[214:217], v[82:85]
	v_mfma_f32_16x16x32_bf16 v[110:113], v[166:169], v[186:189], v[110:113]
	v_mfma_f32_16x16x32_bf16 v[110:113], v[170:173], v[190:193], v[110:113]
	v_mfma_f32_16x16x32_bf16 v[102:105], v[174:177], v[186:189], v[102:105]
	v_mfma_f32_16x16x32_bf16 v[102:105], v[182:185], v[190:193], v[102:105]
	v_mfma_f32_16x16x32_bf16 v[94:97], v[166:169], v[194:197], v[94:97]
	v_mfma_f32_16x16x32_bf16 v[94:97], v[170:173], v[198:201], v[94:97]
	v_mfma_f32_16x16x32_bf16 v[86:89], v[174:177], v[194:197], v[86:89]
	v_mfma_f32_16x16x32_bf16 v[86:89], v[182:185], v[198:201], v[86:89]
	v_mfma_f32_16x16x32_bf16 v[78:81], v[166:169], v[202:205], v[78:81]
	v_mfma_f32_16x16x32_bf16 v[78:81], v[170:173], v[206:209], v[78:81]
	v_mfma_f32_16x16x32_bf16 v[74:77], v[174:177], v[202:205], v[74:77]
	v_mfma_f32_16x16x32_bf16 v[74:77], v[182:185], v[206:209], v[74:77]
	v_mfma_f32_16x16x32_bf16 v[70:73], v[166:169], v[210:213], v[70:73]
	v_mfma_f32_16x16x32_bf16 v[70:73], v[170:173], v[214:217], v[70:73]
	v_mfma_f32_16x16x32_bf16 v[66:69], v[174:177], v[210:213], v[66:69]
	v_mfma_f32_16x16x32_bf16 v[66:69], v[182:185], v[214:217], v[66:69]
	s_barrier
	s_setprio 0
	s_add_i32 s34, s73, s52
	v_lshl_add_u64 v[218:219], v[218:219], 0, s[6:7]
	s_mov_b32 m0, s34
	ds_read_b128 v[186:189], v152 offset:49152
	ds_read_b128 v[190:193], v152 offset:50176
	ds_read_b128 v[194:197], v152 offset:51200
	ds_read_b128 v[198:201], v152 offset:52224
	ds_read_b128 v[202:205], v152 offset:53248
	ds_read_b128 v[206:209], v152 offset:54272
	ds_read_b128 v[210:213], v152 offset:55296
	ds_read_b128 v[214:217], v152 offset:56320
	global_load_lds_dwordx4 v[218:219], off
	s_add_i32 m0, s34, 0x2000
	s_add_u32 s30, s30, 0x80080
	v_lshl_add_u64 v[218:219], v[220:221], 0, s[6:7]
	s_addc_u32 s31, s31, 0
	s_add_i32 s34, s76, s52
	global_load_lds_dwordx4 v[218:219], off
	v_lshl_add_u64 v[218:219], s[30:31], 0, v[132:133]
	s_mov_b32 m0, s34
	s_nop 0
	global_load_lds_dwordx4 v[218:219], off
	v_lshl_add_u64 v[218:219], s[30:31], 0, v[136:137]
	s_add_i32 m0, s34, 0x2000
	s_nop 0
	global_load_lds_dwordx4 v[218:219], off
	v_lshl_add_u64 v[218:219], v[222:223], 0, s[6:7]
	s_mov_b32 m0, s58
	s_nop 0
	global_load_lds_dwordx4 v[218:219], off
	v_lshl_add_u64 v[218:219], v[224:225], 0, s[6:7]
	s_mov_b32 m0, s59
	s_nop 0
	global_load_lds_dwordx4 v[218:219], off
	s_waitcnt vmcnt(8)
	s_waitcnt lgkmcnt(0)
	s_setprio 1
	s_barrier
	v_mfma_f32_16x16x32_bf16 v[62:65], v[144:147], v[186:189], v[62:65]
	v_mfma_f32_16x16x32_bf16 v[62:65], v[154:157], v[190:193], v[62:65]
	v_mfma_f32_16x16x32_bf16 v[58:61], v[158:161], v[186:189], v[58:61]
	v_mfma_f32_16x16x32_bf16 v[58:61], v[162:165], v[190:193], v[58:61]
	v_mfma_f32_16x16x32_bf16 v[54:57], v[144:147], v[194:197], v[54:57]
	v_mfma_f32_16x16x32_bf16 v[54:57], v[154:157], v[198:201], v[54:57]
	v_mfma_f32_16x16x32_bf16 v[50:53], v[158:161], v[194:197], v[50:53]
	v_mfma_f32_16x16x32_bf16 v[50:53], v[162:165], v[198:201], v[50:53]
	v_mfma_f32_16x16x32_bf16 v[42:45], v[144:147], v[202:205], v[42:45]
	v_mfma_f32_16x16x32_bf16 v[42:45], v[154:157], v[206:209], v[42:45]
	v_mfma_f32_16x16x32_bf16 v[34:37], v[158:161], v[202:205], v[34:37]
	v_mfma_f32_16x16x32_bf16 v[34:37], v[162:165], v[206:209], v[34:37]
	v_mfma_f32_16x16x32_bf16 v[26:29], v[144:147], v[210:213], v[26:29]
	v_mfma_f32_16x16x32_bf16 v[26:29], v[154:157], v[214:217], v[26:29]
	v_mfma_f32_16x16x32_bf16 v[18:21], v[158:161], v[210:213], v[18:21]
	v_mfma_f32_16x16x32_bf16 v[18:21], v[162:165], v[214:217], v[18:21]
	v_mfma_f32_16x16x32_bf16 v[46:49], v[166:169], v[186:189], v[46:49]
	v_mfma_f32_16x16x32_bf16 v[46:49], v[170:173], v[190:193], v[46:49]
	v_mfma_f32_16x16x32_bf16 v[38:41], v[174:177], v[186:189], v[38:41]
	v_mfma_f32_16x16x32_bf16 v[38:41], v[182:185], v[190:193], v[38:41]
	v_mfma_f32_16x16x32_bf16 v[30:33], v[166:169], v[194:197], v[30:33]
	v_mfma_f32_16x16x32_bf16 v[30:33], v[170:173], v[198:201], v[30:33]
	v_mfma_f32_16x16x32_bf16 v[22:25], v[174:177], v[194:197], v[22:25]
	v_mfma_f32_16x16x32_bf16 v[22:25], v[182:185], v[198:201], v[22:25]
	v_mfma_f32_16x16x32_bf16 v[14:17], v[166:169], v[202:205], v[14:17]
	v_mfma_f32_16x16x32_bf16 v[14:17], v[170:173], v[206:209], v[14:17]
	v_mfma_f32_16x16x32_bf16 v[10:13], v[174:177], v[202:205], v[10:13]
	v_mfma_f32_16x16x32_bf16 v[10:13], v[182:185], v[206:209], v[10:13]
	v_mfma_f32_16x16x32_bf16 v[6:9], v[166:169], v[210:213], v[6:9]
	v_mfma_f32_16x16x32_bf16 v[6:9], v[170:173], v[214:217], v[6:9]
	v_mfma_f32_16x16x32_bf16 v[2:5], v[174:177], v[210:213], v[2:5]
	v_mfma_f32_16x16x32_bf16 v[2:5], v[182:185], v[214:217], v[2:5]
	s_barrier
	s_setprio 0
	s_add_u32 s28, s28, 0x100
	s_addc_u32 s29, s29, 0
	s_add_u32 s19, s19, 0x100
	s_addc_u32 s21, s21, 0
	s_cmp_ge_i32 s72, s71
	s_mov_b32 s30, s72
	s_cbranch_scc0 .LBB0_2322
	s_and_b64 vcc, exec, s[8:9]
	s_cbranch_vccz .LBB0_2325
	s_barrier

.LBB0_2565:
	ds_read_b128 v[144:147], v151
	ds_read_b128 v[154:157], v151 offset:1024
	ds_read_b128 v[158:161], v151 offset:2048
	ds_read_b128 v[162:165], v151 offset:3072
	ds_read_b128 v[166:169], v152
	ds_read_b128 v[170:173], v152 offset:1024
	ds_read_b128 v[174:177], v152 offset:2048
	ds_read_b128 v[182:185], v152 offset:3072
	s_add_i32 s71, s22, 2
	s_add_u32 s23, s20, 0xffea0080
	s_addc_u32 s26, s21, -1
	s_cmp_eq_u32 s68, s22
	s_cselect_b32 s22, s18, s69
	s_cselect_b32 s27, s17, s26
	s_cselect_b32 s26, s16, s23
	s_cselect_b32 s23, s19, s70
	v_lshl_add_u64 v[218:219], s[20:21], 0, v[138:139]
	s_add_i32 m0, s35, 0xc000
	ds_read_b128 v[186:189], v153
	ds_read_b128 v[190:193], v153 offset:1024
	ds_read_b128 v[194:197], v153 offset:2048
	ds_read_b128 v[198:201], v153 offset:3072
	ds_read_b128 v[202:205], v153 offset:4096
	ds_read_b128 v[206:209], v153 offset:5120
	ds_read_b128 v[210:213], v153 offset:6144
	ds_read_b128 v[214:217], v153 offset:7168
	global_load_lds_dwordx4 v[218:219], off
	v_lshl_add_u64 v[218:219], s[20:21], 0, v[140:141]
	s_add_i32 m0, s35, 0xe000
	s_nop 0
	global_load_lds_dwordx4 v[218:219], off
	s_waitcnt vmcnt(8)
	s_waitcnt lgkmcnt(0)
	s_setprio 1
	s_barrier
	v_mfma_f32_16x16x32_bf16 v[126:129], v[144:147], v[186:189], v[126:129]
	v_mfma_f32_16x16x32_bf16 v[126:129], v[154:157], v[190:193], v[126:129]
	v_mfma_f32_16x16x32_bf16 v[122:125], v[158:161], v[186:189], v[122:125]
	v_mfma_f32_16x16x32_bf16 v[122:125], v[162:165], v[190:193], v[122:125]
	v_mfma_f32_16x16x32_bf16 v[118:121], v[144:147], v[194:197], v[118:121]
	v_mfma_f32_16x16x32_bf16 v[118:121], v[154:157], v[198:201], v[118:121]
	v_mfma_f32_16x16x32_bf16 v[114:117], v[158:161], v[194:197], v[114:117]
	v_mfma_f32_16x16x32_bf16 v[114:117], v[162:165], v[198:201], v[114:117]
	v_mfma_f32_16x16x32_bf16 v[106:109], v[144:147], v[202:205], v[106:109]
	v_mfma_f32_16x16x32_bf16 v[106:109], v[154:157], v[206:209], v[106:109]
	v_mfma_f32_16x16x32_bf16 v[98:101], v[158:161], v[202:205], v[98:101]
	v_mfma_f32_16x16x32_bf16 v[98:101], v[162:165], v[206:209], v[98:101]
	v_mfma_f32_16x16x32_bf16 v[90:93], v[144:147], v[210:213], v[90:93]
	v_mfma_f32_16x16x32_bf16 v[90:93], v[154:157], v[214:217], v[90:93]
	v_mfma_f32_16x16x32_bf16 v[82:85], v[158:161], v[210:213], v[82:85]
	v_mfma_f32_16x16x32_bf16 v[82:85], v[162:165], v[214:217], v[82:85]
	v_mfma_f32_16x16x32_bf16 v[110:113], v[166:169], v[186:189], v[110:113]
	v_mfma_f32_16x16x32_bf16 v[110:113], v[170:173], v[190:193], v[110:113]
	v_mfma_f32_16x16x32_bf16 v[102:105], v[174:177], v[186:189], v[102:105]
	v_mfma_f32_16x16x32_bf16 v[102:105], v[182:185], v[190:193], v[102:105]
	v_mfma_f32_16x16x32_bf16 v[94:97], v[166:169], v[194:197], v[94:97]
	v_mfma_f32_16x16x32_bf16 v[94:97], v[170:173], v[198:201], v[94:97]
	v_mfma_f32_16x16x32_bf16 v[86:89], v[174:177], v[194:197], v[86:89]
	v_mfma_f32_16x16x32_bf16 v[86:89], v[182:185], v[198:201], v[86:89]
	v_mfma_f32_16x16x32_bf16 v[78:81], v[166:169], v[202:205], v[78:81]
	v_mfma_f32_16x16x32_bf16 v[78:81], v[170:173], v[206:209], v[78:81]
	v_mfma_f32_16x16x32_bf16 v[74:77], v[174:177], v[202:205], v[74:77]
	v_mfma_f32_16x16x32_bf16 v[74:77], v[182:185], v[206:209], v[74:77]
	v_mfma_f32_16x16x32_bf16 v[70:73], v[166:169], v[210:213], v[70:73]
	v_mfma_f32_16x16x32_bf16 v[70:73], v[170:173], v[214:217], v[70:73]
	v_mfma_f32_16x16x32_bf16 v[66:69], v[174:177], v[210:213], v[66:69]
	v_mfma_f32_16x16x32_bf16 v[66:69], v[182:185], v[214:217], v[66:69]
	s_barrier
	s_setprio 0
	s_add_i32 s72, s52, s31
	v_lshl_add_u64 v[218:219], s[22:23], 0, v[132:133]
	s_mov_b32 m0, s72
	ds_read_b128 v[186:189], v153 offset:16384
	ds_read_b128 v[190:193], v153 offset:17408
	ds_read_b128 v[194:197], v153 offset:18432
	ds_read_b128 v[198:201], v153 offset:19456
	ds_read_b128 v[202:205], v153 offset:20480
	ds_read_b128 v[206:209], v153 offset:21504
	ds_read_b128 v[210:213], v153 offset:22528
	ds_read_b128 v[214:217], v153 offset:23552
	global_load_lds_dwordx4 v[218:219], off
	s_add_i32 m0, s72, 0x2000
	s_add_u32 s72, s22, 0x160000
	v_lshl_add_u64 v[220:221], s[22:23], 0, v[136:137]
	s_addc_u32 s73, s23, 0
	s_add_i32 s76, s53, s31
	global_load_lds_dwordx4 v[220:221], off
	v_lshl_add_u64 v[222:223], s[72:73], 0, v[132:133]
	s_mov_b32 m0, s76
	v_lshl_add_u64 v[224:225], s[26:27], 0, v[134:135]
	global_load_lds_dwordx4 v[222:223], off
	v_lshl_add_u64 v[222:223], s[72:73], 0, v[136:137]
	s_add_i32 m0, s76, 0x2000
	s_nop 0
	global_load_lds_dwordx4 v[222:223], off
	v_lshl_add_u64 v[222:223], s[26:27], 0, v[130:131]
	s_mov_b32 m0, s35
	s_nop 0
	global_load_lds_dwordx4 v[222:223], off
	s_mov_b32 m0, s36
	s_nop 0
	global_load_lds_dwordx4 v[224:225], off
	s_waitcnt vmcnt(8)
	s_waitcnt lgkmcnt(0)
	s_setprio 1
	s_barrier
	v_mfma_f32_16x16x32_bf16 v[62:65], v[144:147], v[186:189], v[62:65]
	v_mfma_f32_16x16x32_bf16 v[62:65], v[154:157], v[190:193], v[62:65]
	v_mfma_f32_16x16x32_bf16 v[58:61], v[158:161], v[186:189], v[58:61]
	v_mfma_f32_16x16x32_bf16 v[58:61], v[162:165], v[190:193], v[58:61]
	v_mfma_f32_16x16x32_bf16 v[54:57], v[144:147], v[194:197], v[54:57]
	v_mfma_f32_16x16x32_bf16 v[54:57], v[154:157], v[198:201], v[54:57]
	v_mfma_f32_16x16x32_bf16 v[50:53], v[158:161], v[194:197], v[50:53]
	v_mfma_f32_16x16x32_bf16 v[50:53], v[162:165], v[198:201], v[50:53]
	v_mfma_f32_16x16x32_bf16 v[42:45], v[144:147], v[202:205], v[42:45]
	v_mfma_f32_16x16x32_bf16 v[42:45], v[154:157], v[206:209], v[42:45]
	v_mfma_f32_16x16x32_bf16 v[34:37], v[158:161], v[202:205], v[34:37]
	v_mfma_f32_16x16x32_bf16 v[34:37], v[162:165], v[206:209], v[34:37]
	v_mfma_f32_16x16x32_bf16 v[26:29], v[144:147], v[210:213], v[26:29]
	v_mfma_f32_16x16x32_bf16 v[26:29], v[154:157], v[214:217], v[26:29]
	v_mfma_f32_16x16x32_bf16 v[18:21], v[158:161], v[210:213], v[18:21]
	v_mfma_f32_16x16x32_bf16 v[18:21], v[162:165], v[214:217], v[18:21]
	v_mfma_f32_16x16x32_bf16 v[46:49], v[166:169], v[186:189], v[46:49]
	v_mfma_f32_16x16x32_bf16 v[46:49], v[170:173], v[190:193], v[46:49]
	v_mfma_f32_16x16x32_bf16 v[38:41], v[174:177], v[186:189], v[38:41]
	v_mfma_f32_16x16x32_bf16 v[38:41], v[182:185], v[190:193], v[38:41]
	v_mfma_f32_16x16x32_bf16 v[30:33], v[166:169], v[194:197], v[30:33]
	v_mfma_f32_16x16x32_bf16 v[30:33], v[170:173], v[198:201], v[30:33]
	v_mfma_f32_16x16x32_bf16 v[22:25], v[174:177], v[194:197], v[22:25]
	v_mfma_f32_16x16x32_bf16 v[22:25], v[182:185], v[198:201], v[22:25]
	v_mfma_f32_16x16x32_bf16 v[14:17], v[166:169], v[202:205], v[14:17]
	v_mfma_f32_16x16x32_bf16 v[14:17], v[170:173], v[206:209], v[14:17]
	v_mfma_f32_16x16x32_bf16 v[10:13], v[174:177], v[202:205], v[10:13]
	v_mfma_f32_16x16x32_bf16 v[10:13], v[182:185], v[206:209], v[10:13]
	v_mfma_f32_16x16x32_bf16 v[6:9], v[166:169], v[210:213], v[6:9]
	v_mfma_f32_16x16x32_bf16 v[6:9], v[170:173], v[214:217], v[6:9]
	v_mfma_f32_16x16x32_bf16 v[2:5], v[174:177], v[210:213], v[2:5]
	v_mfma_f32_16x16x32_bf16 v[2:5], v[182:185], v[214:217], v[2:5]
	s_barrier
	s_setprio 0
	s_add_i32 s72, 0, 0x18000
	s_add_i32 s73, 0, 0x1c000
	v_add_u32_e32 v162, s72, v149
	v_add_u32_e32 v179, s73, v149
	ds_read_b128 v[144:147], v162
	ds_read_b128 v[154:157], v162 offset:1024
	ds_read_b128 v[158:161], v162 offset:2048
	ds_read_b128 v[162:165], v162 offset:3072
	ds_read_b128 v[166:169], v179
	ds_read_b128 v[170:173], v179 offset:1024
	ds_read_b128 v[174:177], v179 offset:2048
	ds_read_b128 v[182:185], v179 offset:3072
	s_add_u32 s26, s26, 0x160000
	s_addc_u32 s27, s27, 0
	s_mov_b32 m0, s37
	v_lshl_add_u64 v[226:227], s[26:27], 0, v[130:131]
	ds_read_b128 v[186:189], v153 offset:32768
	ds_read_b128 v[190:193], v153 offset:33792
	ds_read_b128 v[194:197], v153 offset:34816
	ds_read_b128 v[198:201], v153 offset:35840
	ds_read_b128 v[202:205], v153 offset:36864
	ds_read_b128 v[206:209], v153 offset:37888
	ds_read_b128 v[210:213], v153 offset:38912
	ds_read_b128 v[214:217], v153 offset:39936
	global_load_lds_dwordx4 v[226:227], off
	v_lshl_add_u64 v[226:227], s[26:27], 0, v[134:135]
	s_mov_b32 m0, s38
	s_nop 0
	global_load_lds_dwordx4 v[226:227], off
	s_waitcnt vmcnt(8)
	s_waitcnt lgkmcnt(0)
	s_setprio 1
	s_barrier
	v_mfma_f32_16x16x32_bf16 v[126:129], v[144:147], v[186:189], v[126:129]
	v_mfma_f32_16x16x32_bf16 v[126:129], v[154:157], v[190:193], v[126:129]
	v_mfma_f32_16x16x32_bf16 v[122:125], v[158:161], v[186:189], v[122:125]
	v_mfma_f32_16x16x32_bf16 v[122:125], v[162:165], v[190:193], v[122:125]
	v_mfma_f32_16x16x32_bf16 v[118:121], v[144:147], v[194:197], v[118:121]
	v_mfma_f32_16x16x32_bf16 v[118:121], v[154:157], v[198:201], v[118:121]
	v_mfma_f32_16x16x32_bf16 v[114:117], v[158:161], v[194:197], v[114:117]
	v_mfma_f32_16x16x32_bf16 v[114:117], v[162:165], v[198:201], v[114:117]
	v_mfma_f32_16x16x32_bf16 v[106:109], v[144:147], v[202:205], v[106:109]
	v_mfma_f32_16x16x32_bf16 v[106:109], v[154:157], v[206:209], v[106:109]
	v_mfma_f32_16x16x32_bf16 v[98:101], v[158:161], v[202:205], v[98:101]
	v_mfma_f32_16x16x32_bf16 v[98:101], v[162:165], v[206:209], v[98:101]
	v_mfma_f32_16x16x32_bf16 v[90:93], v[144:147], v[210:213], v[90:93]
	v_mfma_f32_16x16x32_bf16 v[90:93], v[154:157], v[214:217], v[90:93]
	v_mfma_f32_16x16x32_bf16 v[82:85], v[158:161], v[210:213], v[82:85]
	v_mfma_f32_16x16x32_bf16 v[82:85], v[162:165], v[214:217], v[82:85]
	v_mfma_f32_16x16x32_bf16 v[110:113], v[166:169], v[186:189], v[110:113]
	v_mfma_f32_16x16x32_bf16 v[110:113], v[170:173], v[190:193], v[110:113]
	v_mfma_f32_16x16x32_bf16 v[102:105], v[174:177], v[186:189], v[102:105]
	v_mfma_f32_16x16x32_bf16 v[102:105], v[182:185], v[190:193], v[102:105]
	v_mfma_f32_16x16x32_bf16 v[94:97], v[166:169], v[194:197], v[94:97]
	v_mfma_f32_16x16x32_bf16 v[94:97], v[170:173], v[198:201], v[94:97]
	v_mfma_f32_16x16x32_bf16 v[86:89], v[174:177], v[194:197], v[86:89]
	v_mfma_f32_16x16x32_bf16 v[86:89], v[182:185], v[198:201], v[86:89]
	v_mfma_f32_16x16x32_bf16 v[78:81], v[166:169], v[202:205], v[78:81]
	v_mfma_f32_16x16x32_bf16 v[78:81], v[170:173], v[206:209], v[78:81]
	v_mfma_f32_16x16x32_bf16 v[74:77], v[174:177], v[202:205], v[74:77]
	v_mfma_f32_16x16x32_bf16 v[74:77], v[182:185], v[206:209], v[74:77]
	v_mfma_f32_16x16x32_bf16 v[70:73], v[166:169], v[210:213], v[70:73]
	v_mfma_f32_16x16x32_bf16 v[70:73], v[170:173], v[214:217], v[70:73]
	v_mfma_f32_16x16x32_bf16 v[66:69], v[174:177], v[210:213], v[66:69]
	v_mfma_f32_16x16x32_bf16 v[66:69], v[182:185], v[214:217], v[66:69]
	s_barrier
	s_setprio 0
	s_add_i32 s26, s72, s31
	v_lshl_add_u64 v[218:219], v[218:219], 0, s[4:5]
	s_mov_b32 m0, s26
	ds_read_b128 v[186:189], v153 offset:49152
	ds_read_b128 v[190:193], v153 offset:50176
	ds_read_b128 v[194:197], v153 offset:51200
	ds_read_b128 v[198:201], v153 offset:52224
	ds_read_b128 v[202:205], v153 offset:53248
	ds_read_b128 v[206:209], v153 offset:54272
	ds_read_b128 v[210:213], v153 offset:55296
	ds_read_b128 v[214:217], v153 offset:56320
	global_load_lds_dwordx4 v[218:219], off
	s_add_i32 m0, s26, 0x2000
	s_add_u32 s22, s22, 0x160080
	v_lshl_add_u64 v[218:219], v[220:221], 0, s[4:5]
	s_addc_u32 s23, s23, 0
	s_add_i32 s26, s73, s31
	global_load_lds_dwordx4 v[218:219], off
	v_lshl_add_u64 v[218:219], s[22:23], 0, v[132:133]
	s_mov_b32 m0, s26
	s_nop 0
	global_load_lds_dwordx4 v[218:219], off
	v_lshl_add_u64 v[218:219], s[22:23], 0, v[136:137]
	s_add_i32 m0, s26, 0x2000
	s_nop 0
	global_load_lds_dwordx4 v[218:219], off
	v_lshl_add_u64 v[218:219], v[222:223], 0, s[4:5]
	s_mov_b32 m0, s42
	s_nop 0
	global_load_lds_dwordx4 v[218:219], off
	v_lshl_add_u64 v[218:219], v[224:225], 0, s[4:5]
	s_mov_b32 m0, s43
	s_nop 0
	global_load_lds_dwordx4 v[218:219], off
	s_waitcnt vmcnt(8)
	s_waitcnt lgkmcnt(0)
	s_setprio 1
	s_barrier
	v_mfma_f32_16x16x32_bf16 v[62:65], v[144:147], v[186:189], v[62:65]
	v_mfma_f32_16x16x32_bf16 v[62:65], v[154:157], v[190:193], v[62:65]
	v_mfma_f32_16x16x32_bf16 v[58:61], v[158:161], v[186:189], v[58:61]
	v_mfma_f32_16x16x32_bf16 v[58:61], v[162:165], v[190:193], v[58:61]
	v_mfma_f32_16x16x32_bf16 v[54:57], v[144:147], v[194:197], v[54:57]
	v_mfma_f32_16x16x32_bf16 v[54:57], v[154:157], v[198:201], v[54:57]
	v_mfma_f32_16x16x32_bf16 v[50:53], v[158:161], v[194:197], v[50:53]
	v_mfma_f32_16x16x32_bf16 v[50:53], v[162:165], v[198:201], v[50:53]
	v_mfma_f32_16x16x32_bf16 v[42:45], v[144:147], v[202:205], v[42:45]
	v_mfma_f32_16x16x32_bf16 v[42:45], v[154:157], v[206:209], v[42:45]
	v_mfma_f32_16x16x32_bf16 v[34:37], v[158:161], v[202:205], v[34:37]
	v_mfma_f32_16x16x32_bf16 v[34:37], v[162:165], v[206:209], v[34:37]
	v_mfma_f32_16x16x32_bf16 v[26:29], v[144:147], v[210:213], v[26:29]
	v_mfma_f32_16x16x32_bf16 v[26:29], v[154:157], v[214:217], v[26:29]
	v_mfma_f32_16x16x32_bf16 v[18:21], v[158:161], v[210:213], v[18:21]
	v_mfma_f32_16x16x32_bf16 v[18:21], v[162:165], v[214:217], v[18:21]
	v_mfma_f32_16x16x32_bf16 v[46:49], v[166:169], v[186:189], v[46:49]
	v_mfma_f32_16x16x32_bf16 v[46:49], v[170:173], v[190:193], v[46:49]
	v_mfma_f32_16x16x32_bf16 v[38:41], v[174:177], v[186:189], v[38:41]
	v_mfma_f32_16x16x32_bf16 v[38:41], v[182:185], v[190:193], v[38:41]
	v_mfma_f32_16x16x32_bf16 v[30:33], v[166:169], v[194:197], v[30:33]
	v_mfma_f32_16x16x32_bf16 v[30:33], v[170:173], v[198:201], v[30:33]
	v_mfma_f32_16x16x32_bf16 v[22:25], v[174:177], v[194:197], v[22:25]
	v_mfma_f32_16x16x32_bf16 v[22:25], v[182:185], v[198:201], v[22:25]
	v_mfma_f32_16x16x32_bf16 v[14:17], v[166:169], v[202:205], v[14:17]
	v_mfma_f32_16x16x32_bf16 v[14:17], v[170:173], v[206:209], v[14:17]
	v_mfma_f32_16x16x32_bf16 v[10:13], v[174:177], v[202:205], v[10:13]
	v_mfma_f32_16x16x32_bf16 v[10:13], v[182:185], v[206:209], v[10:13]
	v_mfma_f32_16x16x32_bf16 v[6:9], v[166:169], v[210:213], v[6:9]
	v_mfma_f32_16x16x32_bf16 v[6:9], v[170:173], v[214:217], v[6:9]
	v_mfma_f32_16x16x32_bf16 v[2:5], v[174:177], v[210:213], v[2:5]
	v_mfma_f32_16x16x32_bf16 v[2:5], v[182:185], v[214:217], v[2:5]
	s_barrier
	s_setprio 0
	s_add_u32 s20, s20, 0x100
	s_addc_u32 s21, s21, 0
	s_add_u32 s69, s69, 0x100
	s_addc_u32 s70, s70, 0
	s_cmp_ge_i32 s71, s67
	s_mov_b32 s22, s71
	s_cbranch_scc0 .LBB0_2565
	s_and_b64 vcc, exec, s[6:7]
	s_cbranch_vccz .LBB0_2568
	s_barrier

.LBB0_2731:
	ds_read_b128 v[146:149], v162
	ds_read_b128 v[150:153], v162 offset:1024
	ds_read_b128 v[166:169], v162 offset:2048
	ds_read_b128 v[170:173], v162 offset:3072
	ds_read_b128 v[174:177], v163
	ds_read_b128 v[182:185], v163 offset:1024
	ds_read_b128 v[186:189], v163 offset:2048
	ds_read_b128 v[190:193], v163 offset:3072
	s_add_u32 s24, s4, 0xfff80080
	s_addc_u32 s25, s5, -1
	s_cmp_eq_u32 s55, 28
	s_cselect_b32 s27, s15, s25
	s_cselect_b32 s26, s47, s24
	s_cselect_b32 s25, s13, s54
	s_cselect_b32 s24, s52, s53
	v_lshl_add_u64 v[226:227], s[4:5], 0, v[138:139]
	s_add_i32 m0, s21, 0xc000
	ds_read_b128 v[194:197], v164
	ds_read_b128 v[198:201], v164 offset:1024
	ds_read_b128 v[202:205], v164 offset:2048
	ds_read_b128 v[206:209], v164 offset:3072
	ds_read_b128 v[210:213], v164 offset:4096
	ds_read_b128 v[214:217], v164 offset:5120
	ds_read_b128 v[218:221], v164 offset:6144
	ds_read_b128 v[222:225], v164 offset:7168
	global_load_lds_dwordx4 v[226:227], off
	v_lshl_add_u64 v[226:227], s[4:5], 0, v[140:141]
	s_add_i32 m0, s21, 0xe000
	s_nop 0
	global_load_lds_dwordx4 v[226:227], off
	s_waitcnt vmcnt(8)
	s_waitcnt lgkmcnt(0)
	s_setprio 1
	s_barrier
	v_mfma_f32_16x16x32_bf16 v[126:129], v[146:149], v[194:197], v[126:129]
	v_mfma_f32_16x16x32_bf16 v[126:129], v[150:153], v[198:201], v[126:129]
	v_mfma_f32_16x16x32_bf16 v[122:125], v[166:169], v[194:197], v[122:125]
	v_mfma_f32_16x16x32_bf16 v[122:125], v[170:173], v[198:201], v[122:125]
	v_mfma_f32_16x16x32_bf16 v[110:113], v[146:149], v[202:205], v[110:113]
	v_mfma_f32_16x16x32_bf16 v[110:113], v[150:153], v[206:209], v[110:113]
	v_mfma_f32_16x16x32_bf16 v[106:109], v[166:169], v[202:205], v[106:109]
	v_mfma_f32_16x16x32_bf16 v[106:109], v[170:173], v[206:209], v[106:109]
	v_mfma_f32_16x16x32_bf16 v[94:97], v[146:149], v[210:213], v[94:97]
	v_mfma_f32_16x16x32_bf16 v[94:97], v[150:153], v[214:217], v[94:97]
	v_mfma_f32_16x16x32_bf16 v[90:93], v[166:169], v[210:213], v[90:93]
	v_mfma_f32_16x16x32_bf16 v[90:93], v[170:173], v[214:217], v[90:93]
	v_mfma_f32_16x16x32_bf16 v[78:81], v[146:149], v[218:221], v[78:81]
	v_mfma_f32_16x16x32_bf16 v[78:81], v[150:153], v[222:225], v[78:81]
	v_mfma_f32_16x16x32_bf16 v[74:77], v[166:169], v[218:221], v[74:77]
	v_mfma_f32_16x16x32_bf16 v[74:77], v[170:173], v[222:225], v[74:77]
	v_mfma_f32_16x16x32_bf16 v[118:121], v[174:177], v[194:197], v[118:121]
	v_mfma_f32_16x16x32_bf16 v[118:121], v[182:185], v[198:201], v[118:121]
	v_mfma_f32_16x16x32_bf16 v[114:117], v[186:189], v[194:197], v[114:117]
	v_mfma_f32_16x16x32_bf16 v[114:117], v[190:193], v[198:201], v[114:117]
	v_mfma_f32_16x16x32_bf16 v[102:105], v[174:177], v[202:205], v[102:105]
	v_mfma_f32_16x16x32_bf16 v[102:105], v[182:185], v[206:209], v[102:105]
	v_mfma_f32_16x16x32_bf16 v[98:101], v[186:189], v[202:205], v[98:101]
	v_mfma_f32_16x16x32_bf16 v[98:101], v[190:193], v[206:209], v[98:101]
	v_mfma_f32_16x16x32_bf16 v[86:89], v[174:177], v[210:213], v[86:89]
	v_mfma_f32_16x16x32_bf16 v[86:89], v[182:185], v[214:217], v[86:89]
	v_mfma_f32_16x16x32_bf16 v[82:85], v[186:189], v[210:213], v[82:85]
	v_mfma_f32_16x16x32_bf16 v[82:85], v[190:193], v[214:217], v[82:85]
	v_mfma_f32_16x16x32_bf16 v[70:73], v[174:177], v[218:221], v[70:73]
	v_mfma_f32_16x16x32_bf16 v[70:73], v[182:185], v[222:225], v[70:73]
	v_mfma_f32_16x16x32_bf16 v[66:69], v[186:189], v[218:221], v[66:69]
	v_mfma_f32_16x16x32_bf16 v[66:69], v[190:193], v[222:225], v[66:69]
	s_barrier
	s_setprio 0
	s_add_i32 s56, s44, s30
	v_lshl_add_u64 v[226:227], s[24:25], 0, v[132:133]
	s_mov_b32 m0, s56
	ds_read_b128 v[194:197], v164 offset:16384
	ds_read_b128 v[198:201], v164 offset:17408
	ds_read_b128 v[202:205], v164 offset:18432
	ds_read_b128 v[206:209], v164 offset:19456
	ds_read_b128 v[210:213], v164 offset:20480
	ds_read_b128 v[214:217], v164 offset:21504
	ds_read_b128 v[218:221], v164 offset:22528
	ds_read_b128 v[222:225], v164 offset:23552
	global_load_lds_dwordx4 v[226:227], off
	s_add_i32 m0, s56, 0x2000
	s_add_u32 s56, s24, 0x80000
	v_lshl_add_u64 v[228:229], s[24:25], 0, v[136:137]
	s_addc_u32 s57, s25, 0
	s_add_i32 s58, s45, s30
	global_load_lds_dwordx4 v[228:229], off
	v_lshl_add_u64 v[230:231], s[56:57], 0, v[132:133]
	s_mov_b32 m0, s58
	v_lshl_add_u64 v[232:233], s[26:27], 0, v[134:135]
	global_load_lds_dwordx4 v[230:231], off
	v_lshl_add_u64 v[230:231], s[56:57], 0, v[136:137]
	s_add_i32 m0, s58, 0x2000
	s_nop 0
	global_load_lds_dwordx4 v[230:231], off
	v_lshl_add_u64 v[230:231], s[26:27], 0, v[130:131]
	s_mov_b32 m0, s21
	s_nop 0
	global_load_lds_dwordx4 v[230:231], off
	s_mov_b32 m0, s23
	s_nop 0
	global_load_lds_dwordx4 v[232:233], off
	s_waitcnt vmcnt(8)
	s_waitcnt lgkmcnt(0)
	s_setprio 1
	s_barrier
	v_mfma_f32_16x16x32_bf16 v[62:65], v[146:149], v[194:197], v[62:65]
	v_mfma_f32_16x16x32_bf16 v[62:65], v[150:153], v[198:201], v[62:65]
	v_mfma_f32_16x16x32_bf16 v[58:61], v[166:169], v[194:197], v[58:61]
	v_mfma_f32_16x16x32_bf16 v[58:61], v[170:173], v[198:201], v[58:61]
	v_mfma_f32_16x16x32_bf16 v[46:49], v[146:149], v[202:205], v[46:49]
	v_mfma_f32_16x16x32_bf16 v[46:49], v[150:153], v[206:209], v[46:49]
	v_mfma_f32_16x16x32_bf16 v[42:45], v[166:169], v[202:205], v[42:45]
	v_mfma_f32_16x16x32_bf16 v[42:45], v[170:173], v[206:209], v[42:45]
	v_mfma_f32_16x16x32_bf16 v[30:33], v[146:149], v[210:213], v[30:33]
	v_mfma_f32_16x16x32_bf16 v[30:33], v[150:153], v[214:217], v[30:33]
	v_mfma_f32_16x16x32_bf16 v[26:29], v[166:169], v[210:213], v[26:29]
	v_mfma_f32_16x16x32_bf16 v[26:29], v[170:173], v[214:217], v[26:29]
	v_mfma_f32_16x16x32_bf16 v[14:17], v[146:149], v[218:221], v[14:17]
	v_mfma_f32_16x16x32_bf16 v[14:17], v[150:153], v[222:225], v[14:17]
	v_mfma_f32_16x16x32_bf16 v[10:13], v[166:169], v[218:221], v[10:13]
	v_mfma_f32_16x16x32_bf16 v[10:13], v[170:173], v[222:225], v[10:13]
	v_mfma_f32_16x16x32_bf16 v[54:57], v[174:177], v[194:197], v[54:57]
	v_mfma_f32_16x16x32_bf16 v[54:57], v[182:185], v[198:201], v[54:57]
	v_mfma_f32_16x16x32_bf16 v[50:53], v[186:189], v[194:197], v[50:53]
	v_mfma_f32_16x16x32_bf16 v[50:53], v[190:193], v[198:201], v[50:53]
	v_mfma_f32_16x16x32_bf16 v[38:41], v[174:177], v[202:205], v[38:41]
	v_mfma_f32_16x16x32_bf16 v[38:41], v[182:185], v[206:209], v[38:41]
	v_mfma_f32_16x16x32_bf16 v[34:37], v[186:189], v[202:205], v[34:37]
	v_mfma_f32_16x16x32_bf16 v[34:37], v[190:193], v[206:209], v[34:37]
	v_mfma_f32_16x16x32_bf16 v[22:25], v[174:177], v[210:213], v[22:25]
	v_mfma_f32_16x16x32_bf16 v[22:25], v[182:185], v[214:217], v[22:25]
	v_mfma_f32_16x16x32_bf16 v[18:21], v[186:189], v[210:213], v[18:21]
	v_mfma_f32_16x16x32_bf16 v[18:21], v[190:193], v[214:217], v[18:21]
	v_mfma_f32_16x16x32_bf16 v[6:9], v[174:177], v[218:221], v[6:9]
	v_mfma_f32_16x16x32_bf16 v[6:9], v[182:185], v[222:225], v[6:9]
	v_mfma_f32_16x16x32_bf16 v[2:5], v[186:189], v[218:221], v[2:5]
	v_mfma_f32_16x16x32_bf16 v[2:5], v[190:193], v[222:225], v[2:5]
	s_barrier
	s_setprio 0
	s_add_i32 s56, 0, 0x18000
	s_add_i32 s57, 0, 0x1c000
	v_add_u32_e32 v170, s56, v156
	v_add_u32_e32 v179, s57, v156
	ds_read_b128 v[146:149], v170
	ds_read_b128 v[150:153], v170 offset:1024
	ds_read_b128 v[166:169], v170 offset:2048
	ds_read_b128 v[170:173], v170 offset:3072
	ds_read_b128 v[174:177], v179
	ds_read_b128 v[182:185], v179 offset:1024
	ds_read_b128 v[186:189], v179 offset:2048
	ds_read_b128 v[190:193], v179 offset:3072
	s_add_u32 s26, s26, 0x80000
	s_addc_u32 s27, s27, 0
	s_mov_b32 m0, s31
	v_lshl_add_u64 v[234:235], s[26:27], 0, v[130:131]
	ds_read_b128 v[194:197], v164 offset:32768
	ds_read_b128 v[198:201], v164 offset:33792
	ds_read_b128 v[202:205], v164 offset:34816
	ds_read_b128 v[206:209], v164 offset:35840
	ds_read_b128 v[210:213], v164 offset:36864
	ds_read_b128 v[214:217], v164 offset:37888
	ds_read_b128 v[218:221], v164 offset:38912
	ds_read_b128 v[222:225], v164 offset:39936
	global_load_lds_dwordx4 v[234:235], off
	v_lshl_add_u64 v[234:235], s[26:27], 0, v[134:135]
	s_mov_b32 m0, s34
	s_nop 0
	global_load_lds_dwordx4 v[234:235], off
	s_waitcnt vmcnt(8)
	s_waitcnt lgkmcnt(0)
	s_setprio 1
	s_barrier
	v_mfma_f32_16x16x32_bf16 v[126:129], v[146:149], v[194:197], v[126:129]
	v_mfma_f32_16x16x32_bf16 v[126:129], v[150:153], v[198:201], v[126:129]
	v_mfma_f32_16x16x32_bf16 v[122:125], v[166:169], v[194:197], v[122:125]
	v_mfma_f32_16x16x32_bf16 v[122:125], v[170:173], v[198:201], v[122:125]
	v_mfma_f32_16x16x32_bf16 v[110:113], v[146:149], v[202:205], v[110:113]
	v_mfma_f32_16x16x32_bf16 v[110:113], v[150:153], v[206:209], v[110:113]
	v_mfma_f32_16x16x32_bf16 v[106:109], v[166:169], v[202:205], v[106:109]
	v_mfma_f32_16x16x32_bf16 v[106:109], v[170:173], v[206:209], v[106:109]
	v_mfma_f32_16x16x32_bf16 v[94:97], v[146:149], v[210:213], v[94:97]
	v_mfma_f32_16x16x32_bf16 v[94:97], v[150:153], v[214:217], v[94:97]
	v_mfma_f32_16x16x32_bf16 v[90:93], v[166:169], v[210:213], v[90:93]
	v_mfma_f32_16x16x32_bf16 v[90:93], v[170:173], v[214:217], v[90:93]
	v_mfma_f32_16x16x32_bf16 v[78:81], v[146:149], v[218:221], v[78:81]
	v_mfma_f32_16x16x32_bf16 v[78:81], v[150:153], v[222:225], v[78:81]
	v_mfma_f32_16x16x32_bf16 v[74:77], v[166:169], v[218:221], v[74:77]
	v_mfma_f32_16x16x32_bf16 v[74:77], v[170:173], v[222:225], v[74:77]
	v_mfma_f32_16x16x32_bf16 v[118:121], v[174:177], v[194:197], v[118:121]
	v_mfma_f32_16x16x32_bf16 v[118:121], v[182:185], v[198:201], v[118:121]
	v_mfma_f32_16x16x32_bf16 v[114:117], v[186:189], v[194:197], v[114:117]
	v_mfma_f32_16x16x32_bf16 v[114:117], v[190:193], v[198:201], v[114:117]
	v_mfma_f32_16x16x32_bf16 v[102:105], v[174:177], v[202:205], v[102:105]
	v_mfma_f32_16x16x32_bf16 v[102:105], v[182:185], v[206:209], v[102:105]
	v_mfma_f32_16x16x32_bf16 v[98:101], v[186:189], v[202:205], v[98:101]
	v_mfma_f32_16x16x32_bf16 v[98:101], v[190:193], v[206:209], v[98:101]
	v_mfma_f32_16x16x32_bf16 v[86:89], v[174:177], v[210:213], v[86:89]
	v_mfma_f32_16x16x32_bf16 v[86:89], v[182:185], v[214:217], v[86:89]
	v_mfma_f32_16x16x32_bf16 v[82:85], v[186:189], v[210:213], v[82:85]
	v_mfma_f32_16x16x32_bf16 v[82:85], v[190:193], v[214:217], v[82:85]
	v_mfma_f32_16x16x32_bf16 v[70:73], v[174:177], v[218:221], v[70:73]
	v_mfma_f32_16x16x32_bf16 v[70:73], v[182:185], v[222:225], v[70:73]
	v_mfma_f32_16x16x32_bf16 v[66:69], v[186:189], v[218:221], v[66:69]
	v_mfma_f32_16x16x32_bf16 v[66:69], v[190:193], v[222:225], v[66:69]
	s_barrier
	s_setprio 0
	s_add_i32 s26, s56, s30
	v_lshl_add_u64 v[226:227], v[226:227], 0, s[8:9]
	s_mov_b32 m0, s26
	ds_read_b128 v[194:197], v164 offset:49152
	ds_read_b128 v[198:201], v164 offset:50176
	ds_read_b128 v[202:205], v164 offset:51200
	ds_read_b128 v[206:209], v164 offset:52224
	ds_read_b128 v[210:213], v164 offset:53248
	ds_read_b128 v[214:217], v164 offset:54272
	ds_read_b128 v[218:221], v164 offset:55296
	ds_read_b128 v[222:225], v164 offset:56320
	global_load_lds_dwordx4 v[226:227], off
	s_add_i32 m0, s26, 0x2000
	s_add_u32 s24, s24, 0x80080
	v_lshl_add_u64 v[226:227], v[228:229], 0, s[8:9]
	s_addc_u32 s25, s25, 0
	s_add_i32 s26, s57, s30
	global_load_lds_dwordx4 v[226:227], off
	v_lshl_add_u64 v[226:227], s[24:25], 0, v[132:133]
	s_mov_b32 m0, s26
	s_nop 0
	global_load_lds_dwordx4 v[226:227], off
	v_lshl_add_u64 v[226:227], s[24:25], 0, v[136:137]
	s_add_i32 m0, s26, 0x2000
	s_nop 0
	global_load_lds_dwordx4 v[226:227], off
	v_lshl_add_u64 v[226:227], v[230:231], 0, s[8:9]
	s_mov_b32 m0, s36
	s_nop 0
	global_load_lds_dwordx4 v[226:227], off
	v_lshl_add_u64 v[226:227], v[232:233], 0, s[8:9]
	s_mov_b32 m0, s37
	s_nop 0
	global_load_lds_dwordx4 v[226:227], off
	s_waitcnt vmcnt(8)
	s_waitcnt lgkmcnt(0)
	s_setprio 1
	s_barrier
	v_mfma_f32_16x16x32_bf16 v[62:65], v[146:149], v[194:197], v[62:65]
	v_mfma_f32_16x16x32_bf16 v[62:65], v[150:153], v[198:201], v[62:65]
	v_mfma_f32_16x16x32_bf16 v[58:61], v[166:169], v[194:197], v[58:61]
	v_mfma_f32_16x16x32_bf16 v[58:61], v[170:173], v[198:201], v[58:61]
	v_mfma_f32_16x16x32_bf16 v[46:49], v[146:149], v[202:205], v[46:49]
	v_mfma_f32_16x16x32_bf16 v[46:49], v[150:153], v[206:209], v[46:49]
	v_mfma_f32_16x16x32_bf16 v[42:45], v[166:169], v[202:205], v[42:45]
	v_mfma_f32_16x16x32_bf16 v[42:45], v[170:173], v[206:209], v[42:45]
	v_mfma_f32_16x16x32_bf16 v[30:33], v[146:149], v[210:213], v[30:33]
	v_mfma_f32_16x16x32_bf16 v[30:33], v[150:153], v[214:217], v[30:33]
	v_mfma_f32_16x16x32_bf16 v[26:29], v[166:169], v[210:213], v[26:29]
	v_mfma_f32_16x16x32_bf16 v[26:29], v[170:173], v[214:217], v[26:29]
	v_mfma_f32_16x16x32_bf16 v[14:17], v[146:149], v[218:221], v[14:17]
	v_mfma_f32_16x16x32_bf16 v[14:17], v[150:153], v[222:225], v[14:17]
	v_mfma_f32_16x16x32_bf16 v[10:13], v[166:169], v[218:221], v[10:13]
	v_mfma_f32_16x16x32_bf16 v[10:13], v[170:173], v[222:225], v[10:13]
	v_mfma_f32_16x16x32_bf16 v[54:57], v[174:177], v[194:197], v[54:57]
	v_mfma_f32_16x16x32_bf16 v[54:57], v[182:185], v[198:201], v[54:57]
	v_mfma_f32_16x16x32_bf16 v[50:53], v[186:189], v[194:197], v[50:53]
	v_mfma_f32_16x16x32_bf16 v[50:53], v[190:193], v[198:201], v[50:53]
	v_mfma_f32_16x16x32_bf16 v[38:41], v[174:177], v[202:205], v[38:41]
	v_mfma_f32_16x16x32_bf16 v[38:41], v[182:185], v[206:209], v[38:41]
	v_mfma_f32_16x16x32_bf16 v[34:37], v[186:189], v[202:205], v[34:37]
	v_mfma_f32_16x16x32_bf16 v[34:37], v[190:193], v[206:209], v[34:37]
	v_mfma_f32_16x16x32_bf16 v[22:25], v[174:177], v[210:213], v[22:25]
	v_mfma_f32_16x16x32_bf16 v[22:25], v[182:185], v[214:217], v[22:25]
	v_mfma_f32_16x16x32_bf16 v[18:21], v[186:189], v[210:213], v[18:21]
	v_mfma_f32_16x16x32_bf16 v[18:21], v[190:193], v[214:217], v[18:21]
	v_mfma_f32_16x16x32_bf16 v[6:9], v[174:177], v[218:221], v[6:9]
	v_mfma_f32_16x16x32_bf16 v[6:9], v[182:185], v[222:225], v[6:9]
	v_mfma_f32_16x16x32_bf16 v[2:5], v[186:189], v[218:221], v[2:5]
	v_mfma_f32_16x16x32_bf16 v[2:5], v[190:193], v[222:225], v[2:5]
	s_barrier
	s_setprio 0
	s_add_i32 s55, s55, 2
	s_add_u32 s4, s4, 0x100
	s_addc_u32 s5, s5, 0
	s_add_u32 s53, s53, 0x100
	s_addc_u32 s54, s54, 0
	s_cmp_gt_u32 s55, 29
	s_cbranch_scc0 .LBB0_2731
	s_and_b64 vcc, exec, s[10:11]
	s_cbranch_vccz .LBB0_2734
	s_barrier

.LBB0_3060:
	ds_read_b128 v[154:157], v150
	ds_read_b128 v[158:161], v150 offset:1024
	ds_read_b128 v[162:165], v150 offset:2048
	ds_read_b128 v[166:169], v150 offset:3072
	ds_read_b128 v[170:173], v151
	ds_read_b128 v[174:177], v151 offset:1024
	ds_read_b128 v[182:185], v151 offset:2048
	ds_read_b128 v[186:189], v151 offset:3072
	s_add_u32 s28, s26, 0xfff80080
	s_addc_u32 s29, s27, -1
	s_cmp_eq_u32 s60, 28
	s_cselect_b32 s31, s19, s29
	s_cselect_b32 s30, s56, s28
	s_cselect_b32 s29, s17, s59
	s_cselect_b32 s28, s57, s58
	v_lshl_add_u64 v[146:147], s[26:27], 0, v[138:139]
	s_add_i32 m0, s25, 0xc000
	ds_read_b128 v[190:193], v152
	ds_read_b128 v[194:197], v152 offset:1024
	ds_read_b128 v[198:201], v152 offset:2048
	ds_read_b128 v[202:205], v152 offset:3072
	ds_read_b128 v[206:209], v152 offset:4096
	ds_read_b128 v[210:213], v152 offset:5120
	ds_read_b128 v[214:217], v152 offset:6144
	ds_read_b128 v[218:221], v152 offset:7168
	global_load_lds_dwordx4 v[146:147], off
	v_lshl_add_u64 v[146:147], s[26:27], 0, v[140:141]
	s_add_i32 m0, s25, 0xe000
	s_nop 0
	global_load_lds_dwordx4 v[146:147], off
	s_waitcnt vmcnt(8)
	s_waitcnt lgkmcnt(0)
	s_setprio 1
	s_barrier
	v_mfma_f32_16x16x32_bf16 v[126:129], v[154:157], v[190:193], v[126:129]
	v_mfma_f32_16x16x32_bf16 v[126:129], v[158:161], v[194:197], v[126:129]
	v_mfma_f32_16x16x32_bf16 v[122:125], v[162:165], v[190:193], v[122:125]
	v_mfma_f32_16x16x32_bf16 v[122:125], v[166:169], v[194:197], v[122:125]
	v_mfma_f32_16x16x32_bf16 v[118:121], v[154:157], v[198:201], v[118:121]
	v_mfma_f32_16x16x32_bf16 v[118:121], v[158:161], v[202:205], v[118:121]
	v_mfma_f32_16x16x32_bf16 v[110:113], v[162:165], v[198:201], v[110:113]
	v_mfma_f32_16x16x32_bf16 v[110:113], v[166:169], v[202:205], v[110:113]
	v_mfma_f32_16x16x32_bf16 v[102:105], v[154:157], v[206:209], v[102:105]
	v_mfma_f32_16x16x32_bf16 v[102:105], v[158:161], v[210:213], v[102:105]
	v_mfma_f32_16x16x32_bf16 v[94:97], v[162:165], v[206:209], v[94:97]
	v_mfma_f32_16x16x32_bf16 v[94:97], v[166:169], v[210:213], v[94:97]
	v_mfma_f32_16x16x32_bf16 v[86:89], v[154:157], v[214:217], v[86:89]
	v_mfma_f32_16x16x32_bf16 v[86:89], v[158:161], v[218:221], v[86:89]
	v_mfma_f32_16x16x32_bf16 v[78:81], v[162:165], v[214:217], v[78:81]
	v_mfma_f32_16x16x32_bf16 v[78:81], v[166:169], v[218:221], v[78:81]
	v_mfma_f32_16x16x32_bf16 v[114:117], v[170:173], v[190:193], v[114:117]
	v_mfma_f32_16x16x32_bf16 v[114:117], v[174:177], v[194:197], v[114:117]
	v_mfma_f32_16x16x32_bf16 v[106:109], v[182:185], v[190:193], v[106:109]
	v_mfma_f32_16x16x32_bf16 v[106:109], v[186:189], v[194:197], v[106:109]
	v_mfma_f32_16x16x32_bf16 v[98:101], v[170:173], v[198:201], v[98:101]
	v_mfma_f32_16x16x32_bf16 v[98:101], v[174:177], v[202:205], v[98:101]
	v_mfma_f32_16x16x32_bf16 v[90:93], v[182:185], v[198:201], v[90:93]
	v_mfma_f32_16x16x32_bf16 v[90:93], v[186:189], v[202:205], v[90:93]
	v_mfma_f32_16x16x32_bf16 v[82:85], v[170:173], v[206:209], v[82:85]
	v_mfma_f32_16x16x32_bf16 v[82:85], v[174:177], v[210:213], v[82:85]
	v_mfma_f32_16x16x32_bf16 v[74:77], v[182:185], v[206:209], v[74:77]
	v_mfma_f32_16x16x32_bf16 v[74:77], v[186:189], v[210:213], v[74:77]
	v_mfma_f32_16x16x32_bf16 v[70:73], v[170:173], v[214:217], v[70:73]
	v_mfma_f32_16x16x32_bf16 v[70:73], v[174:177], v[218:221], v[70:73]
	v_mfma_f32_16x16x32_bf16 v[66:69], v[182:185], v[214:217], v[66:69]
	v_mfma_f32_16x16x32_bf16 v[66:69], v[186:189], v[218:221], v[66:69]
	s_barrier
	s_setprio 0
	s_add_i32 s62, s47, s37
	v_lshl_add_u64 v[146:147], s[28:29], 0, v[132:133]
	s_mov_b32 m0, s62
	ds_read_b128 v[190:193], v152 offset:16384
	ds_read_b128 v[194:197], v152 offset:17408
	ds_read_b128 v[198:201], v152 offset:18432
	ds_read_b128 v[202:205], v152 offset:19456
	ds_read_b128 v[206:209], v152 offset:20480
	ds_read_b128 v[210:213], v152 offset:21504
	ds_read_b128 v[214:217], v152 offset:22528
	ds_read_b128 v[218:221], v152 offset:23552
	global_load_lds_dwordx4 v[146:147], off
	s_add_i32 m0, s62, 0x2000
	s_add_u32 s62, s28, 0x80000
	v_lshl_add_u64 v[222:223], s[28:29], 0, v[136:137]
	s_addc_u32 s63, s29, 0
	s_add_i32 s66, s50, s37
	global_load_lds_dwordx4 v[222:223], off
	v_lshl_add_u64 v[224:225], s[62:63], 0, v[132:133]
	s_mov_b32 m0, s66
	v_lshl_add_u64 v[226:227], s[30:31], 0, v[134:135]
	global_load_lds_dwordx4 v[224:225], off
	v_lshl_add_u64 v[224:225], s[62:63], 0, v[136:137]
	s_add_i32 m0, s66, 0x2000
	s_nop 0
	global_load_lds_dwordx4 v[224:225], off
	v_lshl_add_u64 v[224:225], s[30:31], 0, v[130:131]
	s_mov_b32 m0, s25
	s_nop 0
	global_load_lds_dwordx4 v[224:225], off
	s_mov_b32 m0, s38
	s_nop 0
	global_load_lds_dwordx4 v[226:227], off
	s_waitcnt vmcnt(8)
	s_waitcnt lgkmcnt(0)
	s_setprio 1
	s_barrier
	v_mfma_f32_16x16x32_bf16 v[62:65], v[154:157], v[190:193], v[62:65]
	v_mfma_f32_16x16x32_bf16 v[62:65], v[158:161], v[194:197], v[62:65]
	v_mfma_f32_16x16x32_bf16 v[58:61], v[162:165], v[190:193], v[58:61]
	v_mfma_f32_16x16x32_bf16 v[58:61], v[166:169], v[194:197], v[58:61]
	v_mfma_f32_16x16x32_bf16 v[54:57], v[154:157], v[198:201], v[54:57]
	v_mfma_f32_16x16x32_bf16 v[54:57], v[158:161], v[202:205], v[54:57]
	v_mfma_f32_16x16x32_bf16 v[46:49], v[162:165], v[198:201], v[46:49]
	v_mfma_f32_16x16x32_bf16 v[46:49], v[166:169], v[202:205], v[46:49]
	v_mfma_f32_16x16x32_bf16 v[38:41], v[154:157], v[206:209], v[38:41]
	v_mfma_f32_16x16x32_bf16 v[38:41], v[158:161], v[210:213], v[38:41]
	v_mfma_f32_16x16x32_bf16 v[30:33], v[162:165], v[206:209], v[30:33]
	v_mfma_f32_16x16x32_bf16 v[30:33], v[166:169], v[210:213], v[30:33]
	v_mfma_f32_16x16x32_bf16 v[22:25], v[154:157], v[214:217], v[22:25]
	v_mfma_f32_16x16x32_bf16 v[22:25], v[158:161], v[218:221], v[22:25]
	v_mfma_f32_16x16x32_bf16 v[14:17], v[162:165], v[214:217], v[14:17]
	v_mfma_f32_16x16x32_bf16 v[14:17], v[166:169], v[218:221], v[14:17]
	v_mfma_f32_16x16x32_bf16 v[50:53], v[170:173], v[190:193], v[50:53]
	v_mfma_f32_16x16x32_bf16 v[50:53], v[174:177], v[194:197], v[50:53]
	v_mfma_f32_16x16x32_bf16 v[42:45], v[182:185], v[190:193], v[42:45]
	v_mfma_f32_16x16x32_bf16 v[42:45], v[186:189], v[194:197], v[42:45]
	v_mfma_f32_16x16x32_bf16 v[34:37], v[170:173], v[198:201], v[34:37]
	v_mfma_f32_16x16x32_bf16 v[34:37], v[174:177], v[202:205], v[34:37]
	v_mfma_f32_16x16x32_bf16 v[26:29], v[182:185], v[198:201], v[26:29]
	v_mfma_f32_16x16x32_bf16 v[26:29], v[186:189], v[202:205], v[26:29]
	v_mfma_f32_16x16x32_bf16 v[18:21], v[170:173], v[206:209], v[18:21]
	v_mfma_f32_16x16x32_bf16 v[18:21], v[174:177], v[210:213], v[18:21]
	v_mfma_f32_16x16x32_bf16 v[10:13], v[182:185], v[206:209], v[10:13]
	v_mfma_f32_16x16x32_bf16 v[10:13], v[186:189], v[210:213], v[10:13]
	v_mfma_f32_16x16x32_bf16 v[6:9], v[170:173], v[214:217], v[6:9]
	v_mfma_f32_16x16x32_bf16 v[6:9], v[174:177], v[218:221], v[6:9]
	v_mfma_f32_16x16x32_bf16 v[2:5], v[182:185], v[214:217], v[2:5]
	v_mfma_f32_16x16x32_bf16 v[2:5], v[186:189], v[218:221], v[2:5]
	s_barrier
	s_setprio 0
	s_add_i32 s62, 0, 0x18000
	v_add_u32_e32 v153, s62, v148
	s_add_i32 s63, 0, 0x1c000
	ds_read_b128 v[154:157], v153
	ds_read_b128 v[158:161], v153 offset:1024
	ds_read_b128 v[162:165], v153 offset:2048
	ds_read_b128 v[166:169], v153 offset:3072
	v_add_u32_e32 v153, s63, v148
	ds_read_b128 v[170:173], v153
	ds_read_b128 v[174:177], v153 offset:1024
	ds_read_b128 v[182:185], v153 offset:2048
	ds_read_b128 v[186:189], v153 offset:3072
	s_add_u32 s30, s30, 0x80000
	s_addc_u32 s31, s31, 0
	s_mov_b32 m0, s39
	v_lshl_add_u64 v[228:229], s[30:31], 0, v[130:131]
	ds_read_b128 v[190:193], v152 offset:32768
	ds_read_b128 v[194:197], v152 offset:33792
	ds_read_b128 v[198:201], v152 offset:34816
	ds_read_b128 v[202:205], v152 offset:35840
	ds_read_b128 v[206:209], v152 offset:36864
	ds_read_b128 v[210:213], v152 offset:37888
	ds_read_b128 v[214:217], v152 offset:38912
	ds_read_b128 v[218:221], v152 offset:39936
	global_load_lds_dwordx4 v[228:229], off
	v_lshl_add_u64 v[228:229], s[30:31], 0, v[134:135]
	s_mov_b32 m0, s42
	s_nop 0
	global_load_lds_dwordx4 v[228:229], off
	s_waitcnt vmcnt(8)
	s_waitcnt lgkmcnt(0)
	s_setprio 1
	s_barrier
	v_mfma_f32_16x16x32_bf16 v[126:129], v[154:157], v[190:193], v[126:129]
	v_mfma_f32_16x16x32_bf16 v[126:129], v[158:161], v[194:197], v[126:129]
	v_mfma_f32_16x16x32_bf16 v[122:125], v[162:165], v[190:193], v[122:125]
	v_mfma_f32_16x16x32_bf16 v[122:125], v[166:169], v[194:197], v[122:125]
	v_mfma_f32_16x16x32_bf16 v[118:121], v[154:157], v[198:201], v[118:121]
	v_mfma_f32_16x16x32_bf16 v[118:121], v[158:161], v[202:205], v[118:121]
	v_mfma_f32_16x16x32_bf16 v[110:113], v[162:165], v[198:201], v[110:113]
	v_mfma_f32_16x16x32_bf16 v[110:113], v[166:169], v[202:205], v[110:113]
	v_mfma_f32_16x16x32_bf16 v[102:105], v[154:157], v[206:209], v[102:105]
	v_mfma_f32_16x16x32_bf16 v[102:105], v[158:161], v[210:213], v[102:105]
	v_mfma_f32_16x16x32_bf16 v[94:97], v[162:165], v[206:209], v[94:97]
	v_mfma_f32_16x16x32_bf16 v[94:97], v[166:169], v[210:213], v[94:97]
	v_mfma_f32_16x16x32_bf16 v[86:89], v[154:157], v[214:217], v[86:89]
	v_mfma_f32_16x16x32_bf16 v[86:89], v[158:161], v[218:221], v[86:89]
	v_mfma_f32_16x16x32_bf16 v[78:81], v[162:165], v[214:217], v[78:81]
	v_mfma_f32_16x16x32_bf16 v[78:81], v[166:169], v[218:221], v[78:81]
	v_mfma_f32_16x16x32_bf16 v[114:117], v[170:173], v[190:193], v[114:117]
	v_mfma_f32_16x16x32_bf16 v[114:117], v[174:177], v[194:197], v[114:117]
	v_mfma_f32_16x16x32_bf16 v[106:109], v[182:185], v[190:193], v[106:109]
	v_mfma_f32_16x16x32_bf16 v[106:109], v[186:189], v[194:197], v[106:109]
	v_mfma_f32_16x16x32_bf16 v[98:101], v[170:173], v[198:201], v[98:101]
	v_mfma_f32_16x16x32_bf16 v[98:101], v[174:177], v[202:205], v[98:101]
	v_mfma_f32_16x16x32_bf16 v[90:93], v[182:185], v[198:201], v[90:93]
	v_mfma_f32_16x16x32_bf16 v[90:93], v[186:189], v[202:205], v[90:93]
	v_mfma_f32_16x16x32_bf16 v[82:85], v[170:173], v[206:209], v[82:85]
	v_mfma_f32_16x16x32_bf16 v[82:85], v[174:177], v[210:213], v[82:85]
	v_mfma_f32_16x16x32_bf16 v[74:77], v[182:185], v[206:209], v[74:77]
	v_mfma_f32_16x16x32_bf16 v[74:77], v[186:189], v[210:213], v[74:77]
	v_mfma_f32_16x16x32_bf16 v[70:73], v[170:173], v[214:217], v[70:73]
	v_mfma_f32_16x16x32_bf16 v[70:73], v[174:177], v[218:221], v[70:73]
	v_mfma_f32_16x16x32_bf16 v[66:69], v[182:185], v[214:217], v[66:69]
	v_mfma_f32_16x16x32_bf16 v[66:69], v[186:189], v[218:221], v[66:69]
	s_barrier
	s_setprio 0
	s_add_i32 s30, s62, s37
	v_lshl_add_u64 v[146:147], v[146:147], 0, s[6:7]
	s_mov_b32 m0, s30
	ds_read_b128 v[190:193], v152 offset:49152
	ds_read_b128 v[194:197], v152 offset:50176
	ds_read_b128 v[198:201], v152 offset:51200
	ds_read_b128 v[202:205], v152 offset:52224
	ds_read_b128 v[206:209], v152 offset:53248
	ds_read_b128 v[210:213], v152 offset:54272
	ds_read_b128 v[214:217], v152 offset:55296
	ds_read_b128 v[218:221], v152 offset:56320
	global_load_lds_dwordx4 v[146:147], off
	s_add_i32 m0, s30, 0x2000
	s_add_u32 s28, s28, 0x80080
	v_lshl_add_u64 v[146:147], v[222:223], 0, s[6:7]
	s_addc_u32 s29, s29, 0
	s_add_i32 s30, s63, s37
	global_load_lds_dwordx4 v[146:147], off
	v_lshl_add_u64 v[146:147], s[28:29], 0, v[132:133]
	s_mov_b32 m0, s30
	s_nop 0
	global_load_lds_dwordx4 v[146:147], off
	v_lshl_add_u64 v[146:147], s[28:29], 0, v[136:137]
	s_add_i32 m0, s30, 0x2000
	s_nop 0
	global_load_lds_dwordx4 v[146:147], off
	v_lshl_add_u64 v[146:147], v[224:225], 0, s[6:7]
	s_mov_b32 m0, s44
	s_nop 0
	global_load_lds_dwordx4 v[146:147], off
	v_lshl_add_u64 v[146:147], v[226:227], 0, s[6:7]
	s_mov_b32 m0, s45
	s_nop 0
	global_load_lds_dwordx4 v[146:147], off
	s_waitcnt vmcnt(8)
	s_waitcnt lgkmcnt(0)
	s_setprio 1
	s_barrier
	v_mfma_f32_16x16x32_bf16 v[62:65], v[154:157], v[190:193], v[62:65]
	v_mfma_f32_16x16x32_bf16 v[62:65], v[158:161], v[194:197], v[62:65]
	v_mfma_f32_16x16x32_bf16 v[58:61], v[162:165], v[190:193], v[58:61]
	v_mfma_f32_16x16x32_bf16 v[58:61], v[166:169], v[194:197], v[58:61]
	v_mfma_f32_16x16x32_bf16 v[54:57], v[154:157], v[198:201], v[54:57]
	v_mfma_f32_16x16x32_bf16 v[54:57], v[158:161], v[202:205], v[54:57]
	v_mfma_f32_16x16x32_bf16 v[46:49], v[162:165], v[198:201], v[46:49]
	v_mfma_f32_16x16x32_bf16 v[46:49], v[166:169], v[202:205], v[46:49]
	v_mfma_f32_16x16x32_bf16 v[38:41], v[154:157], v[206:209], v[38:41]
	v_mfma_f32_16x16x32_bf16 v[38:41], v[158:161], v[210:213], v[38:41]
	v_mfma_f32_16x16x32_bf16 v[30:33], v[162:165], v[206:209], v[30:33]
	v_mfma_f32_16x16x32_bf16 v[30:33], v[166:169], v[210:213], v[30:33]
	v_mfma_f32_16x16x32_bf16 v[22:25], v[154:157], v[214:217], v[22:25]
	v_mfma_f32_16x16x32_bf16 v[22:25], v[158:161], v[218:221], v[22:25]
	v_mfma_f32_16x16x32_bf16 v[14:17], v[162:165], v[214:217], v[14:17]
	v_mfma_f32_16x16x32_bf16 v[14:17], v[166:169], v[218:221], v[14:17]
	v_mfma_f32_16x16x32_bf16 v[50:53], v[170:173], v[190:193], v[50:53]
	v_mfma_f32_16x16x32_bf16 v[50:53], v[174:177], v[194:197], v[50:53]
	v_mfma_f32_16x16x32_bf16 v[42:45], v[182:185], v[190:193], v[42:45]
	v_mfma_f32_16x16x32_bf16 v[42:45], v[186:189], v[194:197], v[42:45]
	v_mfma_f32_16x16x32_bf16 v[34:37], v[170:173], v[198:201], v[34:37]
	v_mfma_f32_16x16x32_bf16 v[34:37], v[174:177], v[202:205], v[34:37]
	v_mfma_f32_16x16x32_bf16 v[26:29], v[182:185], v[198:201], v[26:29]
	v_mfma_f32_16x16x32_bf16 v[26:29], v[186:189], v[202:205], v[26:29]
	v_mfma_f32_16x16x32_bf16 v[18:21], v[170:173], v[206:209], v[18:21]
	v_mfma_f32_16x16x32_bf16 v[18:21], v[174:177], v[210:213], v[18:21]
	v_mfma_f32_16x16x32_bf16 v[10:13], v[182:185], v[206:209], v[10:13]
	v_mfma_f32_16x16x32_bf16 v[10:13], v[186:189], v[210:213], v[10:13]
	v_mfma_f32_16x16x32_bf16 v[6:9], v[170:173], v[214:217], v[6:9]
	v_mfma_f32_16x16x32_bf16 v[6:9], v[174:177], v[218:221], v[6:9]
	v_mfma_f32_16x16x32_bf16 v[2:5], v[182:185], v[214:217], v[2:5]
	v_mfma_f32_16x16x32_bf16 v[2:5], v[186:189], v[218:221], v[2:5]
	s_barrier
	s_setprio 0
	s_add_i32 s60, s60, 2
	s_add_u32 s26, s26, 0x100
	s_addc_u32 s27, s27, 0
	s_add_u32 s58, s58, 0x100
	s_addc_u32 s59, s59, 0
	s_cmp_gt_u32 s60, 29
	s_cbranch_scc0 .LBB0_3060
	s_and_b64 vcc, exec, s[8:9]
	s_cbranch_vccz .LBB0_3063
	s_barrier

.LBB0_3191:
	ds_read_b128 v[154:157], v150
	ds_read_b128 v[158:161], v150 offset:1024
	ds_read_b128 v[162:165], v150 offset:2048
	ds_read_b128 v[166:169], v150 offset:3072
	ds_read_b128 v[170:173], v151
	ds_read_b128 v[174:177], v151 offset:1024
	ds_read_b128 v[182:185], v151 offset:2048
	ds_read_b128 v[186:189], v151 offset:3072
	s_add_u32 s20, s18, 0xfff80080
	s_addc_u32 s21, s19, -1
	s_cmp_eq_u32 s50, 28
	s_cselect_b32 s23, s11, s21
	s_cselect_b32 s22, s44, s20
	s_cselect_b32 s21, s9, s47
	s_cselect_b32 s20, s45, s46
	v_lshl_add_u64 v[146:147], s[18:19], 0, v[138:139]
	s_add_i32 m0, s17, 0xc000
	ds_read_b128 v[190:193], v152
	ds_read_b128 v[194:197], v152 offset:1024
	ds_read_b128 v[198:201], v152 offset:2048
	ds_read_b128 v[202:205], v152 offset:3072
	ds_read_b128 v[206:209], v152 offset:4096
	ds_read_b128 v[210:213], v152 offset:5120
	ds_read_b128 v[214:217], v152 offset:6144
	ds_read_b128 v[218:221], v152 offset:7168
	global_load_lds_dwordx4 v[146:147], off
	v_lshl_add_u64 v[146:147], s[18:19], 0, v[140:141]
	s_add_i32 m0, s17, 0xe000
	s_nop 0
	global_load_lds_dwordx4 v[146:147], off
	s_waitcnt vmcnt(8)
	s_waitcnt lgkmcnt(0)
	s_setprio 1
	s_barrier
	v_mfma_f32_16x16x32_bf16 v[126:129], v[154:157], v[190:193], v[126:129]
	v_mfma_f32_16x16x32_bf16 v[126:129], v[158:161], v[194:197], v[126:129]
	v_mfma_f32_16x16x32_bf16 v[122:125], v[162:165], v[190:193], v[122:125]
	v_mfma_f32_16x16x32_bf16 v[122:125], v[166:169], v[194:197], v[122:125]
	v_mfma_f32_16x16x32_bf16 v[110:113], v[154:157], v[198:201], v[110:113]
	v_mfma_f32_16x16x32_bf16 v[110:113], v[158:161], v[202:205], v[110:113]
	v_mfma_f32_16x16x32_bf16 v[106:109], v[162:165], v[198:201], v[106:109]
	v_mfma_f32_16x16x32_bf16 v[106:109], v[166:169], v[202:205], v[106:109]
	v_mfma_f32_16x16x32_bf16 v[94:97], v[154:157], v[206:209], v[94:97]
	v_mfma_f32_16x16x32_bf16 v[94:97], v[158:161], v[210:213], v[94:97]
	v_mfma_f32_16x16x32_bf16 v[90:93], v[162:165], v[206:209], v[90:93]
	v_mfma_f32_16x16x32_bf16 v[90:93], v[166:169], v[210:213], v[90:93]
	v_mfma_f32_16x16x32_bf16 v[78:81], v[154:157], v[214:217], v[78:81]
	v_mfma_f32_16x16x32_bf16 v[78:81], v[158:161], v[218:221], v[78:81]
	v_mfma_f32_16x16x32_bf16 v[74:77], v[162:165], v[214:217], v[74:77]
	v_mfma_f32_16x16x32_bf16 v[74:77], v[166:169], v[218:221], v[74:77]
	v_mfma_f32_16x16x32_bf16 v[118:121], v[170:173], v[190:193], v[118:121]
	v_mfma_f32_16x16x32_bf16 v[118:121], v[174:177], v[194:197], v[118:121]
	v_mfma_f32_16x16x32_bf16 v[114:117], v[182:185], v[190:193], v[114:117]
	v_mfma_f32_16x16x32_bf16 v[114:117], v[186:189], v[194:197], v[114:117]
	v_mfma_f32_16x16x32_bf16 v[102:105], v[170:173], v[198:201], v[102:105]
	v_mfma_f32_16x16x32_bf16 v[102:105], v[174:177], v[202:205], v[102:105]
	v_mfma_f32_16x16x32_bf16 v[98:101], v[182:185], v[198:201], v[98:101]
	v_mfma_f32_16x16x32_bf16 v[98:101], v[186:189], v[202:205], v[98:101]
	v_mfma_f32_16x16x32_bf16 v[86:89], v[170:173], v[206:209], v[86:89]
	v_mfma_f32_16x16x32_bf16 v[86:89], v[174:177], v[210:213], v[86:89]
	v_mfma_f32_16x16x32_bf16 v[82:85], v[182:185], v[206:209], v[82:85]
	v_mfma_f32_16x16x32_bf16 v[82:85], v[186:189], v[210:213], v[82:85]
	v_mfma_f32_16x16x32_bf16 v[70:73], v[170:173], v[214:217], v[70:73]
	v_mfma_f32_16x16x32_bf16 v[70:73], v[174:177], v[218:221], v[70:73]
	v_mfma_f32_16x16x32_bf16 v[66:69], v[182:185], v[214:217], v[66:69]
	v_mfma_f32_16x16x32_bf16 v[66:69], v[186:189], v[218:221], v[66:69]
	s_barrier
	s_setprio 0
	s_add_i32 s51, s38, s26
	v_lshl_add_u64 v[146:147], s[20:21], 0, v[134:135]
	s_mov_b32 m0, s51
	ds_read_b128 v[190:193], v152 offset:16384
	ds_read_b128 v[194:197], v152 offset:17408
	ds_read_b128 v[198:201], v152 offset:18432
	ds_read_b128 v[202:205], v152 offset:19456
	ds_read_b128 v[206:209], v152 offset:20480
	ds_read_b128 v[210:213], v152 offset:21504
	ds_read_b128 v[214:217], v152 offset:22528
	ds_read_b128 v[218:221], v152 offset:23552
	global_load_lds_dwordx4 v[146:147], off
	s_add_i32 m0, s51, 0x2000
	s_add_u32 s52, s20, 0x80000
	v_lshl_add_u64 v[222:223], s[20:21], 0, v[130:131]
	s_addc_u32 s53, s21, 0
	s_add_i32 s51, s39, s26
	global_load_lds_dwordx4 v[222:223], off
	v_lshl_add_u64 v[224:225], s[52:53], 0, v[134:135]
	s_mov_b32 m0, s51
	v_lshl_add_u64 v[226:227], s[22:23], 0, v[132:133]
	global_load_lds_dwordx4 v[224:225], off
	v_lshl_add_u64 v[224:225], s[52:53], 0, v[130:131]
	s_add_i32 m0, s51, 0x2000
	s_nop 0
	global_load_lds_dwordx4 v[224:225], off
	v_lshl_add_u64 v[224:225], s[22:23], 0, v[136:137]
	s_mov_b32 m0, s17
	s_nop 0
	global_load_lds_dwordx4 v[224:225], off
	s_mov_b32 m0, s29
	s_nop 0
	global_load_lds_dwordx4 v[226:227], off
	s_waitcnt vmcnt(8)
	s_waitcnt lgkmcnt(0)
	s_setprio 1
	s_barrier
	v_mfma_f32_16x16x32_bf16 v[62:65], v[154:157], v[190:193], v[62:65]
	v_mfma_f32_16x16x32_bf16 v[62:65], v[158:161], v[194:197], v[62:65]
	v_mfma_f32_16x16x32_bf16 v[58:61], v[162:165], v[190:193], v[58:61]
	v_mfma_f32_16x16x32_bf16 v[58:61], v[166:169], v[194:197], v[58:61]
	v_mfma_f32_16x16x32_bf16 v[46:49], v[154:157], v[198:201], v[46:49]
	v_mfma_f32_16x16x32_bf16 v[46:49], v[158:161], v[202:205], v[46:49]
	v_mfma_f32_16x16x32_bf16 v[42:45], v[162:165], v[198:201], v[42:45]
	v_mfma_f32_16x16x32_bf16 v[42:45], v[166:169], v[202:205], v[42:45]
	v_mfma_f32_16x16x32_bf16 v[30:33], v[154:157], v[206:209], v[30:33]
	v_mfma_f32_16x16x32_bf16 v[30:33], v[158:161], v[210:213], v[30:33]
	v_mfma_f32_16x16x32_bf16 v[26:29], v[162:165], v[206:209], v[26:29]
	v_mfma_f32_16x16x32_bf16 v[26:29], v[166:169], v[210:213], v[26:29]
	v_mfma_f32_16x16x32_bf16 v[14:17], v[154:157], v[214:217], v[14:17]
	v_mfma_f32_16x16x32_bf16 v[14:17], v[158:161], v[218:221], v[14:17]
	v_mfma_f32_16x16x32_bf16 v[10:13], v[162:165], v[214:217], v[10:13]
	v_mfma_f32_16x16x32_bf16 v[10:13], v[166:169], v[218:221], v[10:13]
	v_mfma_f32_16x16x32_bf16 v[54:57], v[170:173], v[190:193], v[54:57]
	v_mfma_f32_16x16x32_bf16 v[54:57], v[174:177], v[194:197], v[54:57]
	v_mfma_f32_16x16x32_bf16 v[50:53], v[182:185], v[190:193], v[50:53]
	v_mfma_f32_16x16x32_bf16 v[50:53], v[186:189], v[194:197], v[50:53]
	v_mfma_f32_16x16x32_bf16 v[38:41], v[170:173], v[198:201], v[38:41]
	v_mfma_f32_16x16x32_bf16 v[38:41], v[174:177], v[202:205], v[38:41]
	v_mfma_f32_16x16x32_bf16 v[34:37], v[182:185], v[198:201], v[34:37]
	v_mfma_f32_16x16x32_bf16 v[34:37], v[186:189], v[202:205], v[34:37]
	v_mfma_f32_16x16x32_bf16 v[22:25], v[170:173], v[206:209], v[22:25]
	v_mfma_f32_16x16x32_bf16 v[22:25], v[174:177], v[210:213], v[22:25]
	v_mfma_f32_16x16x32_bf16 v[18:21], v[182:185], v[206:209], v[18:21]
	v_mfma_f32_16x16x32_bf16 v[18:21], v[186:189], v[210:213], v[18:21]
	v_mfma_f32_16x16x32_bf16 v[6:9], v[170:173], v[214:217], v[6:9]
	v_mfma_f32_16x16x32_bf16 v[6:9], v[174:177], v[218:221], v[6:9]
	v_mfma_f32_16x16x32_bf16 v[2:5], v[182:185], v[214:217], v[2:5]
	v_mfma_f32_16x16x32_bf16 v[2:5], v[186:189], v[218:221], v[2:5]
	s_barrier
	s_setprio 0
	s_add_i32 s51, 0, 0x18000
	v_add_u32_e32 v153, s51, v148
	s_add_i32 s52, 0, 0x1c000
	ds_read_b128 v[154:157], v153
	ds_read_b128 v[158:161], v153 offset:1024
	ds_read_b128 v[162:165], v153 offset:2048
	ds_read_b128 v[166:169], v153 offset:3072
	v_add_u32_e32 v153, s52, v148
	ds_read_b128 v[170:173], v153
	ds_read_b128 v[174:177], v153 offset:1024
	ds_read_b128 v[182:185], v153 offset:2048
	ds_read_b128 v[186:189], v153 offset:3072
	s_add_u32 s22, s22, 0x80000
	s_addc_u32 s23, s23, 0
	s_mov_b32 m0, s30
	v_lshl_add_u64 v[228:229], s[22:23], 0, v[136:137]
	ds_read_b128 v[190:193], v152 offset:32768
	ds_read_b128 v[194:197], v152 offset:33792
	ds_read_b128 v[198:201], v152 offset:34816
	ds_read_b128 v[202:205], v152 offset:35840
	ds_read_b128 v[206:209], v152 offset:36864
	ds_read_b128 v[210:213], v152 offset:37888
	ds_read_b128 v[214:217], v152 offset:38912
	ds_read_b128 v[218:221], v152 offset:39936
	global_load_lds_dwordx4 v[228:229], off
	v_lshl_add_u64 v[228:229], s[22:23], 0, v[132:133]
	s_mov_b32 m0, s31
	s_nop 0
	global_load_lds_dwordx4 v[228:229], off
	s_waitcnt vmcnt(8)
	s_waitcnt lgkmcnt(0)
	s_setprio 1
	s_barrier
	v_mfma_f32_16x16x32_bf16 v[126:129], v[154:157], v[190:193], v[126:129]
	v_mfma_f32_16x16x32_bf16 v[126:129], v[158:161], v[194:197], v[126:129]
	v_mfma_f32_16x16x32_bf16 v[122:125], v[162:165], v[190:193], v[122:125]
	v_mfma_f32_16x16x32_bf16 v[122:125], v[166:169], v[194:197], v[122:125]
	v_mfma_f32_16x16x32_bf16 v[110:113], v[154:157], v[198:201], v[110:113]
	v_mfma_f32_16x16x32_bf16 v[110:113], v[158:161], v[202:205], v[110:113]
	v_mfma_f32_16x16x32_bf16 v[106:109], v[162:165], v[198:201], v[106:109]
	v_mfma_f32_16x16x32_bf16 v[106:109], v[166:169], v[202:205], v[106:109]
	v_mfma_f32_16x16x32_bf16 v[94:97], v[154:157], v[206:209], v[94:97]
	v_mfma_f32_16x16x32_bf16 v[94:97], v[158:161], v[210:213], v[94:97]
	v_mfma_f32_16x16x32_bf16 v[90:93], v[162:165], v[206:209], v[90:93]
	v_mfma_f32_16x16x32_bf16 v[90:93], v[166:169], v[210:213], v[90:93]
	v_mfma_f32_16x16x32_bf16 v[78:81], v[154:157], v[214:217], v[78:81]
	v_mfma_f32_16x16x32_bf16 v[78:81], v[158:161], v[218:221], v[78:81]
	v_mfma_f32_16x16x32_bf16 v[74:77], v[162:165], v[214:217], v[74:77]
	v_mfma_f32_16x16x32_bf16 v[74:77], v[166:169], v[218:221], v[74:77]
	v_mfma_f32_16x16x32_bf16 v[118:121], v[170:173], v[190:193], v[118:121]
	v_mfma_f32_16x16x32_bf16 v[118:121], v[174:177], v[194:197], v[118:121]
	v_mfma_f32_16x16x32_bf16 v[114:117], v[182:185], v[190:193], v[114:117]
	v_mfma_f32_16x16x32_bf16 v[114:117], v[186:189], v[194:197], v[114:117]
	v_mfma_f32_16x16x32_bf16 v[102:105], v[170:173], v[198:201], v[102:105]
	v_mfma_f32_16x16x32_bf16 v[102:105], v[174:177], v[202:205], v[102:105]
	v_mfma_f32_16x16x32_bf16 v[98:101], v[182:185], v[198:201], v[98:101]
	v_mfma_f32_16x16x32_bf16 v[98:101], v[186:189], v[202:205], v[98:101]
	v_mfma_f32_16x16x32_bf16 v[86:89], v[170:173], v[206:209], v[86:89]
	v_mfma_f32_16x16x32_bf16 v[86:89], v[174:177], v[210:213], v[86:89]
	v_mfma_f32_16x16x32_bf16 v[82:85], v[182:185], v[206:209], v[82:85]
	v_mfma_f32_16x16x32_bf16 v[82:85], v[186:189], v[210:213], v[82:85]
	v_mfma_f32_16x16x32_bf16 v[70:73], v[170:173], v[214:217], v[70:73]
	v_mfma_f32_16x16x32_bf16 v[70:73], v[174:177], v[218:221], v[70:73]
	v_mfma_f32_16x16x32_bf16 v[66:69], v[182:185], v[214:217], v[66:69]
	v_mfma_f32_16x16x32_bf16 v[66:69], v[186:189], v[218:221], v[66:69]
	s_barrier
	s_setprio 0
	s_add_i32 s22, s51, s26
	v_lshl_add_u64 v[146:147], v[146:147], 0, s[4:5]
	s_mov_b32 m0, s22
	ds_read_b128 v[190:193], v152 offset:49152
	ds_read_b128 v[194:197], v152 offset:50176
	ds_read_b128 v[198:201], v152 offset:51200
	ds_read_b128 v[202:205], v152 offset:52224
	ds_read_b128 v[206:209], v152 offset:53248
	ds_read_b128 v[210:213], v152 offset:54272
	ds_read_b128 v[214:217], v152 offset:55296
	ds_read_b128 v[218:221], v152 offset:56320
	global_load_lds_dwordx4 v[146:147], off
	s_add_i32 m0, s22, 0x2000
	s_add_u32 s20, s20, 0x80080
	v_lshl_add_u64 v[146:147], v[222:223], 0, s[4:5]
	s_addc_u32 s21, s21, 0
	s_add_i32 s22, s52, s26
	global_load_lds_dwordx4 v[146:147], off
	v_lshl_add_u64 v[146:147], s[20:21], 0, v[134:135]
	s_mov_b32 m0, s22
	s_nop 0
	global_load_lds_dwordx4 v[146:147], off
	v_lshl_add_u64 v[146:147], s[20:21], 0, v[130:131]
	s_add_i32 m0, s22, 0x2000
	s_nop 0
	global_load_lds_dwordx4 v[146:147], off
	v_lshl_add_u64 v[146:147], v[224:225], 0, s[4:5]
	s_mov_b32 m0, s35
	s_nop 0
	global_load_lds_dwordx4 v[146:147], off
	v_lshl_add_u64 v[146:147], v[226:227], 0, s[4:5]
	s_mov_b32 m0, s36
	s_nop 0
	global_load_lds_dwordx4 v[146:147], off
	s_waitcnt vmcnt(8)
	s_waitcnt lgkmcnt(0)
	s_setprio 1
	s_barrier
	v_mfma_f32_16x16x32_bf16 v[62:65], v[154:157], v[190:193], v[62:65]
	v_mfma_f32_16x16x32_bf16 v[62:65], v[158:161], v[194:197], v[62:65]
	v_mfma_f32_16x16x32_bf16 v[58:61], v[162:165], v[190:193], v[58:61]
	v_mfma_f32_16x16x32_bf16 v[58:61], v[166:169], v[194:197], v[58:61]
	v_mfma_f32_16x16x32_bf16 v[46:49], v[154:157], v[198:201], v[46:49]
	v_mfma_f32_16x16x32_bf16 v[46:49], v[158:161], v[202:205], v[46:49]
	v_mfma_f32_16x16x32_bf16 v[42:45], v[162:165], v[198:201], v[42:45]
	v_mfma_f32_16x16x32_bf16 v[42:45], v[166:169], v[202:205], v[42:45]
	v_mfma_f32_16x16x32_bf16 v[30:33], v[154:157], v[206:209], v[30:33]
	v_mfma_f32_16x16x32_bf16 v[30:33], v[158:161], v[210:213], v[30:33]
	v_mfma_f32_16x16x32_bf16 v[26:29], v[162:165], v[206:209], v[26:29]
	v_mfma_f32_16x16x32_bf16 v[26:29], v[166:169], v[210:213], v[26:29]
	v_mfma_f32_16x16x32_bf16 v[14:17], v[154:157], v[214:217], v[14:17]
	v_mfma_f32_16x16x32_bf16 v[14:17], v[158:161], v[218:221], v[14:17]
	v_mfma_f32_16x16x32_bf16 v[10:13], v[162:165], v[214:217], v[10:13]
	v_mfma_f32_16x16x32_bf16 v[10:13], v[166:169], v[218:221], v[10:13]
	v_mfma_f32_16x16x32_bf16 v[54:57], v[170:173], v[190:193], v[54:57]
	v_mfma_f32_16x16x32_bf16 v[54:57], v[174:177], v[194:197], v[54:57]
	v_mfma_f32_16x16x32_bf16 v[50:53], v[182:185], v[190:193], v[50:53]
	v_mfma_f32_16x16x32_bf16 v[50:53], v[186:189], v[194:197], v[50:53]
	v_mfma_f32_16x16x32_bf16 v[38:41], v[170:173], v[198:201], v[38:41]
	v_mfma_f32_16x16x32_bf16 v[38:41], v[174:177], v[202:205], v[38:41]
	v_mfma_f32_16x16x32_bf16 v[34:37], v[182:185], v[198:201], v[34:37]
	v_mfma_f32_16x16x32_bf16 v[34:37], v[186:189], v[202:205], v[34:37]
	v_mfma_f32_16x16x32_bf16 v[22:25], v[170:173], v[206:209], v[22:25]
	v_mfma_f32_16x16x32_bf16 v[22:25], v[174:177], v[210:213], v[22:25]
	v_mfma_f32_16x16x32_bf16 v[18:21], v[182:185], v[206:209], v[18:21]
	v_mfma_f32_16x16x32_bf16 v[18:21], v[186:189], v[210:213], v[18:21]
	v_mfma_f32_16x16x32_bf16 v[6:9], v[170:173], v[214:217], v[6:9]
	v_mfma_f32_16x16x32_bf16 v[6:9], v[174:177], v[218:221], v[6:9]
	v_mfma_f32_16x16x32_bf16 v[2:5], v[182:185], v[214:217], v[2:5]
	v_mfma_f32_16x16x32_bf16 v[2:5], v[186:189], v[218:221], v[2:5]
	s_barrier
	s_setprio 0
	s_add_i32 s50, s50, 2
	s_add_u32 s18, s18, 0x100
	s_addc_u32 s19, s19, 0
	s_add_u32 s46, s46, 0x100
	s_addc_u32 s47, s47, 0
	s_cmp_gt_u32 s50, 29
	s_cbranch_scc0 .LBB0_3191
	s_and_b64 vcc, exec, s[6:7]
	s_cbranch_vccz .LBB0_3194
	s_barrier

.LBB0_3274:
	ds_read_b128 v[152:155], v149
	ds_read_b128 v[156:159], v149 offset:1024
	ds_read_b128 v[160:163], v149 offset:2048
	ds_read_b128 v[164:167], v149 offset:3072
	ds_read_b128 v[168:171], v150
	ds_read_b128 v[172:175], v150 offset:1024
	ds_read_b128 v[182:185], v150 offset:2048
	ds_read_b128 v[186:189], v150 offset:3072
	s_add_u32 s22, s20, 0xffea0080
	s_addc_u32 s23, s21, -1
	s_cmpk_eq_i32 s56, 0x54
	s_cselect_b32 s25, s3, s23
	s_cselect_b32 s24, s2, s22
	s_cselect_b32 s23, s19, s55
	s_cselect_b32 s22, s18, s54
	v_lshl_add_u64 v[144:145], s[20:21], 0, v[136:137]
	s_add_i32 m0, s30, 0xc000
	ds_read_b128 v[190:193], v151
	ds_read_b128 v[194:197], v151 offset:1024
	ds_read_b128 v[198:201], v151 offset:2048
	ds_read_b128 v[202:205], v151 offset:3072
	ds_read_b128 v[206:209], v151 offset:4096
	ds_read_b128 v[210:213], v151 offset:5120
	ds_read_b128 v[214:217], v151 offset:6144
	ds_read_b128 v[218:221], v151 offset:7168
	global_load_lds_dwordx4 v[144:145], off
	v_lshl_add_u64 v[144:145], s[20:21], 0, v[138:139]
	s_add_i32 m0, s30, 0xe000
	s_nop 0
	global_load_lds_dwordx4 v[144:145], off
	s_waitcnt vmcnt(8)
	s_waitcnt lgkmcnt(0)
	s_setprio 1
	s_barrier
	v_mfma_f32_16x16x32_bf16 v[124:127], v[152:155], v[190:193], v[124:127]
	v_mfma_f32_16x16x32_bf16 v[124:127], v[156:159], v[194:197], v[124:127]
	v_mfma_f32_16x16x32_bf16 v[120:123], v[160:163], v[190:193], v[120:123]
	v_mfma_f32_16x16x32_bf16 v[120:123], v[164:167], v[194:197], v[120:123]
	v_mfma_f32_16x16x32_bf16 v[116:119], v[152:155], v[198:201], v[116:119]
	v_mfma_f32_16x16x32_bf16 v[116:119], v[156:159], v[202:205], v[116:119]
	v_mfma_f32_16x16x32_bf16 v[108:111], v[160:163], v[198:201], v[108:111]
	v_mfma_f32_16x16x32_bf16 v[108:111], v[164:167], v[202:205], v[108:111]
	v_mfma_f32_16x16x32_bf16 v[100:103], v[152:155], v[206:209], v[100:103]
	v_mfma_f32_16x16x32_bf16 v[100:103], v[156:159], v[210:213], v[100:103]
	v_mfma_f32_16x16x32_bf16 v[92:95], v[160:163], v[206:209], v[92:95]
	v_mfma_f32_16x16x32_bf16 v[92:95], v[164:167], v[210:213], v[92:95]
	v_mfma_f32_16x16x32_bf16 v[84:87], v[152:155], v[214:217], v[84:87]
	v_mfma_f32_16x16x32_bf16 v[84:87], v[156:159], v[218:221], v[84:87]
	v_mfma_f32_16x16x32_bf16 v[76:79], v[160:163], v[214:217], v[76:79]
	v_mfma_f32_16x16x32_bf16 v[76:79], v[164:167], v[218:221], v[76:79]
	v_mfma_f32_16x16x32_bf16 v[112:115], v[168:171], v[190:193], v[112:115]
	v_mfma_f32_16x16x32_bf16 v[112:115], v[172:175], v[194:197], v[112:115]
	v_mfma_f32_16x16x32_bf16 v[104:107], v[182:185], v[190:193], v[104:107]
	v_mfma_f32_16x16x32_bf16 v[104:107], v[186:189], v[194:197], v[104:107]
	v_mfma_f32_16x16x32_bf16 v[96:99], v[168:171], v[198:201], v[96:99]
	v_mfma_f32_16x16x32_bf16 v[96:99], v[172:175], v[202:205], v[96:99]
	v_mfma_f32_16x16x32_bf16 v[88:91], v[182:185], v[198:201], v[88:91]
	v_mfma_f32_16x16x32_bf16 v[88:91], v[186:189], v[202:205], v[88:91]
	v_mfma_f32_16x16x32_bf16 v[80:83], v[168:171], v[206:209], v[80:83]
	v_mfma_f32_16x16x32_bf16 v[80:83], v[172:175], v[210:213], v[80:83]
	v_mfma_f32_16x16x32_bf16 v[72:75], v[182:185], v[206:209], v[72:75]
	v_mfma_f32_16x16x32_bf16 v[72:75], v[186:189], v[210:213], v[72:75]
	v_mfma_f32_16x16x32_bf16 v[68:71], v[168:171], v[214:217], v[68:71]
	v_mfma_f32_16x16x32_bf16 v[68:71], v[172:175], v[218:221], v[68:71]
	v_mfma_f32_16x16x32_bf16 v[64:67], v[182:185], v[214:217], v[64:67]
	v_mfma_f32_16x16x32_bf16 v[64:67], v[186:189], v[218:221], v[64:67]
	s_barrier
	s_setprio 0
	s_add_i32 s57, s42, s29
	v_lshl_add_u64 v[144:145], s[22:23], 0, v[130:131]
	s_mov_b32 m0, s57
	ds_read_b128 v[190:193], v151 offset:16384
	ds_read_b128 v[194:197], v151 offset:17408
	ds_read_b128 v[198:201], v151 offset:18432
	ds_read_b128 v[202:205], v151 offset:19456
	ds_read_b128 v[206:209], v151 offset:20480
	ds_read_b128 v[210:213], v151 offset:21504
	ds_read_b128 v[214:217], v151 offset:22528
	ds_read_b128 v[218:221], v151 offset:23552
	global_load_lds_dwordx4 v[144:145], off
	s_add_i32 m0, s57, 0x2000
	s_add_u32 s58, s22, 0x160000
	v_lshl_add_u64 v[176:177], s[22:23], 0, v[134:135]
	s_addc_u32 s59, s23, 0
	s_add_i32 s57, s43, s29
	global_load_lds_dwordx4 v[176:177], off
	v_lshl_add_u64 v[222:223], s[58:59], 0, v[130:131]
	s_mov_b32 m0, s57
	v_lshl_add_u64 v[224:225], s[24:25], 0, v[132:133]
	global_load_lds_dwordx4 v[222:223], off
	v_lshl_add_u64 v[222:223], s[58:59], 0, v[134:135]
	s_add_i32 m0, s57, 0x2000
	s_nop 0
	global_load_lds_dwordx4 v[222:223], off
	v_lshl_add_u64 v[222:223], s[24:25], 0, v[128:129]
	s_mov_b32 m0, s30
	s_nop 0
	global_load_lds_dwordx4 v[222:223], off
	s_mov_b32 m0, s31
	s_nop 0
	global_load_lds_dwordx4 v[224:225], off
	s_waitcnt vmcnt(8)
	s_waitcnt lgkmcnt(0)
	s_setprio 1
	s_barrier
	v_mfma_f32_16x16x32_bf16 v[60:63], v[152:155], v[190:193], v[60:63]
	v_mfma_f32_16x16x32_bf16 v[60:63], v[156:159], v[194:197], v[60:63]
	v_mfma_f32_16x16x32_bf16 v[56:59], v[160:163], v[190:193], v[56:59]
	v_mfma_f32_16x16x32_bf16 v[56:59], v[164:167], v[194:197], v[56:59]
	v_mfma_f32_16x16x32_bf16 v[52:55], v[152:155], v[198:201], v[52:55]
	v_mfma_f32_16x16x32_bf16 v[52:55], v[156:159], v[202:205], v[52:55]
	v_mfma_f32_16x16x32_bf16 v[44:47], v[160:163], v[198:201], v[44:47]
	v_mfma_f32_16x16x32_bf16 v[44:47], v[164:167], v[202:205], v[44:47]
	v_mfma_f32_16x16x32_bf16 v[36:39], v[152:155], v[206:209], v[36:39]
	v_mfma_f32_16x16x32_bf16 v[36:39], v[156:159], v[210:213], v[36:39]
	v_mfma_f32_16x16x32_bf16 v[28:31], v[160:163], v[206:209], v[28:31]
	v_mfma_f32_16x16x32_bf16 v[28:31], v[164:167], v[210:213], v[28:31]
	v_mfma_f32_16x16x32_bf16 v[20:23], v[152:155], v[214:217], v[20:23]
	v_mfma_f32_16x16x32_bf16 v[20:23], v[156:159], v[218:221], v[20:23]
	v_mfma_f32_16x16x32_bf16 v[12:15], v[160:163], v[214:217], v[12:15]
	v_mfma_f32_16x16x32_bf16 v[12:15], v[164:167], v[218:221], v[12:15]
	v_mfma_f32_16x16x32_bf16 v[48:51], v[168:171], v[190:193], v[48:51]
	v_mfma_f32_16x16x32_bf16 v[48:51], v[172:175], v[194:197], v[48:51]
	v_mfma_f32_16x16x32_bf16 v[40:43], v[182:185], v[190:193], v[40:43]
	v_mfma_f32_16x16x32_bf16 v[40:43], v[186:189], v[194:197], v[40:43]
	v_mfma_f32_16x16x32_bf16 v[32:35], v[168:171], v[198:201], v[32:35]
	v_mfma_f32_16x16x32_bf16 v[32:35], v[172:175], v[202:205], v[32:35]
	v_mfma_f32_16x16x32_bf16 v[24:27], v[182:185], v[198:201], v[24:27]
	v_mfma_f32_16x16x32_bf16 v[24:27], v[186:189], v[202:205], v[24:27]
	v_mfma_f32_16x16x32_bf16 v[16:19], v[168:171], v[206:209], v[16:19]
	v_mfma_f32_16x16x32_bf16 v[16:19], v[172:175], v[210:213], v[16:19]
	v_mfma_f32_16x16x32_bf16 v[8:11], v[182:185], v[206:209], v[8:11]
	v_mfma_f32_16x16x32_bf16 v[8:11], v[186:189], v[210:213], v[8:11]
	v_mfma_f32_16x16x32_bf16 v[4:7], v[168:171], v[214:217], v[4:7]
	v_mfma_f32_16x16x32_bf16 v[4:7], v[172:175], v[218:221], v[4:7]
	v_mfma_f32_16x16x32_bf16 v[0:3], v[182:185], v[214:217], v[0:3]
	v_mfma_f32_16x16x32_bf16 v[0:3], v[186:189], v[218:221], v[0:3]
	s_barrier
	s_setprio 0
	s_add_i32 s57, 0, 0x18000
	s_add_i32 s58, 0, 0x1c000
	v_add_u32_e32 v164, s57, v147
	v_add_u32_e32 v179, s58, v147
	ds_read_b128 v[152:155], v164
	ds_read_b128 v[156:159], v164 offset:1024
	ds_read_b128 v[160:163], v164 offset:2048
	ds_read_b128 v[164:167], v164 offset:3072
	ds_read_b128 v[168:171], v179
	ds_read_b128 v[172:175], v179 offset:1024
	ds_read_b128 v[182:185], v179 offset:2048
	ds_read_b128 v[186:189], v179 offset:3072
	s_add_u32 s24, s24, 0x160000
	s_addc_u32 s25, s25, 0
	s_mov_b32 m0, s34
	v_lshl_add_u64 v[226:227], s[24:25], 0, v[128:129]
	ds_read_b128 v[190:193], v151 offset:32768
	ds_read_b128 v[194:197], v151 offset:33792
	ds_read_b128 v[198:201], v151 offset:34816
	ds_read_b128 v[202:205], v151 offset:35840
	ds_read_b128 v[206:209], v151 offset:36864
	ds_read_b128 v[210:213], v151 offset:37888
	ds_read_b128 v[214:217], v151 offset:38912
	ds_read_b128 v[218:221], v151 offset:39936
	global_load_lds_dwordx4 v[226:227], off
	v_lshl_add_u64 v[226:227], s[24:25], 0, v[132:133]
	s_mov_b32 m0, s35
	s_nop 0
	global_load_lds_dwordx4 v[226:227], off
	s_waitcnt vmcnt(8)
	s_waitcnt lgkmcnt(0)
	s_setprio 1
	s_barrier
	v_mfma_f32_16x16x32_bf16 v[124:127], v[152:155], v[190:193], v[124:127]
	v_mfma_f32_16x16x32_bf16 v[124:127], v[156:159], v[194:197], v[124:127]
	v_mfma_f32_16x16x32_bf16 v[120:123], v[160:163], v[190:193], v[120:123]
	v_mfma_f32_16x16x32_bf16 v[120:123], v[164:167], v[194:197], v[120:123]
	v_mfma_f32_16x16x32_bf16 v[116:119], v[152:155], v[198:201], v[116:119]
	v_mfma_f32_16x16x32_bf16 v[116:119], v[156:159], v[202:205], v[116:119]
	v_mfma_f32_16x16x32_bf16 v[108:111], v[160:163], v[198:201], v[108:111]
	v_mfma_f32_16x16x32_bf16 v[108:111], v[164:167], v[202:205], v[108:111]
	v_mfma_f32_16x16x32_bf16 v[100:103], v[152:155], v[206:209], v[100:103]
	v_mfma_f32_16x16x32_bf16 v[100:103], v[156:159], v[210:213], v[100:103]
	v_mfma_f32_16x16x32_bf16 v[92:95], v[160:163], v[206:209], v[92:95]
	v_mfma_f32_16x16x32_bf16 v[92:95], v[164:167], v[210:213], v[92:95]
	v_mfma_f32_16x16x32_bf16 v[84:87], v[152:155], v[214:217], v[84:87]
	v_mfma_f32_16x16x32_bf16 v[84:87], v[156:159], v[218:221], v[84:87]
	v_mfma_f32_16x16x32_bf16 v[76:79], v[160:163], v[214:217], v[76:79]
	v_mfma_f32_16x16x32_bf16 v[76:79], v[164:167], v[218:221], v[76:79]
	v_mfma_f32_16x16x32_bf16 v[112:115], v[168:171], v[190:193], v[112:115]
	v_mfma_f32_16x16x32_bf16 v[112:115], v[172:175], v[194:197], v[112:115]
	v_mfma_f32_16x16x32_bf16 v[104:107], v[182:185], v[190:193], v[104:107]
	v_mfma_f32_16x16x32_bf16 v[104:107], v[186:189], v[194:197], v[104:107]
	v_mfma_f32_16x16x32_bf16 v[96:99], v[168:171], v[198:201], v[96:99]
	v_mfma_f32_16x16x32_bf16 v[96:99], v[172:175], v[202:205], v[96:99]
	v_mfma_f32_16x16x32_bf16 v[88:91], v[182:185], v[198:201], v[88:91]
	v_mfma_f32_16x16x32_bf16 v[88:91], v[186:189], v[202:205], v[88:91]
	v_mfma_f32_16x16x32_bf16 v[80:83], v[168:171], v[206:209], v[80:83]
	v_mfma_f32_16x16x32_bf16 v[80:83], v[172:175], v[210:213], v[80:83]
	v_mfma_f32_16x16x32_bf16 v[72:75], v[182:185], v[206:209], v[72:75]
	v_mfma_f32_16x16x32_bf16 v[72:75], v[186:189], v[210:213], v[72:75]
	v_mfma_f32_16x16x32_bf16 v[68:71], v[168:171], v[214:217], v[68:71]
	v_mfma_f32_16x16x32_bf16 v[68:71], v[172:175], v[218:221], v[68:71]
	v_mfma_f32_16x16x32_bf16 v[64:67], v[182:185], v[214:217], v[64:67]
	v_mfma_f32_16x16x32_bf16 v[64:67], v[186:189], v[218:221], v[64:67]
	s_barrier
	s_setprio 0
	s_add_i32 s24, s57, s29
	v_lshl_add_u64 v[144:145], v[144:145], 0, s[6:7]
	s_mov_b32 m0, s24
	ds_read_b128 v[190:193], v151 offset:49152
	ds_read_b128 v[194:197], v151 offset:50176
	ds_read_b128 v[198:201], v151 offset:51200
	ds_read_b128 v[202:205], v151 offset:52224
	ds_read_b128 v[206:209], v151 offset:53248
	ds_read_b128 v[210:213], v151 offset:54272
	ds_read_b128 v[214:217], v151 offset:55296
	ds_read_b128 v[218:221], v151 offset:56320
	global_load_lds_dwordx4 v[144:145], off
	s_add_i32 m0, s24, 0x2000
	s_add_u32 s22, s22, 0x160080
	v_lshl_add_u64 v[144:145], v[176:177], 0, s[6:7]
	s_addc_u32 s23, s23, 0
	s_add_i32 s24, s58, s29
	global_load_lds_dwordx4 v[144:145], off
	v_lshl_add_u64 v[144:145], s[22:23], 0, v[130:131]
	s_mov_b32 m0, s24
	s_nop 0
	global_load_lds_dwordx4 v[144:145], off
	v_lshl_add_u64 v[144:145], s[22:23], 0, v[134:135]
	s_add_i32 m0, s24, 0x2000
	s_nop 0
	global_load_lds_dwordx4 v[144:145], off
	v_lshl_add_u64 v[144:145], v[222:223], 0, s[6:7]
	s_mov_b32 m0, s37
	s_nop 0
	global_load_lds_dwordx4 v[144:145], off
	v_lshl_add_u64 v[144:145], v[224:225], 0, s[6:7]
	s_mov_b32 m0, s38
	s_nop 0
	global_load_lds_dwordx4 v[144:145], off
	s_waitcnt vmcnt(8)
	s_waitcnt lgkmcnt(0)
	s_setprio 1
	s_barrier
	v_mfma_f32_16x16x32_bf16 v[60:63], v[152:155], v[190:193], v[60:63]
	v_mfma_f32_16x16x32_bf16 v[60:63], v[156:159], v[194:197], v[60:63]
	v_mfma_f32_16x16x32_bf16 v[56:59], v[160:163], v[190:193], v[56:59]
	v_mfma_f32_16x16x32_bf16 v[56:59], v[164:167], v[194:197], v[56:59]
	v_mfma_f32_16x16x32_bf16 v[52:55], v[152:155], v[198:201], v[52:55]
	v_mfma_f32_16x16x32_bf16 v[52:55], v[156:159], v[202:205], v[52:55]
	v_mfma_f32_16x16x32_bf16 v[44:47], v[160:163], v[198:201], v[44:47]
	v_mfma_f32_16x16x32_bf16 v[44:47], v[164:167], v[202:205], v[44:47]
	v_mfma_f32_16x16x32_bf16 v[36:39], v[152:155], v[206:209], v[36:39]
	v_mfma_f32_16x16x32_bf16 v[36:39], v[156:159], v[210:213], v[36:39]
	v_mfma_f32_16x16x32_bf16 v[28:31], v[160:163], v[206:209], v[28:31]
	v_mfma_f32_16x16x32_bf16 v[28:31], v[164:167], v[210:213], v[28:31]
	v_mfma_f32_16x16x32_bf16 v[20:23], v[152:155], v[214:217], v[20:23]
	v_mfma_f32_16x16x32_bf16 v[20:23], v[156:159], v[218:221], v[20:23]
	v_mfma_f32_16x16x32_bf16 v[12:15], v[160:163], v[214:217], v[12:15]
	v_mfma_f32_16x16x32_bf16 v[12:15], v[164:167], v[218:221], v[12:15]
	v_mfma_f32_16x16x32_bf16 v[48:51], v[168:171], v[190:193], v[48:51]
	v_mfma_f32_16x16x32_bf16 v[48:51], v[172:175], v[194:197], v[48:51]
	v_mfma_f32_16x16x32_bf16 v[40:43], v[182:185], v[190:193], v[40:43]
	v_mfma_f32_16x16x32_bf16 v[40:43], v[186:189], v[194:197], v[40:43]
	v_mfma_f32_16x16x32_bf16 v[32:35], v[168:171], v[198:201], v[32:35]
	v_mfma_f32_16x16x32_bf16 v[32:35], v[172:175], v[202:205], v[32:35]
	v_mfma_f32_16x16x32_bf16 v[24:27], v[182:185], v[198:201], v[24:27]
	v_mfma_f32_16x16x32_bf16 v[24:27], v[186:189], v[202:205], v[24:27]
	v_mfma_f32_16x16x32_bf16 v[16:19], v[168:171], v[206:209], v[16:19]
	v_mfma_f32_16x16x32_bf16 v[16:19], v[172:175], v[210:213], v[16:19]
	v_mfma_f32_16x16x32_bf16 v[8:11], v[182:185], v[206:209], v[8:11]
	v_mfma_f32_16x16x32_bf16 v[8:11], v[186:189], v[210:213], v[8:11]
	v_mfma_f32_16x16x32_bf16 v[4:7], v[168:171], v[214:217], v[4:7]
	v_mfma_f32_16x16x32_bf16 v[4:7], v[172:175], v[218:221], v[4:7]
	v_mfma_f32_16x16x32_bf16 v[0:3], v[182:185], v[214:217], v[0:3]
	v_mfma_f32_16x16x32_bf16 v[0:3], v[186:189], v[218:221], v[0:3]
	s_barrier
	s_setprio 0
	s_add_i32 s56, s56, 2
	s_add_u32 s20, s20, 0x100
	s_addc_u32 s21, s21, 0
	s_add_u32 s54, s54, 0x100
	s_addc_u32 s55, s55, 0
	s_cmpk_gt_u32 s56, 0x55
	s_cbranch_scc0 .LBB0_3274
	s_and_b64 vcc, exec, s[8:9]
	s_cbranch_vccz .LBB0_3277
	s_barrier
